# pn==1 lora sigmoid via v_rcp_f32; write-through (sc1) result stores in the four plain GEMM phases (P2a P6 P8 P9)
# speedup vs baseline: 1.0512x; 1.0033x over previous
; #define PG8_STAGE(bufoff, gbase, voff) do { _Pragma("unroll") for (int _i = 0; _i < 2; ++_i) \
;     __builtin_amdgcn_global_load_lds((const unsigned*)((const char*)(gbase) + (voff)[_i]), (LAS unsigned*)(lds + (bufoff) + ldsw + _i * 8192), 16, 0, 0); } while (0)
; #define PG8_LDA(dst, b, h) do { _Pragma("unroll") for (int m = 0; m < 4; ++m) _Pragma("unroll") for (int k = 0; k < 2; ++k) dst[m][k] = *(const LAS bf16x8*)(lds + PG8_SA(b, h) + aoff + m * 2048 + k * 1024); } while (0)
; #define PG8_LDB(dst, b, h) do { _Pragma("unroll") for (int n = 0; n < 2; ++n) _Pragma("unroll") for (int k = 0; k < 2; ++k) dst[n][k] = *(const LAS bf16x8*)(lds + PG8_SB(b, h) + boff + n * 2048 + k * 1024); } while (0)
; #define PG8_MMA(ai, bj, At, Bt) do { __builtin_amdgcn_s_setprio(1); _Pragma("unroll") for (int m = 0; m < 4; ++m) _Pragma("unroll") for (int n = 0; n < 2; ++n) _Pragma("unroll") for (int k = 0; k < 2; ++k) \
;     acc[ai][bj][m][n] = __builtin_amdgcn_mfma_f32_16x16x32_bf16(Bt[n][k], At[m][k], acc[ai][bj][m][n], 0, 0, 0); __builtin_amdgcn_s_setprio(0); } while (0)
; #define PG8_WAIT_L(n) asm volatile("s_waitcnt lgkmcnt(" #n ")" ::: "memory")
; #define PG8_BAR __builtin_amdgcn_s_barrier()
; #define PG8_SCHED __builtin_amdgcn_sched_barrier(0)
; template <class Epi, class Sched>
; DI void gemm_phase(LAS unsigned char* lds, const Gemm g, const Sched& S, const Epi& E, int wid_k) {
;     ...
;       PG8_LDB(B0, 0, 0); PG8_SCHED; PG8_LDA(At, 0, 0); PG8_STAGE(PG8_SA(1, 1), a1 + hstepA, voffA);
;       PG8_WAIT_L(8); PG8_BAR; PG8_WAIT_L(0); PG8_MMA(0, 0, At, B0); PG8_BAR; PG8_SCHED;
;       PG8_LDB(B1, 0, 1); PG8_STAGE(PG8_SB(0, 0), b2, voffB);
;       PG8_BAR; PG8_WAIT_L(0); PG8_MMA(0, 1, At, B1); PG8_BAR;
;       PG8_LDA(At, 0, 1); PG8_STAGE(PG8_SA(0, 0), a2, voffA);
;       PG8_BAR; PG8_WAIT_L(0); PG8_MMA(1, 0, At, B0); PG8_BAR; PG8_SCHED;
.LBB0_334:
	s_add_u32 s18, s16, 0xfffc0080
	s_addc_u32 s19, s17, -1
	s_add_i32 s65, 0, 0x10000
	v_add_u32_e32 v156, s65, v142
	ds_read_b128 v[144:147], v156
	ds_read_b128 v[148:151], v156 offset:1024
	ds_read_b128 v[152:155], v156 offset:2048
	ds_read_b128 v[156:159], v156 offset:3072
	s_cmp_eq_u32 s64, 12
	s_cselect_b32 s21, s11, s19
	s_cselect_b32 s20, s60, s18
	s_cselect_b32 s19, s9, s63
	s_cselect_b32 s18, s61, s62
	v_lshl_add_u64 v[184:185], s[16:17], 0, v[136:137]
	s_add_i32 m0, s7, 0xc000
	ds_read_b128 v[160:163], v143
	ds_read_b128 v[164:167], v143 offset:1024
	ds_read_b128 v[168:171], v143 offset:2048
	ds_read_b128 v[172:175], v143 offset:3072
	ds_read_b128 v[176:179], v143 offset:4096
	ds_read_b128 v[180:183], v143 offset:5120
	ds_read_b128 v[190:193], v143 offset:6144
	ds_read_b128 v[194:197], v143 offset:7168
	global_load_lds_dwordx4 v[184:185], off
	v_lshl_add_u64 v[184:185], s[16:17], 0, v[138:139]
	s_add_i32 m0, s7, 0xe000
	s_nop 0
	global_load_lds_dwordx4 v[184:185], off
	s_waitcnt lgkmcnt(8)
	s_barrier
	s_waitcnt lgkmcnt(0)
	s_setprio 1
	s_waitcnt lgkmcnt(0)
	v_mfma_f32_16x16x32_bf16 v[126:129], v[144:147], v[160:163], v[126:129]
	v_mfma_f32_16x16x32_bf16 v[122:125], v[152:155], v[160:163], v[122:125]
	v_mfma_f32_16x16x32_bf16 v[118:121], v[144:147], v[168:171], v[118:121]
	v_mfma_f32_16x16x32_bf16 v[114:117], v[152:155], v[168:171], v[114:117]
	v_mfma_f32_16x16x32_bf16 v[102:105], v[144:147], v[176:179], v[102:105]
	v_mfma_f32_16x16x32_bf16 v[98:101], v[152:155], v[176:179], v[98:101]
	v_mfma_f32_16x16x32_bf16 v[86:89], v[144:147], v[190:193], v[86:89]
	v_mfma_f32_16x16x32_bf16 v[82:85], v[152:155], v[190:193], v[82:85]
	v_mfma_f32_16x16x32_bf16 v[126:129], v[148:151], v[164:167], v[126:129]
	v_mfma_f32_16x16x32_bf16 v[122:125], v[156:159], v[164:167], v[122:125]
	v_mfma_f32_16x16x32_bf16 v[118:121], v[148:151], v[172:175], v[118:121]
	v_mfma_f32_16x16x32_bf16 v[114:117], v[156:159], v[172:175], v[114:117]
	v_mfma_f32_16x16x32_bf16 v[102:105], v[148:151], v[180:183], v[102:105]
	v_mfma_f32_16x16x32_bf16 v[98:101], v[156:159], v[180:183], v[98:101]
	v_mfma_f32_16x16x32_bf16 v[86:89], v[148:151], v[194:197], v[86:89]
	v_mfma_f32_16x16x32_bf16 v[82:85], v[156:159], v[194:197], v[82:85]
	s_setprio 0
	s_barrier
	s_add_i32 s68, 0, 0x14000
	v_add_u32_e32 v184, s68, v142
	s_add_i32 s65, s65, s34
	ds_read_b128 v[198:201], v184
	ds_read_b128 v[202:205], v184 offset:1024
	ds_read_b128 v[206:209], v184 offset:2048
	ds_read_b128 v[210:213], v184 offset:3072
	v_lshl_add_u64 v[184:185], s[18:19], 0, v[0:1]
	s_mov_b32 m0, s65
	v_lshl_add_u64 v[186:187], s[18:19], 0, v[134:135]
	global_load_lds_dwordx4 v[184:185], off
	s_add_i32 m0, s65, 0x2000
	s_nop 0
	global_load_lds_dwordx4 v[186:187], off
	s_barrier
	s_waitcnt lgkmcnt(0)
	s_setprio 1
	s_waitcnt lgkmcnt(0)
	v_mfma_f32_16x16x32_bf16 v[110:113], v[198:201], v[160:163], v[110:113]
	v_mfma_f32_16x16x32_bf16 v[106:109], v[206:209], v[160:163], v[106:109]
	v_mfma_f32_16x16x32_bf16 v[94:97], v[198:201], v[168:171], v[94:97]
	v_mfma_f32_16x16x32_bf16 v[90:93], v[206:209], v[168:171], v[90:93]
	v_mfma_f32_16x16x32_bf16 v[78:81], v[198:201], v[176:179], v[78:81]
	v_mfma_f32_16x16x32_bf16 v[74:77], v[206:209], v[176:179], v[74:77]
	v_mfma_f32_16x16x32_bf16 v[70:73], v[198:201], v[190:193], v[70:73]
	v_mfma_f32_16x16x32_bf16 v[66:69], v[206:209], v[190:193], v[66:69]
	v_mfma_f32_16x16x32_bf16 v[110:113], v[202:205], v[164:167], v[110:113]
	v_mfma_f32_16x16x32_bf16 v[106:109], v[210:213], v[164:167], v[106:109]
	v_mfma_f32_16x16x32_bf16 v[94:97], v[202:205], v[172:175], v[94:97]
	v_mfma_f32_16x16x32_bf16 v[90:93], v[210:213], v[172:175], v[90:93]
	v_mfma_f32_16x16x32_bf16 v[78:81], v[202:205], v[180:183], v[78:81]
	v_mfma_f32_16x16x32_bf16 v[74:77], v[210:213], v[180:183], v[74:77]
	v_mfma_f32_16x16x32_bf16 v[70:73], v[202:205], v[194:197], v[70:73]
	v_mfma_f32_16x16x32_bf16 v[66:69], v[210:213], v[194:197], v[66:69]
	s_setprio 0
	s_mov_b32 m0, s7
	v_lshl_add_u64 v[214:215], s[20:21], 0, v[130:131]
	s_barrier
	ds_read_b128 v[160:163], v143 offset:16384
	ds_read_b128 v[164:167], v143 offset:17408
	ds_read_b128 v[168:171], v143 offset:18432
	ds_read_b128 v[172:175], v143 offset:19456
	ds_read_b128 v[176:179], v143 offset:20480
	ds_read_b128 v[180:183], v143 offset:21504
	ds_read_b128 v[190:193], v143 offset:22528
	ds_read_b128 v[194:197], v143 offset:23552
	global_load_lds_dwordx4 v[214:215], off
	v_lshl_add_u64 v[216:217], s[20:21], 0, v[132:133]
	s_mov_b32 m0, s35
	s_nop 0
	global_load_lds_dwordx4 v[216:217], off
	s_barrier
	s_waitcnt lgkmcnt(0)
	s_setprio 1
	s_waitcnt lgkmcnt(0)
	v_mfma_f32_16x16x32_bf16 v[62:65], v[144:147], v[160:163], v[62:65]
	v_mfma_f32_16x16x32_bf16 v[58:61], v[152:155], v[160:163], v[58:61]
	v_mfma_f32_16x16x32_bf16 v[54:57], v[144:147], v[168:171], v[54:57]
	v_mfma_f32_16x16x32_bf16 v[50:53], v[152:155], v[168:171], v[50:53]
	v_mfma_f32_16x16x32_bf16 v[38:41], v[144:147], v[176:179], v[38:41]
	v_mfma_f32_16x16x32_bf16 v[34:37], v[152:155], v[176:179], v[34:37]
	v_mfma_f32_16x16x32_bf16 v[22:25], v[144:147], v[190:193], v[22:25]
	v_mfma_f32_16x16x32_bf16 v[18:21], v[152:155], v[190:193], v[18:21]
	v_mfma_f32_16x16x32_bf16 v[62:65], v[148:151], v[164:167], v[62:65]
	v_mfma_f32_16x16x32_bf16 v[58:61], v[156:159], v[164:167], v[58:61]
	v_mfma_f32_16x16x32_bf16 v[54:57], v[148:151], v[172:175], v[54:57]
	v_mfma_f32_16x16x32_bf16 v[50:53], v[156:159], v[172:175], v[50:53]
	v_mfma_f32_16x16x32_bf16 v[38:41], v[148:151], v[180:183], v[38:41]
	v_mfma_f32_16x16x32_bf16 v[34:37], v[156:159], v[180:183], v[34:37]
	v_mfma_f32_16x16x32_bf16 v[22:25], v[148:151], v[194:197], v[22:25]
	v_mfma_f32_16x16x32_bf16 v[18:21], v[156:159], v[194:197], v[18:21]
	s_setprio 0
	s_barrier
; #define PG8_STAGE(bufoff, gbase, voff) do { _Pragma("unroll") for (int _i = 0; _i < 2; ++_i) \
;     __builtin_amdgcn_global_load_lds((const unsigned*)((const char*)(gbase) + (voff)[_i]), (LAS unsigned*)(lds + (bufoff) + ldsw + _i * 8192), 16, 0, 0); } while (0)
; #define PG8_LDA(dst, b, h) do { _Pragma("unroll") for (int m = 0; m < 4; ++m) _Pragma("unroll") for (int k = 0; k < 2; ++k) dst[m][k] = *(const LAS bf16x8*)(lds + PG8_SA(b, h) + aoff + m * 2048 + k * 1024); } while (0)
; #define PG8_LDB(dst, b, h) do { _Pragma("unroll") for (int n = 0; n < 2; ++n) _Pragma("unroll") for (int k = 0; k < 2; ++k) dst[n][k] = *(const LAS bf16x8*)(lds + PG8_SB(b, h) + boff + n * 2048 + k * 1024); } while (0)
; #define PG8_MMA(ai, bj, At, Bt) do { __builtin_amdgcn_s_setprio(1); _Pragma("unroll") for (int m = 0; m < 4; ++m) _Pragma("unroll") for (int n = 0; n < 2; ++n) _Pragma("unroll") for (int k = 0; k < 2; ++k) \
;     acc[ai][bj][m][n] = __builtin_amdgcn_mfma_f32_16x16x32_bf16(Bt[n][k], At[m][k], acc[ai][bj][m][n], 0, 0, 0); __builtin_amdgcn_s_setprio(0); } while (0)
; #define PG8_WAIT_V(n) asm volatile("s_waitcnt vmcnt(" #n ")" ::: "memory")
; #define PG8_WAIT_L(n) asm volatile("s_waitcnt lgkmcnt(" #n ")" ::: "memory")
; #define PG8_BAR __builtin_amdgcn_s_barrier()
; #define PG8_SCHED __builtin_amdgcn_sched_barrier(0)
; template <class Epi, class Sched>
; DI void gemm_phase(LAS unsigned char* lds, const Gemm g, const Sched& S, const Epi& E, int wid_k) {
;     ...
;       PG8_STAGE(PG8_SB(0, 1), b2 + hstepB, voffB);
;       PG8_WAIT_V(6); PG8_BAR; PG8_MMA(1, 1, At, B1); PG8_BAR;
;       PG8_LDB(B0, 1, 0); PG8_SCHED; PG8_LDA(At, 1, 0); PG8_STAGE(PG8_SA(0, 1), a2 + hstepA, voffA);
;       PG8_WAIT_L(8); PG8_BAR; PG8_WAIT_L(0); PG8_MMA(0, 0, At, B0); PG8_BAR; PG8_SCHED;
;       PG8_LDB(B1, 1, 1); PG8_STAGE(PG8_SB(1, 0), b3, voffB);
;       PG8_BAR; PG8_WAIT_L(0); PG8_MMA(0, 1, At, B1); PG8_BAR;
;       PG8_LDA(At, 1, 1); PG8_STAGE(PG8_SA(1, 0), a3, voffA);
	s_add_u32 s66, s18, 0x40000
	s_addc_u32 s67, s19, 0
	s_add_i32 s65, s68, s34
	v_lshl_add_u64 v[144:145], s[66:67], 0, v[0:1]
	s_mov_b32 m0, s65
	s_nop 0
	global_load_lds_dwordx4 v[144:145], off
	v_lshl_add_u64 v[144:145], s[66:67], 0, v[134:135]
	s_add_i32 m0, s65, 0x2000
	s_nop 0
	global_load_lds_dwordx4 v[144:145], off
	s_waitcnt vmcnt(6)
	s_barrier
	s_setprio 1
	v_mfma_f32_16x16x32_bf16 v[46:49], v[198:201], v[160:163], v[46:49]
	v_mfma_f32_16x16x32_bf16 v[42:45], v[206:209], v[160:163], v[42:45]
	v_mfma_f32_16x16x32_bf16 v[30:33], v[198:201], v[168:171], v[30:33]
	v_mfma_f32_16x16x32_bf16 v[26:29], v[206:209], v[168:171], v[26:29]
	v_mfma_f32_16x16x32_bf16 v[14:17], v[198:201], v[176:179], v[14:17]
	v_mfma_f32_16x16x32_bf16 v[10:13], v[206:209], v[176:179], v[10:13]
	v_mfma_f32_16x16x32_bf16 v[6:9], v[198:201], v[190:193], v[6:9]
	v_mfma_f32_16x16x32_bf16 v[2:5], v[206:209], v[190:193], v[2:5]
	v_mfma_f32_16x16x32_bf16 v[46:49], v[202:205], v[164:167], v[46:49]
	v_mfma_f32_16x16x32_bf16 v[42:45], v[210:213], v[164:167], v[42:45]
	v_mfma_f32_16x16x32_bf16 v[30:33], v[202:205], v[172:175], v[30:33]
	v_mfma_f32_16x16x32_bf16 v[26:29], v[210:213], v[172:175], v[26:29]
	v_mfma_f32_16x16x32_bf16 v[14:17], v[202:205], v[180:183], v[14:17]
	v_mfma_f32_16x16x32_bf16 v[10:13], v[210:213], v[180:183], v[10:13]
	v_mfma_f32_16x16x32_bf16 v[6:9], v[202:205], v[194:197], v[6:9]
	v_mfma_f32_16x16x32_bf16 v[2:5], v[210:213], v[194:197], v[2:5]
	s_setprio 0
	s_add_i32 s65, 0, 0x18000
	v_add_u32_e32 v156, s65, v142
	s_barrier
	ds_read_b128 v[144:147], v156
	ds_read_b128 v[148:151], v156 offset:1024
	ds_read_b128 v[152:155], v156 offset:2048
	ds_read_b128 v[156:159], v156 offset:3072
	s_add_u32 s20, s20, 0x40000
	s_addc_u32 s21, s21, 0
	s_mov_b32 m0, s36
	v_lshl_add_u64 v[198:199], s[20:21], 0, v[130:131]
	ds_read_b128 v[160:163], v143 offset:32768
	ds_read_b128 v[164:167], v143 offset:33792
	ds_read_b128 v[168:171], v143 offset:34816
	ds_read_b128 v[172:175], v143 offset:35840
	ds_read_b128 v[176:179], v143 offset:36864
	ds_read_b128 v[180:183], v143 offset:37888
	ds_read_b128 v[190:193], v143 offset:38912
	ds_read_b128 v[194:197], v143 offset:39936
	global_load_lds_dwordx4 v[198:199], off
	v_lshl_add_u64 v[198:199], s[20:21], 0, v[132:133]
	s_mov_b32 m0, s37
	s_nop 0
	global_load_lds_dwordx4 v[198:199], off
	s_waitcnt lgkmcnt(8)
	s_barrier
	s_waitcnt lgkmcnt(0)
	s_setprio 1
	s_waitcnt lgkmcnt(0)
	v_mfma_f32_16x16x32_bf16 v[126:129], v[144:147], v[160:163], v[126:129]
	v_mfma_f32_16x16x32_bf16 v[122:125], v[152:155], v[160:163], v[122:125]
	v_mfma_f32_16x16x32_bf16 v[118:121], v[144:147], v[168:171], v[118:121]
	v_mfma_f32_16x16x32_bf16 v[114:117], v[152:155], v[168:171], v[114:117]
	v_mfma_f32_16x16x32_bf16 v[102:105], v[144:147], v[176:179], v[102:105]
	v_mfma_f32_16x16x32_bf16 v[98:101], v[152:155], v[176:179], v[98:101]
	v_mfma_f32_16x16x32_bf16 v[86:89], v[144:147], v[190:193], v[86:89]
	v_mfma_f32_16x16x32_bf16 v[82:85], v[152:155], v[190:193], v[82:85]
	v_mfma_f32_16x16x32_bf16 v[126:129], v[148:151], v[164:167], v[126:129]
	v_mfma_f32_16x16x32_bf16 v[122:125], v[156:159], v[164:167], v[122:125]
	v_mfma_f32_16x16x32_bf16 v[118:121], v[148:151], v[172:175], v[118:121]
	v_mfma_f32_16x16x32_bf16 v[114:117], v[156:159], v[172:175], v[114:117]
	v_mfma_f32_16x16x32_bf16 v[102:105], v[148:151], v[180:183], v[102:105]
	v_mfma_f32_16x16x32_bf16 v[98:101], v[156:159], v[180:183], v[98:101]
	v_mfma_f32_16x16x32_bf16 v[86:89], v[148:151], v[194:197], v[86:89]
	v_mfma_f32_16x16x32_bf16 v[82:85], v[156:159], v[194:197], v[82:85]
	s_setprio 0
	s_barrier
	s_add_i32 s20, 0, 0x1c000
	s_add_i32 s21, s65, s34
	v_add_u32_e32 v210, s20, v142
	v_lshl_add_u64 v[184:185], v[184:185], 0, s[78:79]
	s_mov_b32 m0, s21
	ds_read_b128 v[198:201], v210
	ds_read_b128 v[202:205], v210 offset:1024
	ds_read_b128 v[206:209], v210 offset:2048
	ds_read_b128 v[210:213], v210 offset:3072
	global_load_lds_dwordx4 v[184:185], off
	v_lshl_add_u64 v[184:185], v[186:187], 0, s[78:79]
	s_add_i32 m0, s21, 0x2000
	s_nop 0
	global_load_lds_dwordx4 v[184:185], off
	s_barrier
	s_waitcnt lgkmcnt(0)
	s_setprio 1
	s_waitcnt lgkmcnt(0)
	v_mfma_f32_16x16x32_bf16 v[110:113], v[198:201], v[160:163], v[110:113]
	v_mfma_f32_16x16x32_bf16 v[106:109], v[206:209], v[160:163], v[106:109]
	v_mfma_f32_16x16x32_bf16 v[94:97], v[198:201], v[168:171], v[94:97]
	v_mfma_f32_16x16x32_bf16 v[90:93], v[206:209], v[168:171], v[90:93]
	v_mfma_f32_16x16x32_bf16 v[78:81], v[198:201], v[176:179], v[78:81]
	v_mfma_f32_16x16x32_bf16 v[74:77], v[206:209], v[176:179], v[74:77]
	v_mfma_f32_16x16x32_bf16 v[70:73], v[198:201], v[190:193], v[70:73]
	v_mfma_f32_16x16x32_bf16 v[66:69], v[206:209], v[190:193], v[66:69]
	v_mfma_f32_16x16x32_bf16 v[110:113], v[202:205], v[164:167], v[110:113]
	v_mfma_f32_16x16x32_bf16 v[106:109], v[210:213], v[164:167], v[106:109]
	v_mfma_f32_16x16x32_bf16 v[94:97], v[202:205], v[172:175], v[94:97]
	v_mfma_f32_16x16x32_bf16 v[90:93], v[210:213], v[172:175], v[90:93]
	v_mfma_f32_16x16x32_bf16 v[78:81], v[202:205], v[180:183], v[78:81]
	v_mfma_f32_16x16x32_bf16 v[74:77], v[210:213], v[180:183], v[74:77]
	v_mfma_f32_16x16x32_bf16 v[70:73], v[202:205], v[194:197], v[70:73]
	v_mfma_f32_16x16x32_bf16 v[66:69], v[210:213], v[194:197], v[66:69]
	s_setprio 0
	s_mov_b32 m0, s39
	v_lshl_add_u64 v[184:185], v[214:215], 0, s[78:79]
	s_barrier
	ds_read_b128 v[160:163], v143 offset:49152
	ds_read_b128 v[164:167], v143 offset:50176
	ds_read_b128 v[168:171], v143 offset:51200
	ds_read_b128 v[172:175], v143 offset:52224
	ds_read_b128 v[176:179], v143 offset:53248
	ds_read_b128 v[180:183], v143 offset:54272
	ds_read_b128 v[190:193], v143 offset:55296
	ds_read_b128 v[194:197], v143 offset:56320
	global_load_lds_dwordx4 v[184:185], off
	v_lshl_add_u64 v[184:185], v[216:217], 0, s[78:79]
	s_mov_b32 m0, s40
	s_nop 0
	global_load_lds_dwordx4 v[184:185], off
	s_barrier
; #define PG8_STAGE(bufoff, gbase, voff) do { _Pragma("unroll") for (int _i = 0; _i < 2; ++_i) \
;     __builtin_amdgcn_global_load_lds((const unsigned*)((const char*)(gbase) + (voff)[_i]), (LAS unsigned*)(lds + (bufoff) + ldsw + _i * 8192), 16, 0, 0); } while (0)
; #define PG8_MMA(ai, bj, At, Bt) do { __builtin_amdgcn_s_setprio(1); _Pragma("unroll") for (int m = 0; m < 4; ++m) _Pragma("unroll") for (int n = 0; n < 2; ++n) _Pragma("unroll") for (int k = 0; k < 2; ++k) \
;     acc[ai][bj][m][n] = __builtin_amdgcn_mfma_f32_16x16x32_bf16(Bt[n][k], At[m][k], acc[ai][bj][m][n], 0, 0, 0); __builtin_amdgcn_s_setprio(0); } while (0)
; #define PG8_WAIT_V(n) asm volatile("s_waitcnt vmcnt(" #n ")" ::: "memory")
; #define PG8_WAIT_L(n) asm volatile("s_waitcnt lgkmcnt(" #n ")" ::: "memory")
; #define PG8_BAR __builtin_amdgcn_s_barrier()
; #define PG8_SCHED __builtin_amdgcn_sched_barrier(0)
; template <class Epi, class Sched>
; DI void gemm_phase(LAS unsigned char* lds, const Gemm g, const Sched& S, const Epi& E, int wid_k) {
;     ...
;       PG8_BAR; PG8_WAIT_L(0); PG8_MMA(1, 0, At, B0); PG8_BAR; PG8_SCHED;
;       PG8_STAGE(PG8_SB(1, 1), b3 + hstepB, voffB);
;       PG8_WAIT_V(6); PG8_BAR; PG8_MMA(1, 1, At, B1); PG8_BAR;
;     }
	s_waitcnt lgkmcnt(0)
	s_setprio 1
	s_waitcnt lgkmcnt(0)
	v_mfma_f32_16x16x32_bf16 v[62:65], v[144:147], v[160:163], v[62:65]
	v_mfma_f32_16x16x32_bf16 v[58:61], v[152:155], v[160:163], v[58:61]
	v_mfma_f32_16x16x32_bf16 v[54:57], v[144:147], v[168:171], v[54:57]
	v_mfma_f32_16x16x32_bf16 v[50:53], v[152:155], v[168:171], v[50:53]
	v_mfma_f32_16x16x32_bf16 v[38:41], v[144:147], v[176:179], v[38:41]
	v_mfma_f32_16x16x32_bf16 v[34:37], v[152:155], v[176:179], v[34:37]
	v_mfma_f32_16x16x32_bf16 v[22:25], v[144:147], v[190:193], v[22:25]
	v_mfma_f32_16x16x32_bf16 v[18:21], v[152:155], v[190:193], v[18:21]
	v_mfma_f32_16x16x32_bf16 v[62:65], v[148:151], v[164:167], v[62:65]
	v_mfma_f32_16x16x32_bf16 v[58:61], v[156:159], v[164:167], v[58:61]
	v_mfma_f32_16x16x32_bf16 v[54:57], v[148:151], v[172:175], v[54:57]
	v_mfma_f32_16x16x32_bf16 v[50:53], v[156:159], v[172:175], v[50:53]
	v_mfma_f32_16x16x32_bf16 v[38:41], v[148:151], v[180:183], v[38:41]
	v_mfma_f32_16x16x32_bf16 v[34:37], v[156:159], v[180:183], v[34:37]
	v_mfma_f32_16x16x32_bf16 v[22:25], v[148:151], v[194:197], v[22:25]
	v_mfma_f32_16x16x32_bf16 v[18:21], v[156:159], v[194:197], v[18:21]
	s_setprio 0
	s_barrier
	s_add_u32 s18, s18, 0x40080
	s_addc_u32 s19, s19, 0
	s_add_i32 s20, s20, s34
	v_lshl_add_u64 v[144:145], s[18:19], 0, v[0:1]
	s_mov_b32 m0, s20
	s_nop 0
	global_load_lds_dwordx4 v[144:145], off
	v_lshl_add_u64 v[144:145], s[18:19], 0, v[134:135]
	s_add_i32 m0, s20, 0x2000
	s_nop 0
	global_load_lds_dwordx4 v[144:145], off
	s_waitcnt vmcnt(6)
	s_barrier
	s_setprio 1
	v_mfma_f32_16x16x32_bf16 v[46:49], v[198:201], v[160:163], v[46:49]
	v_mfma_f32_16x16x32_bf16 v[42:45], v[206:209], v[160:163], v[42:45]
	v_mfma_f32_16x16x32_bf16 v[30:33], v[198:201], v[168:171], v[30:33]
	v_mfma_f32_16x16x32_bf16 v[26:29], v[206:209], v[168:171], v[26:29]
	v_mfma_f32_16x16x32_bf16 v[14:17], v[198:201], v[176:179], v[14:17]
	v_mfma_f32_16x16x32_bf16 v[10:13], v[206:209], v[176:179], v[10:13]
	v_mfma_f32_16x16x32_bf16 v[6:9], v[198:201], v[190:193], v[6:9]
	v_mfma_f32_16x16x32_bf16 v[2:5], v[206:209], v[190:193], v[2:5]
	v_mfma_f32_16x16x32_bf16 v[46:49], v[202:205], v[164:167], v[46:49]
	v_mfma_f32_16x16x32_bf16 v[42:45], v[210:213], v[164:167], v[42:45]
	v_mfma_f32_16x16x32_bf16 v[30:33], v[202:205], v[172:175], v[30:33]
	v_mfma_f32_16x16x32_bf16 v[26:29], v[210:213], v[172:175], v[26:29]
	v_mfma_f32_16x16x32_bf16 v[14:17], v[202:205], v[180:183], v[14:17]
	v_mfma_f32_16x16x32_bf16 v[10:13], v[210:213], v[180:183], v[10:13]
	v_mfma_f32_16x16x32_bf16 v[6:9], v[202:205], v[194:197], v[6:9]
	v_mfma_f32_16x16x32_bf16 v[2:5], v[210:213], v[194:197], v[2:5]
	s_setprio 0
	s_add_i32 s64, s64, 2
	s_add_u32 s16, s16, 0x100
	s_addc_u32 s17, s17, 0
	s_add_u32 s62, s62, 0x100
	s_addc_u32 s63, s63, 0
	s_cmp_gt_u32 s64, 13
	s_barrier
	s_cbranch_scc0 .LBB0_334
; DI uint4 pack8(f32x4 a, f32x4 b) { uint4 r; r.x = pack2(a[0], a[1]); r.y = pack2(a[2], a[3]); r.z = pack2(b[0], b[1]); r.w = pack2(b[2], b[3]); return r; }
; template <class Epi, class Sched>
; DI void gemm_phase(LAS unsigned char* lds, const Gemm g, const Sched& S, const Epi& E, int wid_k) {
;     ...
;     { int fr_ = fr, fq_ = fq, wr_ = wr, wc_ = wc; asm volatile("" : "+v"(fr_), "+v"(fq_)); asm volatile("" : "+s"(wr_), "+s"(wc_)); E(acc, cur, wr_, wc_, fr_, fq_); }
;     if (!has_next) break;
;   DI void operator()(const Acc8& acc, const pg8::Unit& u, int wr, int wc, int fr, int fq) const {
;     ...
;     for (int ai = 0; ai < 2; ++ai)
; #pragma unroll
;       for (int m = 0; m < 4; ++m) {
;         u16* rowp = O + (size_t)EPI_ROWS(ai, m) * ldc;
; #pragma unroll
;         for (int bj = 0; bj < 2; ++bj) {
;           f32x4 v0 = acc[ai][bj][m][0], v1 = acc[ai][bj][m][1];
;           if (ACT == 1) {
; #pragma unroll
;             for (int e = 0; e < 4; ++e) { const float r0 = fmaxf(v0[e], 0.f), r1 = fmaxf(v1[e], 0.f); v0[e] = r0 * r0; v1[e] = r1 * r1; }
;           }
;           *(uint4*)(rowp + EPI_COL8(bj)) = pack8(v0, v1);
	v_mov_b32_e32 v144, v141
	v_mov_b32_e32 v145, v140
	s_mov_b32 s9, s31
	s_mov_b32 s11, s38
	s_lshl_b32 s6, s6, 8
	s_lshl_b32 s9, s9, 6
	s_add_i32 s9, s9, s6
	v_add_u32_e32 v144, s9, v144
	s_lshl_b32 s6, s49, 8
	s_lshl_b32 s9, s11, 5
	s_add_i32 s9, s9, s6
	v_cvt_pk_bf16_f32 v70, v70, v71
	v_cvt_pk_bf16_f32 v71, v72, v73
	v_cvt_pk_bf16_f32 v72, v66, v67
	v_add_u32_e32 v66, 0x80, v144
	v_lshl_add_u32 v146, v145, 3, s9
	v_ashrrev_i32_e32 v145, 31, v144
	v_ashrrev_i32_e32 v67, 31, v66
	v_lshlrev_b64 v[148:149], 11, v[144:145]
	v_ashrrev_i32_e32 v147, 31, v146
	v_cvt_pk_bf16_f32 v110, v110, v111
	v_cvt_pk_bf16_f32 v111, v112, v113
	v_cvt_pk_bf16_f32 v112, v106, v107
	v_add_u32_e32 v106, 16, v144
	v_lshlrev_b64 v[66:67], 11, v[66:67]
	v_cvt_pk_bf16_f32 v46, v46, v47
	v_cvt_pk_bf16_f32 v47, v48, v49
	v_cvt_pk_bf16_f32 v48, v42, v43
	v_add_u32_e32 v42, 0x90, v144
	v_lshl_add_u64 v[148:149], s[4:5], 0, v[148:149]
	v_cvt_pk_bf16_f32 v126, v126, v127
	v_cvt_pk_bf16_f32 v127, v128, v129
	v_cvt_pk_bf16_f32 v128, v122, v123
	v_lshlrev_b64 v[122:123], 1, v[146:147]
	v_ashrrev_i32_e32 v107, 31, v106
	v_lshl_add_u64 v[66:67], s[4:5], 0, v[66:67]
	v_ashrrev_i32_e32 v43, 31, v42
	v_cvt_pk_bf16_f32 v129, v124, v125
	v_lshl_add_u64 v[124:125], v[148:149], 0, v[122:123]
	v_cvt_pk_bf16_f32 v113, v108, v109
	v_lshlrev_b64 v[106:107], 11, v[106:107]
	v_cvt_pk_bf16_f32 v94, v94, v95
	v_cvt_pk_bf16_f32 v95, v96, v97
	v_cvt_pk_bf16_f32 v96, v90, v91
	v_add_u32_e32 v90, 32, v144
	v_cvt_pk_bf16_f32 v62, v62, v63
	v_cvt_pk_bf16_f32 v63, v64, v65
	v_cvt_pk_bf16_f32 v64, v58, v59
	v_lshl_add_u64 v[58:59], v[66:67], 0, v[122:123]
	v_cvt_pk_bf16_f32 v49, v44, v45
	v_lshlrev_b64 v[42:43], 11, v[42:43]
	v_cvt_pk_bf16_f32 v30, v30, v31
	v_cvt_pk_bf16_f32 v31, v32, v33
	v_cvt_pk_bf16_f32 v32, v26, v27
	v_add_u32_e32 v26, 0xa0, v144
	global_store_dwordx4 v[124:125], v[110:113], off offset:256 sc1
	v_ashrrev_i32_e32 v91, 31, v90
	global_store_dwordx4 v[58:59], v[46:49], off offset:256 sc1
	v_lshl_add_u64 v[110:111], s[4:5], 0, v[106:107]
	v_ashrrev_i32_e32 v27, 31, v26
	v_lshl_add_u64 v[46:47], s[4:5], 0, v[42:43]
	v_lshl_add_u64 v[110:111], v[110:111], 0, v[122:123]
	v_cvt_pk_bf16_f32 v97, v92, v93
	v_lshlrev_b64 v[90:91], 11, v[90:91]
	v_cvt_pk_bf16_f32 v78, v78, v79
	v_cvt_pk_bf16_f32 v79, v80, v81
	v_cvt_pk_bf16_f32 v80, v74, v75
	v_add_u32_e32 v74, 48, v144
	v_lshl_add_u64 v[46:47], v[46:47], 0, v[122:123]
	v_cvt_pk_bf16_f32 v33, v28, v29
	v_lshlrev_b64 v[26:27], 11, v[26:27]
	v_cvt_pk_bf16_f32 v14, v14, v15
	v_cvt_pk_bf16_f32 v15, v16, v17
	v_cvt_pk_bf16_f32 v16, v10, v11
	v_add_u32_e32 v10, 0xb0, v144
	global_store_dwordx4 v[110:111], v[94:97], off offset:256 sc1
	v_ashrrev_i32_e32 v75, 31, v74
	global_store_dwordx4 v[46:47], v[30:33], off offset:256 sc1
	v_lshl_add_u64 v[94:95], s[4:5], 0, v[90:91]
	v_ashrrev_i32_e32 v11, 31, v10
	v_lshl_add_u64 v[30:31], s[4:5], 0, v[26:27]
	v_lshl_add_u64 v[94:95], v[94:95], 0, v[122:123]
	v_cvt_pk_bf16_f32 v81, v76, v77
	v_lshlrev_b64 v[74:75], 11, v[74:75]
	v_lshl_add_u64 v[30:31], v[30:31], 0, v[122:123]
	v_cvt_pk_bf16_f32 v17, v12, v13
	v_lshlrev_b64 v[10:11], 11, v[10:11]
	global_store_dwordx4 v[94:95], v[78:81], off offset:256 sc1
	global_store_dwordx4 v[30:31], v[14:17], off offset:256 sc1
	v_cvt_pk_bf16_f32 v106, v118, v119
	v_lshl_add_u64 v[78:79], s[4:5], 0, v[74:75]
	v_lshl_add_u64 v[14:15], s[4:5], 0, v[10:11]
	v_cvt_pk_bf16_f32 v107, v120, v121
	v_cvt_pk_bf16_f32 v108, v114, v115
	v_cvt_pk_bf16_f32 v109, v116, v117
	v_cvt_pk_bf16_f32 v90, v102, v103
	v_cvt_pk_bf16_f32 v91, v104, v105
	v_cvt_pk_bf16_f32 v92, v98, v99
	v_cvt_pk_bf16_f32 v93, v100, v101
	v_cvt_pk_bf16_f32 v74, v86, v87
	v_cvt_pk_bf16_f32 v75, v88, v89
	v_cvt_pk_bf16_f32 v76, v82, v83
	v_cvt_pk_bf16_f32 v77, v84, v85
	v_lshl_add_u64 v[78:79], v[78:79], 0, v[122:123]
	v_cvt_pk_bf16_f32 v73, v68, v69
	v_cvt_pk_bf16_f32 v65, v60, v61
	v_cvt_pk_bf16_f32 v42, v54, v55
	v_cvt_pk_bf16_f32 v43, v56, v57
	v_cvt_pk_bf16_f32 v44, v50, v51
	v_cvt_pk_bf16_f32 v45, v52, v53
	v_cvt_pk_bf16_f32 v26, v38, v39
	v_cvt_pk_bf16_f32 v27, v40, v41
	v_cvt_pk_bf16_f32 v28, v34, v35
	v_cvt_pk_bf16_f32 v29, v36, v37
	v_cvt_pk_bf16_f32 v10, v22, v23
	v_cvt_pk_bf16_f32 v11, v24, v25
	v_cvt_pk_bf16_f32 v12, v18, v19
	v_cvt_pk_bf16_f32 v13, v20, v21
	v_lshl_add_u64 v[14:15], v[14:15], 0, v[122:123]
	v_cvt_pk_bf16_f32 v6, v6, v7
	v_cvt_pk_bf16_f32 v7, v8, v9
	v_cvt_pk_bf16_f32 v8, v2, v3
	v_cvt_pk_bf16_f32 v9, v4, v5
	s_and_b64 vcc, exec, s[2:3]
	s_mov_b32 s49, s8
	s_mov_b32 s6, s10
	s_mov_b64 s[18:19], s[14:15]
	s_mov_b64 s[16:17], s[12:13]
	s_mov_b32 s60, 0xe6a0000
	s_mov_b32 s61, 0x106a0000
	global_store_dwordx4 v[124:125], v[126:129], off sc1
	global_store_dwordx4 v[110:111], v[106:109], off sc1
	global_store_dwordx4 v[94:95], v[90:93], off sc1
	global_store_dwordx4 v[78:79], v[74:77], off sc1
	global_store_dwordx4 v[78:79], v[70:73], off offset:256 sc1
	global_store_dwordx4 v[58:59], v[62:65], off sc1
	global_store_dwordx4 v[46:47], v[42:45], off sc1
	global_store_dwordx4 v[30:31], v[26:29], off sc1
	global_store_dwordx4 v[14:15], v[10:13], off sc1
	global_store_dwordx4 v[14:15], v[6:9], off offset:256 sc1
	s_cbranch_vccz .LBB0_327
	s_waitcnt vmcnt(0)
	s_cmpk_gt_u32 s24, 0xff
	s_cbranch_scc1 .LBB0_338
	s_barrier

; #define PG8_LDA(dst, b, h) do { _Pragma("unroll") for (int m = 0; m < 4; ++m) _Pragma("unroll") for (int k = 0; k < 2; ++k) dst[m][k] = *(const LAS bf16x8*)(lds + PG8_SA(b, h) + aoff + m * 2048 + k * 1024); } while (0)
; template <class Epi, class Sched>
; DI void gemm_phase(LAS unsigned char* lds, const Gemm g, const Sched& S, const Epi& E, int wid_k) {
;     ...
;   const int aoff = lds_byte(wr * 64 + fr, fq * 8), boff = lds_byte(wc * 32 + fr, fq * 8);
;     ...
;   Unit cur, nxt; int ui = 0;
;   if (!S.next(0, cur)) return;
;   f32x4 acc[2][2][4][2];
; #pragma unroll
;   for (int a = 0; a < 2; ++a)
; #pragma unroll
;     for (int b = 0; b < 2; ++b)
; #pragma unroll
;       for (int m = 0; m < 4; ++m)
; #pragma unroll
;         for (int n = 0; n < 2; ++n) acc[a][b][m][n] = (f32x4){0.f, 0.f, 0.f, 0.f};
;   bf16x8 At[4][2], B0[2][2], B1[2][2];
;   const char* cA = (const char*)g.A + (size_t)cur.pm * tstepA; const char* cB = (const char*)g.Bt + (size_t)cur.pn * tstepB;
;   PG8_STAGE(PG8_SB(0, 0), cB, voffB); PG8_STAGE(PG8_SA(0, 0), cA, voffA); PG8_STAGE(PG8_SB(0, 1), cB + hstepB, voffB); PG8_STAGE(PG8_SA(0, 1), cA + hstepA, voffA);
;   if (wr == 1) PG8_BAR;
;   PG8_WAIT_V(4); PG8_BAR;
;   PG8_STAGE(PG8_SB(1, 0), cB + kstep, voffB); PG8_STAGE(PG8_SA(1, 0), cA + kstep, voffA); PG8_STAGE(PG8_SB(1, 1), cB + hstepB + kstep, voffB);
;   PG8_WAIT_V(6); PG8_BAR;
;   for (;;) {
;     const bool has_next = S.next(ui + 1, nxt);
;     const char* nA = has_next ? (const char*)g.A + (size_t)nxt.pm * tstepA : cA; const char* nB = has_next ? (const char*)g.Bt + (size_t)nxt.pn * tstepB : cB;
;     for (int t = 0; t < nt; t += 2) {
;       const bool last = (t == nt - 2);
;       const char* a1 = cA + (size_t)(t + 1) * kstep;
;       const char* a2 = last ? nA : cA + (size_t)(t + 2) * kstep; const char* b2 = last ? nB : cB + (size_t)(t + 2) * kstep;
;       const char* a3 = a2 + kstep; const char* b3 = b2 + kstep;
;       PG8_LDB(B0, 0, 0); PG8_SCHED; PG8_LDA(At, 0, 0); PG8_STAGE(PG8_SA(1, 1), a1 + hstepA, voffA);
;       PG8_WAIT_L(8); PG8_BAR; PG8_WAIT_L(0); PG8_MMA(0, 0, At, B0); PG8_BAR; PG8_SCHED;
;       PG8_LDB(B1, 0, 1); PG8_STAGE(PG8_SB(0, 0), b2, voffB);
;       PG8_BAR; PG8_WAIT_L(0); PG8_MMA(0, 1, At, B1); PG8_BAR;
;       PG8_LDA(At, 0, 1); PG8_STAGE(PG8_SA(0, 0), a2, voffA);
;       PG8_BAR; PG8_WAIT_L(0); PG8_MMA(1, 0, At, B0); PG8_BAR; PG8_SCHED;
.LBB0_484:
	v_and_b32_e32 v130, 15, v24
	v_bfe_u32 v131, v24, 4, 2
	v_lshlrev_b32_e32 v25, 6, v130
	v_lshlrev_b32_e32 v24, 2, v24
	s_add_i32 s37, 0, 0x18000
	s_and_b32 s13, s27, 3
	v_lshl_or_b32 v25, v131, 4, v25
	s_lshl_b32 s27, s20, 13
	v_and_b32_e32 v24, 32, v24
	s_add_i32 s34, s37, s36
	v_bitop3_b32 v36, v25, s27, v24 bitop3:0xde
	s_lshl_b32 s27, s13, 12
	v_lshl_add_u64 v[32:33], v[10:11], 0, s[78:79]
	s_mov_b32 m0, s34
	s_add_i32 s35, s34, 0x2000
	s_add_i32 s30, s15, 0x8000
	s_add_i32 s31, s15, 0xa000
	s_waitcnt vmcnt(4)
	s_barrier
	global_load_lds_dwordx4 v[32:33], off
	v_lshl_add_u64 v[34:35], v[16:17], 0, s[78:79]
	s_mov_b32 m0, s35
	s_add_u32 s38, s18, 0x10080
	global_load_lds_dwordx4 v[34:35], off
	v_lshl_add_u64 v[28:29], v[8:9], 0, s[78:79]
	s_mov_b32 m0, s30
	s_addc_u32 s39, s19, 0
	s_add_i32 s40, 0, 0x1c000
	v_bitop3_b32 v37, v25, s27, v24 bitop3:0xde
	global_load_lds_dwordx4 v[28:29], off
	v_lshl_add_u64 v[30:31], v[18:19], 0, s[78:79]
	s_mov_b32 m0, s31
	s_add_i32 s27, s40, s36
	global_load_lds_dwordx4 v[30:31], off
	v_lshl_add_u64 v[24:25], s[38:39], 0, v[0:1]
	s_mov_b32 m0, s27
	s_add_i32 s29, s27, 0x2000
	global_load_lds_dwordx4 v[24:25], off
	v_lshl_add_u64 v[26:27], s[38:39], 0, v[22:23]
	s_mov_b32 m0, s29
	s_add_i32 s41, 0, 0x10000
	global_load_lds_dwordx4 v[26:27], off
	v_add_u32_e32 v67, s41, v37
	s_waitcnt vmcnt(6)
	s_barrier
	ds_read_b128 v[38:41], v67
	ds_read_b128 v[42:45], v67 offset:1024
	ds_read_b128 v[46:49], v67 offset:2048
	ds_read_b128 v[50:53], v67 offset:3072
	s_add_i32 s60, 0, 0x14000
	v_add_u32_e32 v66, 0, v36
	v_add_u32_e32 v184, s60, v37
	v_add_u32_e32 v185, s37, v37
	v_add_u32_e32 v36, s40, v37
	s_add_u32 s38, s16, 0x10080
	s_addc_u32 s39, s17, 0
	s_add_i32 s40, s15, 0xc000
	v_lshl_add_u64 v[88:89], s[38:39], 0, v[20:21]
	s_mov_b32 m0, s40
	s_add_i32 s37, s15, 0xe000
	ds_read_b128 v[54:57], v66
	ds_read_b128 v[58:61], v66 offset:1024
	ds_read_b128 v[62:65], v66 offset:2048
	ds_read_b128 v[68:71], v66 offset:3072
	ds_read_b128 v[72:75], v66 offset:4096
	ds_read_b128 v[76:79], v66 offset:5120
	ds_read_b128 v[80:83], v66 offset:6144
	ds_read_b128 v[84:87], v66 offset:7168
	global_load_lds_dwordx4 v[88:89], off
	v_lshl_add_u64 v[88:89], s[38:39], 0, v[2:3]
	s_mov_b32 m0, s37
	s_nop 0
	global_load_lds_dwordx4 v[88:89], off
	s_waitcnt lgkmcnt(8)
	s_barrier
	s_waitcnt lgkmcnt(0)
	s_setprio 1
	s_waitcnt lgkmcnt(0)
	v_mfma_f32_16x16x32_bf16 v[88:91], v[38:41], v[54:57], 0
	v_mfma_f32_16x16x32_bf16 v[92:95], v[46:49], v[54:57], 0
	v_mfma_f32_16x16x32_bf16 v[96:99], v[38:41], v[62:65], 0
	v_mfma_f32_16x16x32_bf16 v[100:103], v[46:49], v[62:65], 0
	v_mfma_f32_16x16x32_bf16 v[104:107], v[38:41], v[72:75], 0
	v_mfma_f32_16x16x32_bf16 v[108:111], v[46:49], v[72:75], 0
	v_mfma_f32_16x16x32_bf16 v[112:115], v[38:41], v[80:83], 0
	v_mfma_f32_16x16x32_bf16 v[116:119], v[46:49], v[80:83], 0
	v_mfma_f32_16x16x32_bf16 v[88:91], v[42:45], v[58:61], v[88:91]
	v_mfma_f32_16x16x32_bf16 v[92:95], v[50:53], v[58:61], v[92:95]
	v_mfma_f32_16x16x32_bf16 v[96:99], v[42:45], v[68:71], v[96:99]
	v_mfma_f32_16x16x32_bf16 v[100:103], v[50:53], v[68:71], v[100:103]
	v_mfma_f32_16x16x32_bf16 v[104:107], v[42:45], v[76:79], v[104:107]
	v_mfma_f32_16x16x32_bf16 v[108:111], v[50:53], v[76:79], v[108:111]
	v_mfma_f32_16x16x32_bf16 v[112:115], v[42:45], v[84:87], v[112:115]
	v_mfma_f32_16x16x32_bf16 v[116:119], v[50:53], v[84:87], v[116:119]
	s_setprio 0
	s_barrier
	s_mov_b64 s[48:49], 0x100
	s_add_i32 s38, s41, s36
	v_lshl_add_u64 v[128:129], v[10:11], 0, s[48:49]
	s_mov_b32 m0, s38
	s_add_i32 s39, s38, 0x2000
	ds_read_b128 v[120:123], v184
	ds_read_b128 v[124:127], v184 offset:1024
	ds_read_b128 v[132:135], v184 offset:2048
	ds_read_b128 v[136:139], v184 offset:3072
	global_load_lds_dwordx4 v[128:129], off
	v_lshl_add_u64 v[128:129], v[16:17], 0, s[48:49]
	s_mov_b32 m0, s39
	s_nop 0
	global_load_lds_dwordx4 v[128:129], off
	s_barrier
	s_waitcnt lgkmcnt(0)
	s_setprio 1
	s_waitcnt lgkmcnt(0)
	v_mfma_f32_16x16x32_bf16 v[140:143], v[120:123], v[54:57], 0
	v_mfma_f32_16x16x32_bf16 v[54:57], v[132:135], v[54:57], 0
	v_mfma_f32_16x16x32_bf16 v[140:143], v[124:127], v[58:61], v[140:143]
	v_mfma_f32_16x16x32_bf16 v[54:57], v[136:139], v[58:61], v[54:57]
	v_mfma_f32_16x16x32_bf16 v[58:61], v[120:123], v[62:65], 0
	v_mfma_f32_16x16x32_bf16 v[62:65], v[132:135], v[62:65], 0
	v_mfma_f32_16x16x32_bf16 v[58:61], v[124:127], v[68:71], v[58:61]
	v_mfma_f32_16x16x32_bf16 v[62:65], v[136:139], v[68:71], v[62:65]
	v_mfma_f32_16x16x32_bf16 v[68:71], v[120:123], v[72:75], 0
	v_mfma_f32_16x16x32_bf16 v[72:75], v[132:135], v[72:75], 0
	v_mfma_f32_16x16x32_bf16 v[68:71], v[124:127], v[76:79], v[68:71]
	v_mfma_f32_16x16x32_bf16 v[72:75], v[136:139], v[76:79], v[72:75]
	v_mfma_f32_16x16x32_bf16 v[76:79], v[120:123], v[80:83], 0
	v_mfma_f32_16x16x32_bf16 v[80:83], v[132:135], v[80:83], 0
	v_mfma_f32_16x16x32_bf16 v[76:79], v[124:127], v[84:87], v[76:79]
	v_mfma_f32_16x16x32_bf16 v[80:83], v[136:139], v[84:87], v[80:83]
	s_setprio 0
	s_mov_b32 m0, s15
	v_lshl_add_u64 v[128:129], v[8:9], 0, s[48:49]
	s_barrier
	ds_read_b128 v[84:87], v66 offset:16384
	ds_read_b128 v[144:147], v66 offset:17408
	ds_read_b128 v[148:151], v66 offset:18432
	ds_read_b128 v[152:155], v66 offset:19456
	ds_read_b128 v[156:159], v66 offset:20480
	ds_read_b128 v[160:163], v66 offset:21504
	ds_read_b128 v[164:167], v66 offset:22528
	ds_read_b128 v[168:171], v66 offset:23552
	global_load_lds_dwordx4 v[128:129], off
	v_lshl_add_u64 v[128:129], v[18:19], 0, s[48:49]
	s_mov_b32 m0, s23
	s_nop 0
	global_load_lds_dwordx4 v[128:129], off
	s_barrier
; #define PG8_STAGE(bufoff, gbase, voff) do { _Pragma("unroll") for (int _i = 0; _i < 2; ++_i) \
;     __builtin_amdgcn_global_load_lds((const unsigned*)((const char*)(gbase) + (voff)[_i]), (LAS unsigned*)(lds + (bufoff) + ldsw + _i * 8192), 16, 0, 0); } while (0)
; #define PG8_LDA(dst, b, h) do { _Pragma("unroll") for (int m = 0; m < 4; ++m) _Pragma("unroll") for (int k = 0; k < 2; ++k) dst[m][k] = *(const LAS bf16x8*)(lds + PG8_SA(b, h) + aoff + m * 2048 + k * 1024); } while (0)
; #define PG8_LDB(dst, b, h) do { _Pragma("unroll") for (int n = 0; n < 2; ++n) _Pragma("unroll") for (int k = 0; k < 2; ++k) dst[n][k] = *(const LAS bf16x8*)(lds + PG8_SB(b, h) + boff + n * 2048 + k * 1024); } while (0)
; #define PG8_MMA(ai, bj, At, Bt) do { __builtin_amdgcn_s_setprio(1); _Pragma("unroll") for (int m = 0; m < 4; ++m) _Pragma("unroll") for (int n = 0; n < 2; ++n) _Pragma("unroll") for (int k = 0; k < 2; ++k) \
;     acc[ai][bj][m][n] = __builtin_amdgcn_mfma_f32_16x16x32_bf16(Bt[n][k], At[m][k], acc[ai][bj][m][n], 0, 0, 0); __builtin_amdgcn_s_setprio(0); } while (0)
; #define PG8_WAIT_V(n) asm volatile("s_waitcnt vmcnt(" #n ")" ::: "memory")
; #define PG8_WAIT_L(n) asm volatile("s_waitcnt lgkmcnt(" #n ")" ::: "memory")
; #define PG8_BAR __builtin_amdgcn_s_barrier()
; #define PG8_SCHED __builtin_amdgcn_sched_barrier(0)
; template <class Epi, class Sched>
; DI void gemm_phase(LAS unsigned char* lds, const Gemm g, const Sched& S, const Epi& E, int wid_k) {
;     ...
;       PG8_BAR; PG8_WAIT_L(0); PG8_MMA(1, 0, At, B0); PG8_BAR; PG8_SCHED;
;       PG8_STAGE(PG8_SB(0, 1), b2 + hstepB, voffB);
;       PG8_WAIT_V(6); PG8_BAR; PG8_MMA(1, 1, At, B1); PG8_BAR;
;       PG8_LDB(B0, 1, 0); PG8_SCHED; PG8_LDA(At, 1, 0); PG8_STAGE(PG8_SA(0, 1), a2 + hstepA, voffA);
;       PG8_WAIT_L(8); PG8_BAR; PG8_WAIT_L(0); PG8_MMA(0, 0, At, B0); PG8_BAR; PG8_SCHED;
;       PG8_LDB(B1, 1, 1); PG8_STAGE(PG8_SB(1, 0), b3, voffB);
	s_waitcnt lgkmcnt(0)
	s_setprio 1
	s_waitcnt lgkmcnt(0)
	v_mfma_f32_16x16x32_bf16 v[172:175], v[38:41], v[84:87], 0
	v_mfma_f32_16x16x32_bf16 v[180:183], v[38:41], v[148:151], 0
	v_mfma_f32_16x16x32_bf16 v[194:197], v[38:41], v[156:159], 0
	v_mfma_f32_16x16x32_bf16 v[38:41], v[38:41], v[164:167], 0
	v_mfma_f32_16x16x32_bf16 v[172:175], v[42:45], v[144:147], v[172:175]
	v_mfma_f32_16x16x32_bf16 v[180:183], v[42:45], v[152:155], v[180:183]
	v_mfma_f32_16x16x32_bf16 v[190:193], v[46:49], v[148:151], 0
	v_mfma_f32_16x16x32_bf16 v[194:197], v[42:45], v[160:163], v[194:197]
	v_mfma_f32_16x16x32_bf16 v[38:41], v[42:45], v[168:171], v[38:41]
	v_mfma_f32_16x16x32_bf16 v[42:45], v[46:49], v[164:167], 0
	v_mfma_f32_16x16x32_bf16 v[176:179], v[46:49], v[84:87], 0
	v_mfma_f32_16x16x32_bf16 v[190:193], v[50:53], v[152:155], v[190:193]
	v_mfma_f32_16x16x32_bf16 v[198:201], v[46:49], v[156:159], 0
	v_mfma_f32_16x16x32_bf16 v[42:45], v[50:53], v[168:171], v[42:45]
	v_mfma_f32_16x16x32_bf16 v[176:179], v[50:53], v[144:147], v[176:179]
	v_mfma_f32_16x16x32_bf16 v[198:201], v[50:53], v[160:163], v[198:201]
	s_setprio 0
	s_barrier
	s_add_u32 s48, s18, 0x10100
	s_addc_u32 s49, s19, 0
	s_add_i32 s36, s60, s36
	v_lshl_add_u64 v[46:47], s[48:49], 0, v[0:1]
	s_mov_b32 m0, s36
	s_add_i32 s41, s36, 0x2000
	global_load_lds_dwordx4 v[46:47], off
	v_lshl_add_u64 v[46:47], s[48:49], 0, v[22:23]
	s_mov_b32 m0, s41
	s_nop 0
	global_load_lds_dwordx4 v[46:47], off
	s_waitcnt vmcnt(6)
	s_barrier
	s_setprio 1
	v_mfma_f32_16x16x32_bf16 v[46:49], v[120:123], v[84:87], 0
	v_mfma_f32_16x16x32_bf16 v[50:53], v[132:135], v[84:87], 0
	v_mfma_f32_16x16x32_bf16 v[46:49], v[124:127], v[144:147], v[46:49]
	v_mfma_f32_16x16x32_bf16 v[50:53], v[136:139], v[144:147], v[50:53]
	v_mfma_f32_16x16x32_bf16 v[84:87], v[120:123], v[148:151], 0
	v_mfma_f32_16x16x32_bf16 v[144:147], v[132:135], v[148:151], 0
	v_mfma_f32_16x16x32_bf16 v[148:151], v[120:123], v[156:159], 0
	v_mfma_f32_16x16x32_bf16 v[120:123], v[120:123], v[164:167], 0
	v_mfma_f32_16x16x32_bf16 v[84:87], v[124:127], v[152:155], v[84:87]
	v_mfma_f32_16x16x32_bf16 v[148:151], v[124:127], v[160:163], v[148:151]
	v_mfma_f32_16x16x32_bf16 v[120:123], v[124:127], v[168:171], v[120:123]
	v_mfma_f32_16x16x32_bf16 v[124:127], v[132:135], v[164:167], 0
	v_mfma_f32_16x16x32_bf16 v[144:147], v[136:139], v[152:155], v[144:147]
	v_mfma_f32_16x16x32_bf16 v[152:155], v[132:135], v[156:159], 0
	v_mfma_f32_16x16x32_bf16 v[124:127], v[136:139], v[168:171], v[124:127]
	v_mfma_f32_16x16x32_bf16 v[152:155], v[136:139], v[160:163], v[152:155]
	s_setprio 0
	s_barrier
	ds_read_b128 v[132:135], v185
	ds_read_b128 v[136:139], v185 offset:1024
	ds_read_b128 v[156:159], v185 offset:2048
	ds_read_b128 v[160:163], v185 offset:3072
	s_add_u32 s48, s16, 0x10100
	s_addc_u32 s49, s17, 0
	s_mov_b32 m0, s21
	v_lshl_add_u64 v[128:129], s[48:49], 0, v[20:21]
	ds_read_b128 v[164:167], v66 offset:32768
	ds_read_b128 v[168:171], v66 offset:33792
	ds_read_b128 v[202:205], v66 offset:34816
	ds_read_b128 v[206:209], v66 offset:35840
	ds_read_b128 v[210:213], v66 offset:36864
	ds_read_b128 v[214:217], v66 offset:37888
	ds_read_b128 v[232:235], v66 offset:38912
	ds_read_b128 v[236:239], v66 offset:39936
	global_load_lds_dwordx4 v[128:129], off
	v_lshl_add_u64 v[128:129], s[48:49], 0, v[2:3]
	s_mov_b32 m0, s22
	s_nop 0
	global_load_lds_dwordx4 v[128:129], off
	s_waitcnt lgkmcnt(8)
	s_barrier
	s_waitcnt lgkmcnt(0)
	s_setprio 1
	s_waitcnt lgkmcnt(0)
	v_mfma_f32_16x16x32_bf16 v[88:91], v[132:135], v[164:167], v[88:91]
	v_mfma_f32_16x16x32_bf16 v[92:95], v[156:159], v[164:167], v[92:95]
	v_mfma_f32_16x16x32_bf16 v[96:99], v[132:135], v[202:205], v[96:99]
	v_mfma_f32_16x16x32_bf16 v[100:103], v[156:159], v[202:205], v[100:103]
	v_mfma_f32_16x16x32_bf16 v[104:107], v[132:135], v[210:213], v[104:107]
	v_mfma_f32_16x16x32_bf16 v[108:111], v[156:159], v[210:213], v[108:111]
	v_mfma_f32_16x16x32_bf16 v[112:115], v[132:135], v[232:235], v[112:115]
	v_mfma_f32_16x16x32_bf16 v[116:119], v[156:159], v[232:235], v[116:119]
	v_mfma_f32_16x16x32_bf16 v[88:91], v[136:139], v[168:171], v[88:91]
	v_mfma_f32_16x16x32_bf16 v[92:95], v[160:163], v[168:171], v[92:95]
	v_mfma_f32_16x16x32_bf16 v[96:99], v[136:139], v[206:209], v[96:99]
	v_mfma_f32_16x16x32_bf16 v[100:103], v[160:163], v[206:209], v[100:103]
	v_mfma_f32_16x16x32_bf16 v[104:107], v[136:139], v[214:217], v[104:107]
	v_mfma_f32_16x16x32_bf16 v[108:111], v[160:163], v[214:217], v[108:111]
	v_mfma_f32_16x16x32_bf16 v[112:115], v[136:139], v[236:239], v[112:115]
	v_mfma_f32_16x16x32_bf16 v[116:119], v[160:163], v[236:239], v[116:119]
	s_setprio 0
	s_barrier
	s_mov_b64 s[48:49], 0x180
	s_mov_b32 m0, s34
	v_lshl_add_u64 v[128:129], v[10:11], 0, s[48:49]
	ds_read_b128 v[240:243], v36
	ds_read_b128 v[244:247], v36 offset:1024
	ds_read_b128 v[248:251], v36 offset:2048
	ds_read_b128 v[222:225], v36 offset:3072
	global_load_lds_dwordx4 v[128:129], off
	v_lshl_add_u64 v[128:129], v[16:17], 0, s[48:49]
	s_mov_b32 m0, s35
	s_nop 0
	global_load_lds_dwordx4 v[128:129], off
	s_barrier
; #define PG8_STAGE(bufoff, gbase, voff) do { _Pragma("unroll") for (int _i = 0; _i < 2; ++_i) \
;     __builtin_amdgcn_global_load_lds((const unsigned*)((const char*)(gbase) + (voff)[_i]), (LAS unsigned*)(lds + (bufoff) + ldsw + _i * 8192), 16, 0, 0); } while (0)
; #define PG8_LDA(dst, b, h) do { _Pragma("unroll") for (int m = 0; m < 4; ++m) _Pragma("unroll") for (int k = 0; k < 2; ++k) dst[m][k] = *(const LAS bf16x8*)(lds + PG8_SA(b, h) + aoff + m * 2048 + k * 1024); } while (0)
; #define PG8_LDB(dst, b, h) do { _Pragma("unroll") for (int n = 0; n < 2; ++n) _Pragma("unroll") for (int k = 0; k < 2; ++k) dst[n][k] = *(const LAS bf16x8*)(lds + PG8_SB(b, h) + boff + n * 2048 + k * 1024); } while (0)
; #define PG8_MMA(ai, bj, At, Bt) do { __builtin_amdgcn_s_setprio(1); _Pragma("unroll") for (int m = 0; m < 4; ++m) _Pragma("unroll") for (int n = 0; n < 2; ++n) _Pragma("unroll") for (int k = 0; k < 2; ++k) \
;     acc[ai][bj][m][n] = __builtin_amdgcn_mfma_f32_16x16x32_bf16(Bt[n][k], At[m][k], acc[ai][bj][m][n], 0, 0, 0); __builtin_amdgcn_s_setprio(0); } while (0)
; #define PG8_WAIT_V(n) asm volatile("s_waitcnt vmcnt(" #n ")" ::: "memory")
; #define PG8_WAIT_L(n) asm volatile("s_waitcnt lgkmcnt(" #n ")" ::: "memory")
; #define PG8_BAR __builtin_amdgcn_s_barrier()
; #define PG8_SCHED __builtin_amdgcn_sched_barrier(0)
; template <class Epi, class Sched>
; DI void gemm_phase(LAS unsigned char* lds, const Gemm g, const Sched& S, const Epi& E, int wid_k) {
;     ...
;       PG8_LDB(B0, 0, 0); PG8_SCHED; PG8_LDA(At, 0, 0); PG8_STAGE(PG8_SA(1, 1), a1 + hstepA, voffA);
;     ...
;       PG8_BAR; PG8_WAIT_L(0); PG8_MMA(0, 1, At, B1); PG8_BAR;
;       PG8_LDA(At, 1, 1); PG8_STAGE(PG8_SA(1, 0), a3, voffA);
;       PG8_BAR; PG8_WAIT_L(0); PG8_MMA(1, 0, At, B0); PG8_BAR; PG8_SCHED;
;       PG8_STAGE(PG8_SB(1, 1), b3 + hstepB, voffB);
;       PG8_WAIT_V(6); PG8_BAR; PG8_MMA(1, 1, At, B1); PG8_BAR;
	s_waitcnt lgkmcnt(0)
	s_setprio 1
	s_waitcnt lgkmcnt(0)
	v_mfma_f32_16x16x32_bf16 v[54:57], v[248:251], v[164:167], v[54:57]
	v_mfma_f32_16x16x32_bf16 v[58:61], v[240:243], v[202:205], v[58:61]
	v_mfma_f32_16x16x32_bf16 v[62:65], v[248:251], v[202:205], v[62:65]
	v_mfma_f32_16x16x32_bf16 v[68:71], v[240:243], v[210:213], v[68:71]
	v_mfma_f32_16x16x32_bf16 v[72:75], v[248:251], v[210:213], v[72:75]
	v_mfma_f32_16x16x32_bf16 v[76:79], v[240:243], v[232:235], v[76:79]
	v_mfma_f32_16x16x32_bf16 v[80:83], v[248:251], v[232:235], v[80:83]
	v_mfma_f32_16x16x32_bf16 v[140:143], v[240:243], v[164:167], v[140:143]
	v_mfma_f32_16x16x32_bf16 v[54:57], v[222:225], v[168:171], v[54:57]
	v_mfma_f32_16x16x32_bf16 v[58:61], v[244:247], v[206:209], v[58:61]
	v_mfma_f32_16x16x32_bf16 v[62:65], v[222:225], v[206:209], v[62:65]
	v_mfma_f32_16x16x32_bf16 v[68:71], v[244:247], v[214:217], v[68:71]
	v_mfma_f32_16x16x32_bf16 v[72:75], v[222:225], v[214:217], v[72:75]
	v_mfma_f32_16x16x32_bf16 v[76:79], v[244:247], v[236:239], v[76:79]
	v_mfma_f32_16x16x32_bf16 v[80:83], v[222:225], v[236:239], v[80:83]
	v_mfma_f32_16x16x32_bf16 v[140:143], v[244:247], v[168:171], v[140:143]
	s_setprio 0
	s_mov_b32 m0, s30
	v_lshl_add_u64 v[128:129], v[8:9], 0, s[48:49]
	s_barrier
	ds_read_b128 v[164:167], v66 offset:49152
	ds_read_b128 v[168:171], v66 offset:50176
	ds_read_b128 v[202:205], v66 offset:51200
	ds_read_b128 v[206:209], v66 offset:52224
	ds_read_b128 v[210:213], v66 offset:53248
	ds_read_b128 v[214:217], v66 offset:54272
	ds_read_b128 v[232:235], v66 offset:55296
	ds_read_b128 v[236:239], v66 offset:56320
	global_load_lds_dwordx4 v[128:129], off
	v_lshl_add_u64 v[128:129], v[18:19], 0, s[48:49]
	s_mov_b32 m0, s31
	s_nop 0
	global_load_lds_dwordx4 v[128:129], off
	s_barrier
	s_waitcnt lgkmcnt(0)
	s_setprio 1
	s_waitcnt lgkmcnt(0)
	v_mfma_f32_16x16x32_bf16 v[190:193], v[156:159], v[202:205], v[190:193]
	v_mfma_f32_16x16x32_bf16 v[38:41], v[132:135], v[232:235], v[38:41]
	v_mfma_f32_16x16x32_bf16 v[42:45], v[156:159], v[232:235], v[42:45]
	v_mfma_f32_16x16x32_bf16 v[172:175], v[132:135], v[164:167], v[172:175]
	v_mfma_f32_16x16x32_bf16 v[176:179], v[156:159], v[164:167], v[176:179]
	v_mfma_f32_16x16x32_bf16 v[180:183], v[132:135], v[202:205], v[180:183]
	v_mfma_f32_16x16x32_bf16 v[190:193], v[160:163], v[206:209], v[190:193]
	v_mfma_f32_16x16x32_bf16 v[194:197], v[132:135], v[210:213], v[194:197]
	v_mfma_f32_16x16x32_bf16 v[198:201], v[156:159], v[210:213], v[198:201]
	v_mfma_f32_16x16x32_bf16 v[38:41], v[136:139], v[236:239], v[38:41]
	v_mfma_f32_16x16x32_bf16 v[42:45], v[160:163], v[236:239], v[42:45]
	v_mfma_f32_16x16x32_bf16 v[172:175], v[136:139], v[168:171], v[172:175]
	v_mfma_f32_16x16x32_bf16 v[176:179], v[160:163], v[168:171], v[176:179]
	v_mfma_f32_16x16x32_bf16 v[180:183], v[136:139], v[206:209], v[180:183]
	v_mfma_f32_16x16x32_bf16 v[194:197], v[136:139], v[214:217], v[194:197]
	v_mfma_f32_16x16x32_bf16 v[198:201], v[160:163], v[214:217], v[198:201]
	s_setprio 0
	s_barrier
	s_add_u32 s18, s18, 0x10180
	s_addc_u32 s19, s19, 0
	s_mov_b32 m0, s27
	v_lshl_add_u64 v[128:129], s[18:19], 0, v[0:1]
	global_load_lds_dwordx4 v[128:129], off
	v_lshl_add_u64 v[22:23], s[18:19], 0, v[22:23]
	s_mov_b32 m0, s29
	s_nop 0
	global_load_lds_dwordx4 v[22:23], off
	s_waitcnt vmcnt(6)
	s_barrier
	s_setprio 1
	v_mfma_f32_16x16x32_bf16 v[46:49], v[240:243], v[164:167], v[46:49]
	v_mfma_f32_16x16x32_bf16 v[50:53], v[248:251], v[164:167], v[50:53]
	v_mfma_f32_16x16x32_bf16 v[84:87], v[240:243], v[202:205], v[84:87]
	v_mfma_f32_16x16x32_bf16 v[120:123], v[240:243], v[232:235], v[120:123]
	v_mfma_f32_16x16x32_bf16 v[124:127], v[248:251], v[232:235], v[124:127]
	v_mfma_f32_16x16x32_bf16 v[46:49], v[244:247], v[168:171], v[46:49]
	v_mfma_f32_16x16x32_bf16 v[50:53], v[222:225], v[168:171], v[50:53]
	v_mfma_f32_16x16x32_bf16 v[84:87], v[244:247], v[206:209], v[84:87]
	v_mfma_f32_16x16x32_bf16 v[132:135], v[248:251], v[202:205], v[144:147]
	v_mfma_f32_16x16x32_bf16 v[136:139], v[240:243], v[210:213], v[148:151]
	v_mfma_f32_16x16x32_bf16 v[144:147], v[248:251], v[210:213], v[152:155]
	v_mfma_f32_16x16x32_bf16 v[120:123], v[244:247], v[236:239], v[120:123]
	v_mfma_f32_16x16x32_bf16 v[124:127], v[222:225], v[236:239], v[124:127]
	v_mfma_f32_16x16x32_bf16 v[132:135], v[222:225], v[206:209], v[132:135]
	v_mfma_f32_16x16x32_bf16 v[136:139], v[244:247], v[214:217], v[136:139]
	v_mfma_f32_16x16x32_bf16 v[144:147], v[222:225], v[214:217], v[144:147]
	s_setprio 0
	s_barrier
	ds_read_b128 v[148:151], v67
	ds_read_b128 v[152:155], v67 offset:1024
	ds_read_b128 v[156:159], v67 offset:2048
	ds_read_b128 v[160:163], v67 offset:3072
	s_add_u32 s16, s16, 0x10180
	s_addc_u32 s17, s17, 0
	s_mov_b32 m0, s40
	v_lshl_add_u64 v[20:21], s[16:17], 0, v[20:21]
	ds_read_b128 v[164:167], v66
	ds_read_b128 v[168:171], v66 offset:1024
	ds_read_b128 v[202:205], v66 offset:2048
	ds_read_b128 v[206:209], v66 offset:3072
	ds_read_b128 v[210:213], v66 offset:4096
	ds_read_b128 v[214:217], v66 offset:5120
	ds_read_b128 v[222:225], v66 offset:6144
	ds_read_b128 v[232:235], v66 offset:7168
	global_load_lds_dwordx4 v[20:21], off
	v_lshl_add_u64 v[2:3], s[16:17], 0, v[2:3]
	s_mov_b32 m0, s37
	s_nop 0
	global_load_lds_dwordx4 v[2:3], off
	s_waitcnt lgkmcnt(8)
	s_barrier
; #define PG8_STAGE(bufoff, gbase, voff) do { _Pragma("unroll") for (int _i = 0; _i < 2; ++_i) \
;     __builtin_amdgcn_global_load_lds((const unsigned*)((const char*)(gbase) + (voff)[_i]), (LAS unsigned*)(lds + (bufoff) + ldsw + _i * 8192), 16, 0, 0); } while (0)
; #define PG8_LDA(dst, b, h) do { _Pragma("unroll") for (int m = 0; m < 4; ++m) _Pragma("unroll") for (int k = 0; k < 2; ++k) dst[m][k] = *(const LAS bf16x8*)(lds + PG8_SA(b, h) + aoff + m * 2048 + k * 1024); } while (0)
; #define PG8_LDB(dst, b, h) do { _Pragma("unroll") for (int n = 0; n < 2; ++n) _Pragma("unroll") for (int k = 0; k < 2; ++k) dst[n][k] = *(const LAS bf16x8*)(lds + PG8_SB(b, h) + boff + n * 2048 + k * 1024); } while (0)
; #define PG8_MMA(ai, bj, At, Bt) do { __builtin_amdgcn_s_setprio(1); _Pragma("unroll") for (int m = 0; m < 4; ++m) _Pragma("unroll") for (int n = 0; n < 2; ++n) _Pragma("unroll") for (int k = 0; k < 2; ++k) \
;     acc[ai][bj][m][n] = __builtin_amdgcn_mfma_f32_16x16x32_bf16(Bt[n][k], At[m][k], acc[ai][bj][m][n], 0, 0, 0); __builtin_amdgcn_s_setprio(0); } while (0)
; #define PG8_WAIT_V(n) asm volatile("s_waitcnt vmcnt(" #n ")" ::: "memory")
; #define PG8_WAIT_L(n) asm volatile("s_waitcnt lgkmcnt(" #n ")" ::: "memory")
; #define PG8_BAR __builtin_amdgcn_s_barrier()
; #define PG8_SCHED __builtin_amdgcn_sched_barrier(0)
; template <class Epi, class Sched>
; DI void gemm_phase(LAS unsigned char* lds, const Gemm g, const Sched& S, const Epi& E, int wid_k) {
;     ...
;       PG8_WAIT_L(8); PG8_BAR; PG8_WAIT_L(0); PG8_MMA(0, 0, At, B0); PG8_BAR; PG8_SCHED;
;       PG8_LDB(B1, 0, 1); PG8_STAGE(PG8_SB(0, 0), b2, voffB);
;       PG8_BAR; PG8_WAIT_L(0); PG8_MMA(0, 1, At, B1); PG8_BAR;
;       PG8_LDA(At, 0, 1); PG8_STAGE(PG8_SA(0, 0), a2, voffA);
;       PG8_BAR; PG8_WAIT_L(0); PG8_MMA(1, 0, At, B0); PG8_BAR; PG8_SCHED;
;       PG8_STAGE(PG8_SB(0, 1), b2 + hstepB, voffB);
;       PG8_WAIT_V(6); PG8_BAR; PG8_MMA(1, 1, At, B1); PG8_BAR;
	s_waitcnt lgkmcnt(0)
	s_setprio 1
	s_waitcnt lgkmcnt(0)
	v_mfma_f32_16x16x32_bf16 v[20:23], v[148:151], v[164:167], v[88:91]
	v_mfma_f32_16x16x32_bf16 v[88:91], v[156:159], v[164:167], v[92:95]
	v_mfma_f32_16x16x32_bf16 v[92:95], v[148:151], v[202:205], v[96:99]
	v_mfma_f32_16x16x32_bf16 v[96:99], v[156:159], v[202:205], v[100:103]
	v_mfma_f32_16x16x32_bf16 v[100:103], v[148:151], v[210:213], v[104:107]
	v_mfma_f32_16x16x32_bf16 v[104:107], v[156:159], v[210:213], v[108:111]
	v_mfma_f32_16x16x32_bf16 v[108:111], v[148:151], v[222:225], v[112:115]
	v_mfma_f32_16x16x32_bf16 v[20:23], v[152:155], v[168:171], v[20:23]
	v_mfma_f32_16x16x32_bf16 v[88:91], v[160:163], v[168:171], v[88:91]
	v_mfma_f32_16x16x32_bf16 v[92:95], v[152:155], v[206:209], v[92:95]
	v_mfma_f32_16x16x32_bf16 v[96:99], v[160:163], v[206:209], v[96:99]
	v_mfma_f32_16x16x32_bf16 v[100:103], v[152:155], v[214:217], v[100:103]
	v_mfma_f32_16x16x32_bf16 v[104:107], v[160:163], v[214:217], v[104:107]
	v_mfma_f32_16x16x32_bf16 v[236:239], v[152:155], v[232:235], v[108:111]
	v_mfma_f32_16x16x32_bf16 v[108:111], v[156:159], v[222:225], v[116:119]
	v_mfma_f32_16x16x32_bf16 v[240:243], v[160:163], v[232:235], v[108:111]
	s_setprio 0
	s_barrier
	s_mov_b32 m0, s38
	s_nop 3
	ds_read_b128 v[108:111], v184
	ds_read_b128 v[112:115], v184 offset:1024
	ds_read_b128 v[116:119], v184 offset:2048
	ds_read_b128 v[244:247], v184 offset:3072
	global_load_lds_dwordx4 v[10:11], off
	s_mov_b32 m0, s39
	s_nop 0
	global_load_lds_dwordx4 v[16:17], off
	s_barrier
	s_waitcnt lgkmcnt(0)
	s_setprio 1
	s_waitcnt lgkmcnt(0)
	v_mfma_f32_16x16x32_bf16 v[58:61], v[108:111], v[202:205], v[58:61]
	v_mfma_f32_16x16x32_bf16 v[140:143], v[108:111], v[164:167], v[140:143]
	v_mfma_f32_16x16x32_bf16 v[54:57], v[116:119], v[164:167], v[54:57]
	v_mfma_f32_16x16x32_bf16 v[164:167], v[112:115], v[206:209], v[58:61]
	v_mfma_f32_16x16x32_bf16 v[58:61], v[116:119], v[202:205], v[62:65]
	v_mfma_f32_16x16x32_bf16 v[140:143], v[112:115], v[168:171], v[140:143]
	v_mfma_f32_16x16x32_bf16 v[54:57], v[244:247], v[168:171], v[54:57]
	v_mfma_f32_16x16x32_bf16 v[168:171], v[244:247], v[206:209], v[58:61]
	v_mfma_f32_16x16x32_bf16 v[58:61], v[108:111], v[210:213], v[68:71]
	v_mfma_f32_16x16x32_bf16 v[68:71], v[112:115], v[214:217], v[58:61]
	v_mfma_f32_16x16x32_bf16 v[58:61], v[116:119], v[210:213], v[72:75]
	v_mfma_f32_16x16x32_bf16 v[72:75], v[244:247], v[214:217], v[58:61]
	v_mfma_f32_16x16x32_bf16 v[58:61], v[108:111], v[222:225], v[76:79]
	v_mfma_f32_16x16x32_bf16 v[76:79], v[112:115], v[232:235], v[58:61]
	v_mfma_f32_16x16x32_bf16 v[58:61], v[116:119], v[222:225], v[80:83]
	v_mfma_f32_16x16x32_bf16 v[80:83], v[244:247], v[232:235], v[58:61]
	s_setprio 0
	s_mov_b32 m0, s15
	s_barrier
	s_nop 3
	ds_read_b128 v[58:61], v66 offset:16384
	ds_read_b128 v[62:65], v66 offset:17408
	ds_read_b128 v[202:205], v66 offset:18432
	ds_read_b128 v[206:209], v66 offset:19456
	ds_read_b128 v[210:213], v66 offset:20480
	ds_read_b128 v[214:217], v66 offset:21504
	ds_read_b128 v[222:225], v66 offset:22528
	ds_read_b128 v[232:235], v66 offset:23552
	global_load_lds_dwordx4 v[8:9], off
	s_mov_b32 m0, s23
	s_nop 0
	global_load_lds_dwordx4 v[18:19], off
	s_barrier
	s_waitcnt lgkmcnt(0)
	s_setprio 1
	s_waitcnt lgkmcnt(0)
	v_mfma_f32_16x16x32_bf16 v[8:11], v[148:151], v[58:61], v[172:175]
	v_mfma_f32_16x16x32_bf16 v[16:19], v[156:159], v[58:61], v[176:179]
	v_mfma_f32_16x16x32_bf16 v[176:179], v[156:159], v[202:205], v[190:193]
	v_mfma_f32_16x16x32_bf16 v[190:193], v[156:159], v[210:213], v[198:201]
	v_mfma_f32_16x16x32_bf16 v[38:41], v[148:151], v[222:225], v[38:41]
	v_mfma_f32_16x16x32_bf16 v[8:11], v[152:155], v[62:65], v[8:11]
	v_mfma_f32_16x16x32_bf16 v[16:19], v[160:163], v[62:65], v[16:19]
	v_mfma_f32_16x16x32_bf16 v[172:175], v[148:151], v[202:205], v[180:183]
	v_mfma_f32_16x16x32_bf16 v[180:183], v[148:151], v[210:213], v[194:197]
	v_mfma_f32_16x16x32_bf16 v[190:193], v[160:163], v[214:217], v[190:193]
	v_mfma_f32_16x16x32_bf16 v[148:151], v[152:155], v[232:235], v[38:41]
	v_mfma_f32_16x16x32_bf16 v[38:41], v[156:159], v[222:225], v[42:45]
	v_mfma_f32_16x16x32_bf16 v[172:175], v[152:155], v[206:209], v[172:175]
	v_mfma_f32_16x16x32_bf16 v[176:179], v[160:163], v[206:209], v[176:179]
	v_mfma_f32_16x16x32_bf16 v[180:183], v[152:155], v[214:217], v[180:183]
	v_mfma_f32_16x16x32_bf16 v[152:155], v[160:163], v[232:235], v[38:41]
	s_setprio 0
	s_barrier
	s_mov_b32 m0, s36
	s_nop 0
	global_load_lds_dwordx4 v[12:13], off
	s_mov_b32 m0, s41
	s_nop 0
	global_load_lds_dwordx4 v[14:15], off
	s_waitcnt vmcnt(6)
	s_barrier
	s_setprio 1
	v_mfma_f32_16x16x32_bf16 v[38:41], v[116:119], v[58:61], v[50:53]
	v_mfma_f32_16x16x32_bf16 v[156:159], v[244:247], v[62:65], v[38:41]
	v_mfma_f32_16x16x32_bf16 v[38:41], v[108:111], v[202:205], v[84:87]
	v_mfma_f32_16x16x32_bf16 v[160:163], v[112:115], v[206:209], v[38:41]
	v_mfma_f32_16x16x32_bf16 v[38:41], v[116:119], v[202:205], v[132:135]
	v_mfma_f32_16x16x32_bf16 v[132:135], v[244:247], v[206:209], v[38:41]
	v_mfma_f32_16x16x32_bf16 v[38:41], v[108:111], v[210:213], v[136:139]
	v_mfma_f32_16x16x32_bf16 v[136:139], v[112:115], v[214:217], v[38:41]
	v_mfma_f32_16x16x32_bf16 v[38:41], v[116:119], v[210:213], v[144:147]
	v_mfma_f32_16x16x32_bf16 v[12:15], v[108:111], v[58:61], v[46:49]
	v_mfma_f32_16x16x32_bf16 v[144:147], v[244:247], v[214:217], v[38:41]
	v_mfma_f32_16x16x32_bf16 v[38:41], v[108:111], v[222:225], v[120:123]
	v_mfma_f32_16x16x32_bf16 v[12:15], v[112:115], v[62:65], v[12:15]
	v_mfma_f32_16x16x32_bf16 v[194:197], v[112:115], v[232:235], v[38:41]
	v_mfma_f32_16x16x32_bf16 v[38:41], v[116:119], v[222:225], v[124:127]
	v_mfma_f32_16x16x32_bf16 v[198:201], v[244:247], v[232:235], v[38:41]
	s_setprio 0
	s_barrier
; #define PG8_STAGE(bufoff, gbase, voff) do { _Pragma("unroll") for (int _i = 0; _i < 2; ++_i) \
;     __builtin_amdgcn_global_load_lds((const unsigned*)((const char*)(gbase) + (voff)[_i]), (LAS unsigned*)(lds + (bufoff) + ldsw + _i * 8192), 16, 0, 0); } while (0)
; #define PG8_LDA(dst, b, h) do { _Pragma("unroll") for (int m = 0; m < 4; ++m) _Pragma("unroll") for (int k = 0; k < 2; ++k) dst[m][k] = *(const LAS bf16x8*)(lds + PG8_SA(b, h) + aoff + m * 2048 + k * 1024); } while (0)
; #define PG8_LDB(dst, b, h) do { _Pragma("unroll") for (int n = 0; n < 2; ++n) _Pragma("unroll") for (int k = 0; k < 2; ++k) dst[n][k] = *(const LAS bf16x8*)(lds + PG8_SB(b, h) + boff + n * 2048 + k * 1024); } while (0)
; #define PG8_MMA(ai, bj, At, Bt) do { __builtin_amdgcn_s_setprio(1); _Pragma("unroll") for (int m = 0; m < 4; ++m) _Pragma("unroll") for (int n = 0; n < 2; ++n) _Pragma("unroll") for (int k = 0; k < 2; ++k) \
;     acc[ai][bj][m][n] = __builtin_amdgcn_mfma_f32_16x16x32_bf16(Bt[n][k], At[m][k], acc[ai][bj][m][n], 0, 0, 0); __builtin_amdgcn_s_setprio(0); } while (0)
; #define PG8_WAIT_V(n) asm volatile("s_waitcnt vmcnt(" #n ")" ::: "memory")
; #define PG8_WAIT_L(n) asm volatile("s_waitcnt lgkmcnt(" #n ")" ::: "memory")
; #define PG8_BAR __builtin_amdgcn_s_barrier()
; #define PG8_SCHED __builtin_amdgcn_sched_barrier(0)
; template <class Epi, class Sched>
; DI void gemm_phase(LAS unsigned char* lds, const Gemm g, const Sched& S, const Epi& E, int wid_k) {
;     ...
;       PG8_LDB(B0, 1, 0); PG8_SCHED; PG8_LDA(At, 1, 0); PG8_STAGE(PG8_SA(0, 1), a2 + hstepA, voffA);
;       PG8_WAIT_L(8); PG8_BAR; PG8_WAIT_L(0); PG8_MMA(0, 0, At, B0); PG8_BAR; PG8_SCHED;
;       PG8_LDB(B1, 1, 1); PG8_STAGE(PG8_SB(1, 0), b3, voffB);
;       PG8_BAR; PG8_WAIT_L(0); PG8_MMA(0, 1, At, B1); PG8_BAR;
;       PG8_LDA(At, 1, 1); PG8_STAGE(PG8_SA(1, 0), a3, voffA);
;       PG8_BAR; PG8_WAIT_L(0); PG8_MMA(1, 0, At, B0); PG8_BAR; PG8_SCHED;
;       PG8_STAGE(PG8_SB(1, 1), b3 + hstepB, voffB);
;       PG8_WAIT_V(6); PG8_BAR; PG8_MMA(1, 1, At, B1); PG8_BAR;
	ds_read_b128 v[202:205], v185
	ds_read_b128 v[206:209], v185 offset:1024
	ds_read_b128 v[210:213], v185 offset:2048
	ds_read_b128 v[214:217], v185 offset:3072
	s_mov_b32 m0, s21
	ds_read_b128 v[38:41], v66 offset:32768
	ds_read_b128 v[42:45], v66 offset:33792
	ds_read_b128 v[46:49], v66 offset:34816
	ds_read_b128 v[50:53], v66 offset:35840
	ds_read_b128 v[84:87], v66 offset:36864
	ds_read_b128 v[222:225], v66 offset:37888
	ds_read_b128 v[232:235], v66 offset:38912
	ds_read_b128 v[244:247], v66 offset:39936
	global_load_lds_dwordx4 v[4:5], off
	s_mov_b32 m0, s22
	s_nop 0
	global_load_lds_dwordx4 v[6:7], off
	s_waitcnt lgkmcnt(8)
	s_barrier
	s_waitcnt lgkmcnt(0)
	s_setprio 1
	s_waitcnt lgkmcnt(0)
	v_mfma_f32_16x16x32_bf16 v[2:5], v[202:205], v[38:41], v[20:23]
	v_mfma_f32_16x16x32_bf16 v[126:129], v[206:209], v[42:45], v[2:5]
	v_mfma_f32_16x16x32_bf16 v[2:5], v[210:213], v[38:41], v[88:91]
	v_mfma_f32_16x16x32_bf16 v[122:125], v[214:217], v[42:45], v[2:5]
	v_mfma_f32_16x16x32_bf16 v[2:5], v[202:205], v[46:49], v[92:95]
	v_mfma_f32_16x16x32_bf16 v[118:121], v[206:209], v[50:53], v[2:5]
	v_mfma_f32_16x16x32_bf16 v[2:5], v[210:213], v[46:49], v[96:99]
	v_mfma_f32_16x16x32_bf16 v[114:117], v[214:217], v[50:53], v[2:5]
	v_mfma_f32_16x16x32_bf16 v[2:5], v[202:205], v[84:87], v[100:103]
	v_mfma_f32_16x16x32_bf16 v[110:113], v[206:209], v[222:225], v[2:5]
	v_mfma_f32_16x16x32_bf16 v[2:5], v[210:213], v[84:87], v[104:107]
	v_mfma_f32_16x16x32_bf16 v[106:109], v[214:217], v[222:225], v[2:5]
	v_mfma_f32_16x16x32_bf16 v[2:5], v[202:205], v[232:235], v[236:239]
	v_mfma_f32_16x16x32_bf16 v[102:105], v[206:209], v[244:247], v[2:5]
	v_mfma_f32_16x16x32_bf16 v[2:5], v[210:213], v[232:235], v[240:243]
	v_mfma_f32_16x16x32_bf16 v[98:101], v[214:217], v[244:247], v[2:5]
	s_setprio 0
	s_barrier
	s_mov_b32 m0, s34
	s_nop 3
	ds_read_b128 v[2:5], v36
	ds_read_b128 v[236:239], v36 offset:1024
	ds_read_b128 v[240:243], v36 offset:2048
	ds_read_b128 v[248:251], v36 offset:3072
	global_load_lds_dwordx4 v[32:33], off
	s_mov_b32 m0, s35
	s_nop 0
	global_load_lds_dwordx4 v[34:35], off
	s_barrier
	s_waitcnt lgkmcnt(0)
	s_setprio 1
	s_waitcnt lgkmcnt(0)
	v_mfma_f32_16x16x32_bf16 v[20:23], v[2:5], v[38:41], v[140:143]
	v_mfma_f32_16x16x32_bf16 v[62:65], v[236:239], v[42:45], v[20:23]
	v_mfma_f32_16x16x32_bf16 v[20:23], v[240:243], v[38:41], v[54:57]
	v_mfma_f32_16x16x32_bf16 v[58:61], v[248:251], v[42:45], v[20:23]
	v_mfma_f32_16x16x32_bf16 v[20:23], v[2:5], v[46:49], v[164:167]
	v_mfma_f32_16x16x32_bf16 v[54:57], v[236:239], v[50:53], v[20:23]
	v_mfma_f32_16x16x32_bf16 v[20:23], v[240:243], v[46:49], v[168:171]
	v_mfma_f32_16x16x32_bf16 v[50:53], v[248:251], v[50:53], v[20:23]
	v_mfma_f32_16x16x32_bf16 v[20:23], v[2:5], v[84:87], v[68:71]
	v_mfma_f32_16x16x32_bf16 v[46:49], v[236:239], v[222:225], v[20:23]
	v_mfma_f32_16x16x32_bf16 v[20:23], v[240:243], v[84:87], v[72:75]
	v_mfma_f32_16x16x32_bf16 v[42:45], v[248:251], v[222:225], v[20:23]
	v_mfma_f32_16x16x32_bf16 v[20:23], v[2:5], v[232:235], v[76:79]
	v_mfma_f32_16x16x32_bf16 v[38:41], v[236:239], v[244:247], v[20:23]
	v_mfma_f32_16x16x32_bf16 v[20:23], v[240:243], v[232:235], v[80:83]
	v_mfma_f32_16x16x32_bf16 v[184:187], v[248:251], v[244:247], v[20:23]
	s_setprio 0
	s_mov_b32 m0, s30
	s_barrier
	s_nop 3
	ds_read_b128 v[20:23], v66 offset:49152
	ds_read_b128 v[140:143], v66 offset:50176
	ds_read_b128 v[164:167], v66 offset:51200
	ds_read_b128 v[168:171], v66 offset:52224
	ds_read_b128 v[222:225], v66 offset:53248
	ds_read_b128 v[232:235], v66 offset:54272
	ds_read_b128 v[244:247], v66 offset:55296
	ds_read_b128 v[32:35], v66 offset:56320
	global_load_lds_dwordx4 v[28:29], off
	s_mov_b32 m0, s31
	s_nop 0
	global_load_lds_dwordx4 v[30:31], off
	s_barrier
	s_waitcnt lgkmcnt(0)
	s_setprio 1
	s_waitcnt lgkmcnt(0)
	v_mfma_f32_16x16x32_bf16 v[6:9], v[202:205], v[20:23], v[8:11]
	v_mfma_f32_16x16x32_bf16 v[94:97], v[206:209], v[140:143], v[6:9]
	v_mfma_f32_16x16x32_bf16 v[6:9], v[210:213], v[20:23], v[16:19]
	v_mfma_f32_16x16x32_bf16 v[90:93], v[214:217], v[140:143], v[6:9]
	v_mfma_f32_16x16x32_bf16 v[6:9], v[202:205], v[164:167], v[172:175]
	v_mfma_f32_16x16x32_bf16 v[86:89], v[206:209], v[168:171], v[6:9]
	v_mfma_f32_16x16x32_bf16 v[6:9], v[210:213], v[164:167], v[176:179]
	v_mfma_f32_16x16x32_bf16 v[82:85], v[214:217], v[168:171], v[6:9]
	v_mfma_f32_16x16x32_bf16 v[6:9], v[202:205], v[222:225], v[180:183]
	v_mfma_f32_16x16x32_bf16 v[78:81], v[206:209], v[232:235], v[6:9]
	v_mfma_f32_16x16x32_bf16 v[6:9], v[210:213], v[222:225], v[190:193]
	v_mfma_f32_16x16x32_bf16 v[74:77], v[214:217], v[232:235], v[6:9]
	v_mfma_f32_16x16x32_bf16 v[6:9], v[202:205], v[244:247], v[148:151]
	v_mfma_f32_16x16x32_bf16 v[70:73], v[206:209], v[32:35], v[6:9]
	v_mfma_f32_16x16x32_bf16 v[6:9], v[210:213], v[244:247], v[152:155]
	v_mfma_f32_16x16x32_bf16 v[66:69], v[214:217], v[32:35], v[6:9]
	s_setprio 0
	s_barrier
	s_mov_b32 m0, s27
	s_nop 0
	global_load_lds_dwordx4 v[24:25], off
	s_mov_b32 m0, s29
	s_nop 0
	global_load_lds_dwordx4 v[26:27], off
	s_waitcnt vmcnt(6)
	s_barrier
	s_setprio 1
	v_mfma_f32_16x16x32_bf16 v[6:9], v[2:5], v[20:23], v[12:15]
	v_mfma_f32_16x16x32_bf16 v[10:13], v[240:243], v[20:23], v[156:159]
	v_mfma_f32_16x16x32_bf16 v[26:29], v[248:251], v[140:143], v[10:13]
	v_mfma_f32_16x16x32_bf16 v[10:13], v[2:5], v[164:167], v[160:163]
	v_mfma_f32_16x16x32_bf16 v[22:25], v[236:239], v[168:171], v[10:13]
	v_mfma_f32_16x16x32_bf16 v[10:13], v[240:243], v[164:167], v[132:135]
	v_mfma_f32_16x16x32_bf16 v[18:21], v[248:251], v[168:171], v[10:13]
	v_mfma_f32_16x16x32_bf16 v[10:13], v[2:5], v[222:225], v[136:139]
	v_mfma_f32_16x16x32_bf16 v[2:5], v[2:5], v[244:247], v[194:197]
	v_mfma_f32_16x16x32_bf16 v[14:17], v[236:239], v[232:235], v[10:13]
	v_mfma_f32_16x16x32_bf16 v[10:13], v[240:243], v[222:225], v[144:147]
	v_mfma_f32_16x16x32_bf16 v[222:225], v[236:239], v[32:35], v[2:5]
	v_mfma_f32_16x16x32_bf16 v[2:5], v[240:243], v[244:247], v[198:201]
	v_mfma_f32_16x16x32_bf16 v[6:9], v[236:239], v[140:143], v[6:9]
	v_mfma_f32_16x16x32_bf16 v[10:13], v[248:251], v[232:235], v[10:13]
	v_mfma_f32_16x16x32_bf16 v[2:5], v[248:251], v[32:35], v[2:5]
	s_setprio 0
	s_barrier
;   DI void operator()(const Acc8& acc, const pg8::Unit& u, int wr, int wc, int fr, int fq) const {
;     ...
;         const int c8 = bj * 128 + wc * 32 + 8 * fq;
;         const float4 a0a = *(const float4*)(a0 + c8), a0b = *(const float4*)(a0 + c8 + 4);
;         const float4 kaa = *(const float4*)(k_a + c8), kab = *(const float4*)(k_a + c8 + 4);
;         const float4 kwa = *(const float4*)(k_k + c8), kwb = *(const float4*)(k_k + c8 + 4);
; #pragma unroll
;         for (int ai = 0; ai < 2; ++ai) {
;           f32x4 kq0[4], kq1[4]; float invq[4];
; #pragma unroll
;           for (int m = 0; m < 4; ++m) {
;             const unsigned row = (unsigned)EPI_ROWS(ai, m);
;             kq0[m] = *(const f32x4*)((const char*)zk + (row * 256u + c8) * 4u); kq1[m] = *(const f32x4*)((const char*)zk + (row * 256u + c8) * 4u + 16);
;             invq[m] = invn[row * 4u + (c8 >> 6)];
;           }
; #pragma unroll
;           for (int m = 0; m < 4; ++m) {
;             const unsigned o2 = ((unsigned)EPI_ROWS(ai, m) * 256u + c8) * 2u;
;             const f32x4 k0 = kq0[m], k1 = kq1[m]; const float inv = invq[m];
;             const f32x4 x0 = acc[ai][bj][m][0], x1 = acc[ai][bj][m][1];
;             f32x4 kk0, kk1;
;             kk0[0] = k0[0] * kwa.x * inv; kk0[1] = k0[1] * kwa.y * inv; kk0[2] = k0[2] * kwa.z * inv; kk0[3] = k0[3] * kwa.w * inv;
;             kk1[0] = k1[0] * kwb.x * inv; kk1[1] = k1[1] * kwb.y * inv; kk1[2] = k1[2] * kwb.z * inv; kk1[3] = k1[3] * kwb.w * inv;
;             f32x4 av0, av1, kka0, kka1, kp0, kp1;
;             av0[0] = sigmoidf_(a0a.x + x0[0]); av0[1] = sigmoidf_(a0a.y + x0[1]); av0[2] = sigmoidf_(a0a.z + x0[2]); av0[3] = sigmoidf_(a0a.w + x0[3]);
;             av1[0] = sigmoidf_(a0b.x + x1[0]); av1[1] = sigmoidf_(a0b.y + x1[1]); av1[2] = sigmoidf_(a0b.z + x1[2]); av1[3] = sigmoidf_(a0b.w + x1[3]);
;             kka0 = kk0 * av0; kka1 = kk1 * av1;
;             kp0[0] = k0[0] * (1.f + (av0[0] - 1.f) * kaa.x); kp0[1] = k0[1] * (1.f + (av0[1] - 1.f) * kaa.y);
;             kp0[2] = k0[2] * (1.f + (av0[2] - 1.f) * kaa.z); kp0[3] = k0[3] * (1.f + (av0[3] - 1.f) * kaa.w);
;             kp1[0] = k1[0] * (1.f + (av1[0] - 1.f) * kab.x); kp1[1] = k1[1] * (1.f + (av1[1] - 1.f) * kab.y);
;             kp1[2] = k1[2] * (1.f + (av1[2] - 1.f) * kab.z); kp1[3] = k1[3] * (1.f + (av1[3] - 1.f) * kab.w);
	s_mov_b64 s[18:19], -1
	v_lshlrev_b32_e32 v0, 3, v131
	v_lshl_add_u32 v192, s13, 5, v0
	s_lshl_b32 s13, s14, 8
	s_lshl_b32 s14, s20, 6
	s_add_i32 s14, s14, s13
	v_add_u32_e32 v190, s14, v130
	v_ashrrev_i32_e32 v193, 31, v192
	s_mov_b64 s[14:15], 0
	s_cmp_lt_i32 s12, 1
	s_mov_b64 s[16:17], 0
	s_cbranch_scc1 .LBB0_488
	s_cmp_eq_u32 s12, 1
	s_mov_b64 s[16:17], -1
	s_cbranch_scc0 .LBB0_487
	s_add_u32 s18, s2, 0xfea0000
	s_addc_u32 s19, s3, 0
	s_add_u32 s16, s2, 0xeea0000
	s_addc_u32 s17, s3, 0
	s_add_u32 s20, s2, 0x7f0000
	s_addc_u32 s21, s3, 0
	s_add_u32 s22, s2, 0xbea0000
	s_addc_u32 s23, s3, 0
	s_add_u32 s13, s24, s8
	s_addc_u32 s27, s25, s9
	s_lshl_b64 s[24:25], s[64:65], 2
	s_add_u32 s30, s13, s24
	s_addc_u32 s31, s27, s25
	s_add_u32 s6, s6, s8
	v_lshlrev_b64 v[30:31], 2, v[192:193]
	s_addc_u32 s7, s7, s9
	v_lshl_add_u64 v[198:199], s[30:31], 0, v[30:31]
	s_add_u32 s6, s6, s24
	global_load_dwordx4 v[138:141], v[198:199], off
	global_load_dwordx4 v[134:137], v[198:199], off offset:16
	s_addc_u32 s7, s7, s25
	s_add_u32 s4, s4, s8
	v_lshlrev_b32_e32 v213, 2, v192
	v_lshlrev_b32_e32 v0, 10, v190
	s_addc_u32 s5, s5, s9
	v_ashrrev_i32_e32 v212, 6, v192
	v_add_u32_e32 v0, v0, v213
	s_add_u32 s4, s4, s24
	v_lshlrev_b32_e32 v203, 2, v190
	global_load_dwordx4 v[170:173], v0, s[22:23] offset:16
	global_load_dwordx4 v[178:181], v0, s[22:23]
	s_addc_u32 s5, s5, s25
	v_add_u32_e32 v0, v203, v212
	v_lshl_add_u64 v[196:197], s[4:5], 0, v[30:31]
	v_lshl_add_u64 v[32:33], v[0:1], 2, s[20:21]
	global_load_dwordx4 v[142:145], v[196:197], off offset:16
	global_load_dwordx4 v[146:149], v[196:197], off
	global_load_dword v204, v[32:33], off
	v_lshl_add_u64 v[194:195], s[6:7], 0, v[30:31]
	global_load_dwordx4 v[130:133], v[194:195], off offset:16
	global_load_dwordx4 v[150:153], v[194:195], off
	v_add_u32_e32 v0, 16, v190
	v_add_u32_e32 v32, 32, v190
	v_lshlrev_b32_e32 v249, 2, v0
	v_add_u32_e32 v33, 48, v190
	v_lshlrev_b32_e32 v250, 10, v0
	v_lshlrev_b32_e32 v247, 2, v32
	v_add_u32_e32 v0, v249, v212
	v_lshlrev_b32_e32 v248, 10, v32
	v_lshlrev_b32_e32 v245, 10, v33
	v_lshlrev_b32_e32 v244, 2, v33
	v_lshl_add_u64 v[32:33], v[0:1], 2, s[20:21]
	v_add_u32_e32 v0, v247, v212
	v_add_u32_e32 v34, v250, v213
	v_mov_b64_e32 v[234:235], v[186:187]
	v_lshl_add_u64 v[30:31], v[0:1], 2, s[20:21]
	v_add_u32_e32 v0, v244, v212
	v_add_u32_e32 v35, v248, v213
	v_add_u32_e32 v36, v245, v213
	v_mov_b64_e32 v[232:233], v[184:185]
	global_load_dwordx4 v[182:185], v34, s[22:23]
	global_load_dwordx4 v[174:177], v34, s[22:23] offset:16
	global_load_dword v202, v[32:33], off
	global_load_dwordx4 v[162:165], v35, s[22:23] offset:16
	global_load_dwordx4 v[166:169], v35, s[22:23]
	global_load_dword v200, v[30:31], off
	global_load_dwordx4 v[158:161], v36, s[22:23]
	v_lshl_add_u64 v[30:31], v[0:1], 2, s[20:21]
	global_load_dwordx4 v[154:157], v36, s[22:23] offset:16
	global_load_dword v0, v[30:31], off
	v_lshlrev_b32_e32 v243, 9, v190
	v_lshlrev_b32_e32 v240, 1, v192
	v_add_u32_e32 v201, v243, v240
	v_add_u32_e32 v242, 0x2000, v243
	v_add_u32_e32 v241, 0x4000, v243
	v_add_u32_e32 v239, 0x6000, v243
	v_add_u32_e32 v218, 0x10000, v243
	s_waitcnt vmcnt(0)
	v_add_f32_e32 v30, v126, v138
	v_add_f32_e32 v31, v127, v139
	v_mul_f32_e32 v30, 0xbfb8aa3b, v30
	v_mul_f32_e32 v31, 0xbfb8aa3b, v31
	v_exp_f32_e32 v30, v30
	v_exp_f32_e32 v31, v31
	v_add_f32_e32 v34, v122, v134
	v_add_f32_e32 v35, v123, v135
	v_add_f32_e32 v36, v124, v136
	v_pk_add_f32 v[30:31], v[30:31], 1.0 op_sel_hi:[1,0]
	v_mul_f32_e32 v34, 0xbfb8aa3b, v34
	v_mul_f32_e32 v35, 0xbfb8aa3b, v35
	v_mul_f32_e32 v36, 0xbfb8aa3b, v36
	v_exp_f32_e32 v210, v34
	v_exp_f32_e32 v211, v35
	v_pk_mul_f32 v[186:187], v[144:145], v[172:173]
	v_exp_f32_e32 v206, v36
	v_pk_mul_f32 v[208:209], v[204:205], v[186:187] op_sel_hi:[0,1]
	v_pk_mul_f32 v[34:35], v[148:149], v[180:181]
	v_pk_mul_f32 v[36:37], v[146:147], v[178:179]
	v_pk_mul_f32 v[214:215], v[142:143], v[170:171]
	v_pk_mul_f32 v[34:35], v[34:35], v[204:205] op_sel_hi:[1,0]
	v_pk_mul_f32 v[36:37], v[36:37], v[204:205] op_sel_hi:[1,0]
	v_pk_mul_f32 v[204:205], v[204:205], v[214:215] op_sel_hi:[0,1]
	v_add_f32_e32 v32, v128, v140
	v_add_f32_e32 v33, v129, v141
	v_mul_f32_e32 v32, 0xbfb8aa3b, v32
	v_mul_f32_e32 v33, 0xbfb8aa3b, v33
	v_exp_f32_e32 v32, v32
	v_exp_f32_e32 v33, v33
	v_rcp_f32_e32 v31, v31
	v_pk_add_f32 v[32:33], v[32:33], 1.0 op_sel_hi:[1,0]
	v_rcp_f32_e32 v30, v30
	s_nop 0
	v_pk_add_f32 v[186:187], v[30:31], -1.0 op_sel_hi:[1,0]
	v_pk_mul_f32 v[30:31], v[30:31], v[36:37]
	v_pk_fma_f32 v[186:187], v[186:187], v[150:151], 1.0 op_sel_hi:[1,1,0]
	v_pk_add_f32 v[36:37], v[210:211], 1.0 op_sel_hi:[1,0]
	v_pk_mul_f32 v[178:179], v[186:187], v[178:179]
	v_rcp_f32_e32 v33, v33
	v_add_f32_e32 v207, v125, v137
	v_rcp_f32_e32 v32, v32
	s_nop 0
	v_pk_mul_f32 v[34:35], v[32:33], v[34:35]
	v_pk_add_f32 v[32:33], v[32:33], -1.0 op_sel_hi:[1,0]
	v_mul_f32_e32 v207, 0xbfb8aa3b, v207
	v_pk_fma_f32 v[32:33], v[32:33], v[152:153], 1.0 op_sel_hi:[1,1,0]
	v_exp_f32_e32 v207, v207
	v_pk_mul_f32 v[180:181], v[32:33], v[180:181]
	v_rcp_f32_e32 v33, v37
	v_cvt_pk_bf16_f32 v30, v30, v31
	v_rcp_f32_e32 v32, v36
	v_pk_add_f32 v[36:37], v[206:207], 1.0 op_sel_hi:[1,0]
	v_pk_add_f32 v[186:187], v[32:33], -1.0 op_sel_hi:[1,0]
	v_pk_fma_f32 v[186:187], v[186:187], v[130:131], 1.0 op_sel_hi:[1,1,0]
	v_pk_mul_f32 v[32:33], v[32:33], v[204:205]
	v_pk_mul_f32 v[170:171], v[186:187], v[170:171]
	v_rcp_f32_e32 v37, v37
	v_cvt_pk_bf16_f32 v31, v34, v35
	v_rcp_f32_e32 v36, v36
	s_nop 0
	v_pk_mul_f32 v[186:187], v[36:37], v[208:209]
	v_cvt_pk_bf16_f32 v32, v32, v33
	v_cvt_pk_bf16_f32 v33, v186, v187
; DI uint4 pack8(f32x4 a, f32x4 b) { uint4 r; r.x = pack2(a[0], a[1]); r.y = pack2(a[2], a[3]); r.z = pack2(b[0], b[1]); r.w = pack2(b[2], b[3]); return r; }
; DI float sigmoidf_(float x) { return 1.f / (1.f + __expf(-x)); }
;   DI void operator()(const Acc8& acc, const pg8::Unit& u, int wr, int wc, int fr, int fq) const {
;     ...
;           for (int m = 0; m < 4; ++m) {
;             const unsigned o2 = ((unsigned)EPI_ROWS(ai, m) * 256u + c8) * 2u;
;             const f32x4 k0 = kq0[m], k1 = kq1[m]; const float inv = invq[m];
;             const f32x4 x0 = acc[ai][bj][m][0], x1 = acc[ai][bj][m][1];
;             f32x4 kk0, kk1;
;             kk0[0] = k0[0] * kwa.x * inv; kk0[1] = k0[1] * kwa.y * inv; kk0[2] = k0[2] * kwa.z * inv; kk0[3] = k0[3] * kwa.w * inv;
;             kk1[0] = k1[0] * kwb.x * inv; kk1[1] = k1[1] * kwb.y * inv; kk1[2] = k1[2] * kwb.z * inv; kk1[3] = k1[3] * kwb.w * inv;
;             f32x4 av0, av1, kka0, kka1, kp0, kp1;
;             av0[0] = sigmoidf_(a0a.x + x0[0]); av0[1] = sigmoidf_(a0a.y + x0[1]); av0[2] = sigmoidf_(a0a.z + x0[2]); av0[3] = sigmoidf_(a0a.w + x0[3]);
;             av1[0] = sigmoidf_(a0b.x + x1[0]); av1[1] = sigmoidf_(a0b.y + x1[1]); av1[2] = sigmoidf_(a0b.z + x1[2]); av1[3] = sigmoidf_(a0b.w + x1[3]);
;             kka0 = kk0 * av0; kka1 = kk1 * av1;
;             kp0[0] = k0[0] * (1.f + (av0[0] - 1.f) * kaa.x); kp0[1] = k0[1] * (1.f + (av0[1] - 1.f) * kaa.y);
;             kp0[2] = k0[2] * (1.f + (av0[2] - 1.f) * kaa.z); kp0[3] = k0[3] * (1.f + (av0[3] - 1.f) * kaa.w);
;             kp1[0] = k1[0] * (1.f + (av1[0] - 1.f) * kab.x); kp1[1] = k1[1] * (1.f + (av1[1] - 1.f) * kab.y);
;             kp1[2] = k1[2] * (1.f + (av1[2] - 1.f) * kab.z); kp1[3] = k1[3] * (1.f + (av1[3] - 1.f) * kab.w);
;             *(uint4*)((char*)sKKA + o2) = pack8(kka0, kka1); *(uint4*)((char*)sKP + o2) = pack8(kp0, kp1);
	v_pk_mul_f32 v[34:35], v[144:145], v[176:177]
	global_store_dwordx4 v201, v[30:33], s[18:19]
	v_pk_add_f32 v[36:37], v[36:37], -1.0 op_sel_hi:[1,0]
	s_nop 0
	v_cvt_pk_bf16_f32 v32, v170, v171
	v_pk_mul_f32 v[170:171], v[202:203], v[34:35] op_sel_hi:[0,1]
	v_add_f32_e32 v34, v118, v138
	v_add_f32_e32 v35, v119, v139
	v_mul_f32_e32 v34, 0xbfb8aa3b, v34
	v_mul_f32_e32 v35, 0xbfb8aa3b, v35
	v_exp_f32_e32 v34, v34
	v_exp_f32_e32 v35, v35
	v_pk_fma_f32 v[36:37], v[36:37], v[132:133], 1.0 op_sel_hi:[1,1,0]
	v_cvt_pk_bf16_f32 v30, v178, v179
	v_pk_mul_f32 v[36:37], v[36:37], v[172:173]
	v_pk_add_f32 v[34:35], v[34:35], 1.0 op_sel_hi:[1,0]
	v_cvt_pk_bf16_f32 v31, v180, v181
	v_cvt_pk_bf16_f32 v33, v36, v37
	global_store_dwordx4 v201, v[30:33], s[16:17]
	v_pk_mul_f32 v[36:37], v[142:143], v[174:175]
	v_add_f32_e32 v178, v114, v134
	v_pk_mul_f32 v[30:31], v[148:149], v[184:185]
	v_pk_mul_f32 v[32:33], v[146:147], v[182:183]
	v_pk_mul_f32 v[30:31], v[30:31], v[202:203] op_sel_hi:[1,0]
	v_pk_mul_f32 v[32:33], v[32:33], v[202:203] op_sel_hi:[1,0]
	v_pk_mul_f32 v[172:173], v[202:203], v[36:37] op_sel_hi:[0,1]
	v_add_f32_e32 v36, v120, v140
	v_add_f32_e32 v37, v121, v141
	v_mul_f32_e32 v36, 0xbfb8aa3b, v36
	v_mul_f32_e32 v37, 0xbfb8aa3b, v37
	v_exp_f32_e32 v36, v36
	v_exp_f32_e32 v37, v37
	v_rcp_f32_e32 v35, v35
	v_pk_add_f32 v[36:37], v[36:37], 1.0 op_sel_hi:[1,0]
	v_rcp_f32_e32 v34, v34
	s_nop 0
	v_pk_add_f32 v[186:187], v[34:35], -1.0 op_sel_hi:[1,0]
	v_add_f32_e32 v179, v115, v135
	v_pk_fma_f32 v[186:187], v[186:187], v[150:151], 1.0 op_sel_hi:[1,1,0]
	v_mul_f32_e32 v178, 0xbfb8aa3b, v178
	v_pk_mul_f32 v[182:183], v[186:187], v[182:183]
	v_rcp_f32_e32 v37, v37
	v_mul_f32_e32 v179, 0xbfb8aa3b, v179
	v_exp_f32_e32 v178, v178
	v_exp_f32_e32 v179, v179
	v_rcp_f32_e32 v36, v36
	s_nop 0
	v_pk_mul_f32 v[186:187], v[36:37], v[30:31]
	v_pk_mul_f32 v[30:31], v[34:35], v[32:33]
	v_pk_add_f32 v[32:33], v[178:179], 1.0 op_sel_hi:[1,0]
	v_pk_add_f32 v[34:35], v[36:37], -1.0 op_sel_hi:[1,0]
	v_pk_fma_f32 v[34:35], v[34:35], v[152:153], 1.0 op_sel_hi:[1,1,0]
	v_add_f32_e32 v180, v116, v136
	v_pk_mul_f32 v[34:35], v[34:35], v[184:185]
	v_rcp_f32_e32 v33, v33
	v_add_f32_e32 v181, v117, v137
	v_mul_f32_e32 v180, 0xbfb8aa3b, v180
	v_mul_f32_e32 v181, 0xbfb8aa3b, v181
	v_exp_f32_e32 v180, v180
	v_exp_f32_e32 v181, v181
	v_rcp_f32_e32 v32, v32
	v_pk_add_f32 v[36:37], v[180:181], 1.0 op_sel_hi:[1,0]
	v_pk_add_f32 v[178:179], v[32:33], -1.0 op_sel_hi:[1,0]
	v_pk_fma_f32 v[178:179], v[178:179], v[130:131], 1.0 op_sel_hi:[1,1,0]
	v_pk_mul_f32 v[32:33], v[32:33], v[172:173]
	v_pk_mul_f32 v[174:175], v[178:179], v[174:175]
	v_rcp_f32_e32 v37, v37
	v_add_u32_e32 v201, v242, v240
	v_rcp_f32_e32 v36, v36
	s_nop 0
	v_pk_mul_f32 v[170:171], v[36:37], v[170:171]
	v_cvt_pk_bf16_f32 v30, v30, v31
	v_cvt_pk_bf16_f32 v31, v186, v187
	v_cvt_pk_bf16_f32 v32, v32, v33
	v_cvt_pk_bf16_f32 v33, v170, v171
	global_store_dwordx4 v201, v[30:33], s[18:19]
	v_pk_add_f32 v[36:37], v[36:37], -1.0 op_sel_hi:[1,0]
	v_add_u32_e32 v180, v241, v240
	v_cvt_pk_bf16_f32 v31, v34, v35
	v_pk_mul_f32 v[34:35], v[144:145], v[164:165]
	v_cvt_pk_bf16_f32 v30, v182, v183
	v_pk_mul_f32 v[170:171], v[200:201], v[34:35] op_sel_hi:[0,1]
	v_add_f32_e32 v34, v110, v138
	v_add_f32_e32 v35, v111, v139
	v_mul_f32_e32 v34, 0xbfb8aa3b, v34
	v_mul_f32_e32 v35, 0xbfb8aa3b, v35
	v_exp_f32_e32 v34, v34
	v_exp_f32_e32 v35, v35
	v_pk_fma_f32 v[36:37], v[36:37], v[132:133], 1.0 op_sel_hi:[1,1,0]
	v_cvt_pk_bf16_f32 v32, v174, v175
	v_pk_mul_f32 v[36:37], v[36:37], v[176:177]
	v_pk_add_f32 v[34:35], v[34:35], 1.0 op_sel_hi:[1,0]
	v_cvt_pk_bf16_f32 v33, v36, v37
	v_pk_mul_f32 v[36:37], v[142:143], v[162:163]
	global_store_dwordx4 v201, v[30:33], s[16:17]
	v_pk_mul_f32 v[172:173], v[200:201], v[36:37] op_sel_hi:[0,1]
	v_add_f32_e32 v36, v112, v140
	v_add_f32_e32 v37, v113, v141
	v_mul_f32_e32 v36, 0xbfb8aa3b, v36
	v_mul_f32_e32 v37, 0xbfb8aa3b, v37
	v_exp_f32_e32 v36, v36
	v_exp_f32_e32 v37, v37
	v_rcp_f32_e32 v35, v35
	v_pk_add_f32 v[36:37], v[36:37], 1.0 op_sel_hi:[1,0]
	v_rcp_f32_e32 v34, v34
	s_nop 0
	v_pk_add_f32 v[178:179], v[34:35], -1.0 op_sel_hi:[1,0]
	v_pk_mul_f32 v[32:33], v[146:147], v[166:167]
	v_pk_fma_f32 v[178:179], v[178:179], v[150:151], 1.0 op_sel_hi:[1,1,0]
	v_add_f32_e32 v174, v106, v134
	v_pk_mul_f32 v[166:167], v[178:179], v[166:167]
	v_rcp_f32_e32 v37, v37
	v_add_f32_e32 v175, v107, v135
	v_mul_f32_e32 v174, 0xbfb8aa3b, v174
	v_mul_f32_e32 v175, 0xbfb8aa3b, v175
	v_exp_f32_e32 v174, v174
	v_exp_f32_e32 v175, v175
	v_pk_mul_f32 v[30:31], v[148:149], v[168:169]
	v_pk_mul_f32 v[30:31], v[30:31], v[200:201] op_sel_hi:[1,0]
	v_pk_mul_f32 v[32:33], v[32:33], v[200:201] op_sel_hi:[1,0]
	v_rcp_f32_e32 v36, v36
	s_nop 0
	v_pk_mul_f32 v[178:179], v[36:37], v[30:31]
	v_pk_mul_f32 v[30:31], v[34:35], v[32:33]
	v_pk_add_f32 v[32:33], v[174:175], 1.0 op_sel_hi:[1,0]
	v_pk_add_f32 v[34:35], v[36:37], -1.0 op_sel_hi:[1,0]
	v_pk_fma_f32 v[34:35], v[34:35], v[152:153], 1.0 op_sel_hi:[1,1,0]
	v_add_f32_e32 v176, v108, v136
	v_pk_mul_f32 v[34:35], v[34:35], v[168:169]
	v_rcp_f32_e32 v33, v33
	v_add_f32_e32 v177, v109, v137
	v_mul_f32_e32 v176, 0xbfb8aa3b, v176
	v_mul_f32_e32 v177, 0xbfb8aa3b, v177
	v_exp_f32_e32 v176, v176
	v_exp_f32_e32 v177, v177
	v_rcp_f32_e32 v32, v32
	v_pk_add_f32 v[36:37], v[176:177], 1.0 op_sel_hi:[1,0]
	v_pk_add_f32 v[168:169], v[32:33], -1.0 op_sel_hi:[1,0]
	v_pk_fma_f32 v[168:169], v[168:169], v[130:131], 1.0 op_sel_hi:[1,1,0]
	v_pk_mul_f32 v[32:33], v[32:33], v[172:173]
	v_pk_mul_f32 v[162:163], v[168:169], v[162:163]
	v_rcp_f32_e32 v37, v37
	v_cvt_pk_bf16_f32 v30, v30, v31
	v_rcp_f32_e32 v36, v36
; DI uint4 pack8(f32x4 a, f32x4 b) { uint4 r; r.x = pack2(a[0], a[1]); r.y = pack2(a[2], a[3]); r.z = pack2(b[0], b[1]); r.w = pack2(b[2], b[3]); return r; }
; DI float sigmoidf_(float x) { return 1.f / (1.f + __expf(-x)); }
;   DI void operator()(const Acc8& acc, const pg8::Unit& u, int wr, int wc, int fr, int fq) const {
;     ...
;         for (int ai = 0; ai < 2; ++ai) {
;           f32x4 kq0[4], kq1[4]; float invq[4];
; #pragma unroll
;           for (int m = 0; m < 4; ++m) {
;             const unsigned row = (unsigned)EPI_ROWS(ai, m);
;             kq0[m] = *(const f32x4*)((const char*)zk + (row * 256u + c8) * 4u); kq1[m] = *(const f32x4*)((const char*)zk + (row * 256u + c8) * 4u + 16);
;             invq[m] = invn[row * 4u + (c8 >> 6)];
;           }
;     ...
;           for (int m = 0; m < 4; ++m) {
;             const unsigned o2 = ((unsigned)EPI_ROWS(ai, m) * 256u + c8) * 2u;
;             const f32x4 k0 = kq0[m], k1 = kq1[m]; const float inv = invq[m];
;             const f32x4 x0 = acc[ai][bj][m][0], x1 = acc[ai][bj][m][1];
;             f32x4 kk0, kk1;
;             kk0[0] = k0[0] * kwa.x * inv; kk0[1] = k0[1] * kwa.y * inv; kk0[2] = k0[2] * kwa.z * inv; kk0[3] = k0[3] * kwa.w * inv;
;             kk1[0] = k1[0] * kwb.x * inv; kk1[1] = k1[1] * kwb.y * inv; kk1[2] = k1[2] * kwb.z * inv; kk1[3] = k1[3] * kwb.w * inv;
;             f32x4 av0, av1, kka0, kka1, kp0, kp1;
;             av0[0] = sigmoidf_(a0a.x + x0[0]); av0[1] = sigmoidf_(a0a.y + x0[1]); av0[2] = sigmoidf_(a0a.z + x0[2]); av0[3] = sigmoidf_(a0a.w + x0[3]);
;             av1[0] = sigmoidf_(a0b.x + x1[0]); av1[1] = sigmoidf_(a0b.y + x1[1]); av1[2] = sigmoidf_(a0b.z + x1[2]); av1[3] = sigmoidf_(a0b.w + x1[3]);
;             kka0 = kk0 * av0; kka1 = kk1 * av1;
;             kp0[0] = k0[0] * (1.f + (av0[0] - 1.f) * kaa.x); kp0[1] = k0[1] * (1.f + (av0[1] - 1.f) * kaa.y);
;             kp0[2] = k0[2] * (1.f + (av0[2] - 1.f) * kaa.z); kp0[3] = k0[3] * (1.f + (av0[3] - 1.f) * kaa.w);
;             kp1[0] = k1[0] * (1.f + (av1[0] - 1.f) * kab.x); kp1[1] = k1[1] * (1.f + (av1[1] - 1.f) * kab.y);
;             kp1[2] = k1[2] * (1.f + (av1[2] - 1.f) * kab.z); kp1[3] = k1[3] * (1.f + (av1[3] - 1.f) * kab.w);
;             *(uint4*)((char*)sKKA + o2) = pack8(kka0, kka1); *(uint4*)((char*)sKP + o2) = pack8(kp0, kp1);
	s_nop 0
	v_pk_mul_f32 v[168:169], v[36:37], v[170:171]
	v_pk_add_f32 v[36:37], v[36:37], -1.0 op_sel_hi:[1,0]
	v_cvt_pk_bf16_f32 v31, v178, v179
	v_pk_fma_f32 v[36:37], v[36:37], v[132:133], 1.0 op_sel_hi:[1,1,0]
	v_cvt_pk_bf16_f32 v32, v32, v33
	v_pk_mul_f32 v[36:37], v[36:37], v[164:165]
	v_cvt_pk_bf16_f32 v33, v168, v169
	global_store_dwordx4 v180, v[30:33], s[18:19]
	v_add_f32_e32 v169, v101, v137
	v_mul_f32_e32 v169, 0xbfb8aa3b, v169
	v_cvt_pk_bf16_f32 v30, v166, v167
	v_cvt_pk_bf16_f32 v31, v34, v35
	v_cvt_pk_bf16_f32 v32, v162, v163
	v_cvt_pk_bf16_f32 v33, v36, v37
	global_store_dwordx4 v180, v[30:33], s[16:17]
	v_pk_mul_f32 v[34:35], v[144:145], v[156:157]
	v_pk_mul_f32 v[36:37], v[142:143], v[154:155]
	v_pk_mul_f32 v[30:31], v[148:149], v[160:161]
	v_pk_mul_f32 v[32:33], v[146:147], v[158:159]
	v_pk_mul_f32 v[30:31], v[30:31], v[0:1] op_sel_hi:[1,0]
	v_pk_mul_f32 v[32:33], v[32:33], v[0:1] op_sel_hi:[1,0]
	v_pk_mul_f32 v[162:163], v[0:1], v[34:35] op_sel_hi:[0,1]
	v_pk_mul_f32 v[164:165], v[0:1], v[36:37] op_sel_hi:[0,1]
	v_add_f32_e32 v0, v102, v138
	v_mul_f32_e32 v0, 0xbfb8aa3b, v0
	v_exp_f32_e32 v34, v0
	v_add_f32_e32 v0, v103, v139
	v_mul_f32_e32 v0, 0xbfb8aa3b, v0
	v_exp_f32_e32 v35, v0
	v_add_f32_e32 v0, v104, v140
	v_mul_f32_e32 v0, 0xbfb8aa3b, v0
	v_exp_f32_e32 v36, v0
	v_add_f32_e32 v0, v105, v141
	v_mul_f32_e32 v0, 0xbfb8aa3b, v0
	v_exp_f32_e32 v37, v0
	v_add_f32_e32 v0, v98, v134
	v_mul_f32_e32 v0, 0xbfb8aa3b, v0
	v_exp_f32_e32 v166, v0
	v_add_f32_e32 v0, v99, v135
	v_mul_f32_e32 v0, 0xbfb8aa3b, v0
	v_exp_f32_e32 v167, v0
	v_add_f32_e32 v0, v100, v136
	v_mul_f32_e32 v0, 0xbfb8aa3b, v0
	v_pk_add_f32 v[34:35], v[34:35], 1.0 op_sel_hi:[1,0]
	v_exp_f32_e32 v168, v0
	v_pk_add_f32 v[36:37], v[36:37], 1.0 op_sel_hi:[1,0]
	v_exp_f32_e32 v169, v169
	v_add_u32_e32 v172, v239, v240
	v_rcp_f32_e32 v35, v35
	v_rcp_f32_e32 v34, v34
	s_nop 0
	v_pk_add_f32 v[170:171], v[34:35], -1.0 op_sel_hi:[1,0]
	s_nop 0
	v_pk_fma_f32 v[170:171], v[170:171], v[150:151], 1.0 op_sel_hi:[1,1,0]
	s_nop 0
	v_pk_mul_f32 v[158:159], v[170:171], v[158:159]
	v_rcp_f32_e32 v37, v37
	v_rcp_f32_e32 v36, v36
	s_nop 0
	v_pk_mul_f32 v[170:171], v[36:37], v[30:31]
	v_pk_mul_f32 v[30:31], v[34:35], v[32:33]
	v_pk_add_f32 v[32:33], v[166:167], 1.0 op_sel_hi:[1,0]
	v_pk_add_f32 v[34:35], v[36:37], -1.0 op_sel_hi:[1,0]
	v_pk_fma_f32 v[34:35], v[34:35], v[152:153], 1.0 op_sel_hi:[1,1,0]
	v_cvt_pk_bf16_f32 v30, v30, v31
	v_pk_mul_f32 v[34:35], v[34:35], v[160:161]
	v_rcp_f32_e32 v33, v33
	v_cvt_pk_bf16_f32 v31, v170, v171
	v_pk_add_f32 v[36:37], v[168:169], 1.0 op_sel_hi:[1,0]
	v_rcp_f32_e32 v32, v32
	s_nop 0
	v_pk_add_f32 v[160:161], v[32:33], -1.0 op_sel_hi:[1,0]
	v_pk_mul_f32 v[32:33], v[32:33], v[164:165]
	v_pk_fma_f32 v[160:161], v[160:161], v[130:131], 1.0 op_sel_hi:[1,1,0]
	v_cvt_pk_bf16_f32 v32, v32, v33
	v_pk_mul_f32 v[154:155], v[160:161], v[154:155]
	v_rcp_f32_e32 v37, v37
	v_rcp_f32_e32 v36, v36
	s_nop 0
	v_pk_mul_f32 v[160:161], v[36:37], v[162:163]
	v_pk_add_f32 v[36:37], v[36:37], -1.0 op_sel_hi:[1,0]
	v_cvt_pk_bf16_f32 v33, v160, v161
	v_pk_fma_f32 v[36:37], v[36:37], v[132:133], 1.0 op_sel_hi:[1,1,0]
	global_store_dwordx4 v172, v[30:33], s[18:19]
	v_pk_mul_f32 v[36:37], v[36:37], v[156:157]
	s_nop 0
	v_cvt_pk_bf16_f32 v30, v158, v159
	v_cvt_pk_bf16_f32 v31, v34, v35
	v_cvt_pk_bf16_f32 v32, v154, v155
	v_cvt_pk_bf16_f32 v33, v36, v37
	global_store_dwordx4 v172, v[30:33], s[16:17]
	v_add_u32_e32 v0, 0x80, v190
	v_lshlrev_b32_e32 v191, 10, v0
	v_lshlrev_b32_e32 v246, 2, v0
	v_add_u32_e32 v30, v191, v213
	v_add_u32_e32 v0, v246, v212
	global_load_dwordx4 v[178:181], v30, s[22:23] offset:16
	global_load_dwordx4 v[182:185], v30, s[22:23]
	v_lshl_add_u64 v[30:31], v[0:1], 2, s[20:21]
	global_load_dword v30, v[30:31], off
	v_add_u32_e32 v0, 0x90, v190
	v_lshlrev_b32_e32 v227, 2, v0
	v_lshlrev_b32_e32 v219, 10, v0
	v_add_u32_e32 v0, v227, v212
	v_lshl_add_u64 v[32:33], v[0:1], 2, s[20:21]
	v_add_u32_e32 v0, 0xa0, v190
	v_lshlrev_b32_e32 v236, 2, v0
	v_add_u32_e32 v31, v219, v213
	v_lshlrev_b32_e32 v201, 10, v0
	v_add_u32_e32 v0, v236, v212
	global_load_dwordx4 v[170:173], v31, s[22:23] offset:16
	global_load_dwordx4 v[174:177], v31, s[22:23]
	global_load_dword v202, v[32:33], off
	v_lshl_add_u64 v[32:33], v[0:1], 2, s[20:21]
	v_add_u32_e32 v0, 0xb0, v190
	v_lshlrev_b32_e32 v238, 2, v0
	v_add_u32_e32 v31, v201, v213
	v_lshlrev_b32_e32 v237, 10, v0
	v_add_u32_e32 v0, v238, v212
	global_load_dwordx4 v[162:165], v31, s[22:23] offset:16
	global_load_dwordx4 v[166:169], v31, s[22:23]
	global_load_dword v200, v[32:33], off
	v_add_u32_e32 v31, v237, v213
	v_lshl_add_u64 v[32:33], v[0:1], 2, s[20:21]
	global_load_dwordx4 v[154:157], v31, s[22:23] offset:16
	global_load_dwordx4 v[158:161], v31, s[22:23]
	global_load_dword v0, v[32:33], off
	v_add_u32_e32 v231, v218, v240
	s_waitcnt vmcnt(0)
; DI uint4 pack8(f32x4 a, f32x4 b) { uint4 r; r.x = pack2(a[0], a[1]); r.y = pack2(a[2], a[3]); r.z = pack2(b[0], b[1]); r.w = pack2(b[2], b[3]); return r; }
; DI float sigmoidf_(float x) { return 1.f / (1.f + __expf(-x)); }
;   DI void operator()(const Acc8& acc, const pg8::Unit& u, int wr, int wc, int fr, int fq) const {
;     ...
;           for (int m = 0; m < 4; ++m) {
;             const unsigned o2 = ((unsigned)EPI_ROWS(ai, m) * 256u + c8) * 2u;
;             const f32x4 k0 = kq0[m], k1 = kq1[m]; const float inv = invq[m];
;             const f32x4 x0 = acc[ai][bj][m][0], x1 = acc[ai][bj][m][1];
;             f32x4 kk0, kk1;
;             kk0[0] = k0[0] * kwa.x * inv; kk0[1] = k0[1] * kwa.y * inv; kk0[2] = k0[2] * kwa.z * inv; kk0[3] = k0[3] * kwa.w * inv;
;             kk1[0] = k1[0] * kwb.x * inv; kk1[1] = k1[1] * kwb.y * inv; kk1[2] = k1[2] * kwb.z * inv; kk1[3] = k1[3] * kwb.w * inv;
;             f32x4 av0, av1, kka0, kka1, kp0, kp1;
;             av0[0] = sigmoidf_(a0a.x + x0[0]); av0[1] = sigmoidf_(a0a.y + x0[1]); av0[2] = sigmoidf_(a0a.z + x0[2]); av0[3] = sigmoidf_(a0a.w + x0[3]);
;             av1[0] = sigmoidf_(a0b.x + x1[0]); av1[1] = sigmoidf_(a0b.y + x1[1]); av1[2] = sigmoidf_(a0b.z + x1[2]); av1[3] = sigmoidf_(a0b.w + x1[3]);
;             kka0 = kk0 * av0; kka1 = kk1 * av1;
;             kp0[0] = k0[0] * (1.f + (av0[0] - 1.f) * kaa.x); kp0[1] = k0[1] * (1.f + (av0[1] - 1.f) * kaa.y);
;             kp0[2] = k0[2] * (1.f + (av0[2] - 1.f) * kaa.z); kp0[3] = k0[3] * (1.f + (av0[3] - 1.f) * kaa.w);
;             kp1[0] = k1[0] * (1.f + (av1[0] - 1.f) * kab.x); kp1[1] = k1[1] * (1.f + (av1[1] - 1.f) * kab.y);
;             kp1[2] = k1[2] * (1.f + (av1[2] - 1.f) * kab.z); kp1[3] = k1[3] * (1.f + (av1[3] - 1.f) * kab.w);
;             *(uint4*)((char*)sKKA + o2) = pack8(kka0, kka1); *(uint4*)((char*)sKP + o2) = pack8(kp0, kp1);
	v_pk_mul_f32 v[32:33], v[148:149], v[184:185]
	v_pk_mul_f32 v[34:35], v[146:147], v[182:183]
	v_pk_mul_f32 v[208:209], v[32:33], v[30:31] op_sel_hi:[1,0]
	v_pk_mul_f32 v[32:33], v[144:145], v[180:181]
	v_pk_mul_f32 v[210:211], v[34:35], v[30:31] op_sel_hi:[1,0]
	v_pk_mul_f32 v[204:205], v[30:31], v[32:33] op_sel_hi:[0,1]
	v_add_f32_e32 v32, v96, v140
	v_mul_f32_e32 v32, 0xbfb8aa3b, v32
	v_exp_f32_e32 v216, v32
	v_add_f32_e32 v32, v97, v141
	v_mul_f32_e32 v32, 0xbfb8aa3b, v32
	v_pk_mul_f32 v[34:35], v[142:143], v[178:179]
	v_exp_f32_e32 v217, v32
	v_add_f32_e32 v32, v90, v134
	v_pk_mul_f32 v[206:207], v[30:31], v[34:35] op_sel_hi:[0,1]
	v_add_f32_e32 v30, v94, v138
	v_add_f32_e32 v31, v95, v139
	v_mul_f32_e32 v32, 0xbfb8aa3b, v32
	v_mul_f32_e32 v30, 0xbfb8aa3b, v30
	v_mul_f32_e32 v31, 0xbfb8aa3b, v31
	v_exp_f32_e32 v214, v32
	v_add_f32_e32 v32, v91, v135
	v_exp_f32_e32 v30, v30
	v_exp_f32_e32 v31, v31
	v_mul_f32_e32 v32, 0xbfb8aa3b, v32
	v_exp_f32_e32 v215, v32
	v_add_f32_e32 v32, v92, v136
	v_mul_f32_e32 v32, 0xbfb8aa3b, v32
	v_exp_f32_e32 v212, v32
	v_add_f32_e32 v32, v93, v137
	v_mul_f32_e32 v32, 0xbfb8aa3b, v32
	v_pk_add_f32 v[30:31], v[30:31], 1.0 op_sel_hi:[1,0]
	v_exp_f32_e32 v213, v32
	s_nop 0
	v_rcp_f32_e32 v31, v31
	s_nop 0
	v_rcp_f32_e32 v30, v30
	s_nop 0
	v_pk_add_f32 v[32:33], v[30:31], -1.0 op_sel_hi:[1,0]
	v_pk_mul_f32 v[30:31], v[30:31], v[210:211]
	v_pk_fma_f32 v[32:33], v[32:33], v[150:151], 1.0 op_sel_hi:[1,1,0]
	v_cvt_pk_bf16_f32 v30, v30, v31
	v_pk_mul_f32 v[182:183], v[32:33], v[182:183]
	v_pk_add_f32 v[32:33], v[216:217], 1.0 op_sel_hi:[1,0]
	v_add_u32_e32 v217, 0x14000, v243
	v_add_u32_e32 v216, 0x16000, v243
	v_rcp_f32_e32 v33, v33
	s_nop 0
	v_rcp_f32_e32 v32, v32
	s_nop 0
	v_pk_mul_f32 v[34:35], v[32:33], v[208:209]
	v_pk_add_f32 v[32:33], v[32:33], -1.0 op_sel_hi:[1,0]
	v_cvt_pk_bf16_f32 v31, v34, v35
	v_pk_fma_f32 v[32:33], v[32:33], v[152:153], 1.0 op_sel_hi:[1,1,0]
	v_pk_mul_f32 v[34:35], v[144:145], v[172:173]
	v_pk_mul_f32 v[36:37], v[32:33], v[184:185]
	v_pk_add_f32 v[32:33], v[214:215], 1.0 op_sel_hi:[1,0]
	s_nop 0
	s_nop 0
	v_rcp_f32_e32 v33, v33
	s_nop 0
	v_rcp_f32_e32 v32, v32
	s_nop 0
	v_pk_add_f32 v[184:185], v[32:33], -1.0 op_sel_hi:[1,0]
	v_pk_mul_f32 v[32:33], v[32:33], v[206:207]
	v_pk_fma_f32 v[184:185], v[184:185], v[130:131], 1.0 op_sel_hi:[1,1,0]
	v_cvt_pk_bf16_f32 v32, v32, v33
	v_pk_mul_f32 v[178:179], v[184:185], v[178:179]
	v_pk_add_f32 v[184:185], v[212:213], 1.0 op_sel_hi:[1,0]
	s_nop 0
	s_nop 0
	v_rcp_f32_e32 v185, v185
	s_nop 0
	v_rcp_f32_e32 v184, v184
	s_nop 0
	v_pk_mul_f32 v[186:187], v[184:185], v[204:205]
	v_pk_add_f32 v[184:185], v[184:185], -1.0 op_sel_hi:[1,0]
	v_cvt_pk_bf16_f32 v33, v186, v187
	global_store_dwordx4 v231, v[30:33], s[18:19]
	v_pk_fma_f32 v[184:185], v[184:185], v[132:133], 1.0 op_sel_hi:[1,1,0]
	s_nop 0
	v_cvt_pk_bf16_f32 v32, v178, v179
	v_pk_mul_f32 v[178:179], v[202:203], v[34:35] op_sel_hi:[0,1]
	v_add_f32_e32 v34, v86, v138
	v_add_f32_e32 v35, v87, v139
	v_mul_f32_e32 v34, 0xbfb8aa3b, v34
	v_mul_f32_e32 v35, 0xbfb8aa3b, v35
	v_exp_f32_e32 v34, v34
	v_exp_f32_e32 v35, v35
	v_pk_mul_f32 v[180:181], v[184:185], v[180:181]
	v_cvt_pk_bf16_f32 v30, v182, v183
	v_cvt_pk_bf16_f32 v31, v36, v37
	v_pk_add_f32 v[34:35], v[34:35], 1.0 op_sel_hi:[1,0]
	v_cvt_pk_bf16_f32 v33, v180, v181
	global_store_dwordx4 v231, v[30:33], s[16:17]
	v_pk_mul_f32 v[36:37], v[142:143], v[170:171]
	v_add_f32_e32 v182, v82, v134
	v_pk_mul_f32 v[30:31], v[148:149], v[176:177]
	v_pk_mul_f32 v[32:33], v[146:147], v[174:175]
	v_pk_mul_f32 v[30:31], v[30:31], v[202:203] op_sel_hi:[1,0]
	v_pk_mul_f32 v[32:33], v[32:33], v[202:203] op_sel_hi:[1,0]
	v_pk_mul_f32 v[180:181], v[202:203], v[36:37] op_sel_hi:[0,1]
	v_rcp_f32_e32 v35, v35
	v_add_f32_e32 v36, v88, v140
	v_add_f32_e32 v37, v89, v141
	v_mul_f32_e32 v36, 0xbfb8aa3b, v36
	v_mul_f32_e32 v37, 0xbfb8aa3b, v37
	v_exp_f32_e32 v36, v36
	v_exp_f32_e32 v37, v37
	v_rcp_f32_e32 v34, v34
	s_nop 0
	v_pk_add_f32 v[186:187], v[34:35], -1.0 op_sel_hi:[1,0]
	v_pk_add_f32 v[36:37], v[36:37], 1.0 op_sel_hi:[1,0]
	v_pk_fma_f32 v[186:187], v[186:187], v[150:151], 1.0 op_sel_hi:[1,1,0]
	v_mul_f32_e32 v182, 0xbfb8aa3b, v182
	v_pk_mul_f32 v[174:175], v[186:187], v[174:175]
	v_exp_f32_e32 v184, v182
	v_add_f32_e32 v182, v83, v135
	v_mul_f32_e32 v182, 0xbfb8aa3b, v182
	v_rcp_f32_e32 v37, v37
	v_exp_f32_e32 v185, v182
	v_add_f32_e32 v182, v84, v136
	v_add_f32_e32 v183, v85, v137
	v_rcp_f32_e32 v36, v36
	s_nop 0
	v_pk_mul_f32 v[186:187], v[36:37], v[30:31]
	v_pk_mul_f32 v[30:31], v[34:35], v[32:33]
	v_pk_add_f32 v[32:33], v[36:37], -1.0 op_sel_hi:[1,0]
	v_mul_f32_e32 v182, 0xbfb8aa3b, v182
	v_pk_fma_f32 v[32:33], v[32:33], v[152:153], 1.0 op_sel_hi:[1,1,0]
	v_mul_f32_e32 v183, 0xbfb8aa3b, v183
	v_pk_mul_f32 v[34:35], v[32:33], v[176:177]
	v_pk_add_f32 v[32:33], v[184:185], 1.0 op_sel_hi:[1,0]
	v_exp_f32_e32 v182, v182
	v_exp_f32_e32 v183, v183
	v_add_u32_e32 v231, 0x12000, v243
	v_add_u32_e32 v204, v231, v240
	v_rcp_f32_e32 v33, v33
	v_cvt_pk_bf16_f32 v30, v30, v31
	v_cvt_pk_bf16_f32 v31, v186, v187
	v_rcp_f32_e32 v32, v32
	s_nop 0
	v_pk_add_f32 v[36:37], v[32:33], -1.0 op_sel_hi:[1,0]
	v_pk_mul_f32 v[32:33], v[32:33], v[180:181]
	v_pk_fma_f32 v[36:37], v[36:37], v[130:131], 1.0 op_sel_hi:[1,1,0]
	v_cvt_pk_bf16_f32 v32, v32, v33
	v_pk_mul_f32 v[36:37], v[36:37], v[170:171]
	v_pk_add_f32 v[170:171], v[182:183], 1.0 op_sel_hi:[1,0]
	v_add_u32_e32 v180, v217, v240
	s_nop 0
	v_rcp_f32_e32 v171, v171
	s_nop 0
	v_rcp_f32_e32 v170, v170
	s_nop 0
	v_pk_mul_f32 v[176:177], v[170:171], v[178:179]
	v_pk_add_f32 v[170:171], v[170:171], -1.0 op_sel_hi:[1,0]
; DI uint4 pack8(f32x4 a, f32x4 b) { uint4 r; r.x = pack2(a[0], a[1]); r.y = pack2(a[2], a[3]); r.z = pack2(b[0], b[1]); r.w = pack2(b[2], b[3]); return r; }
; DI float sigmoidf_(float x) { return 1.f / (1.f + __expf(-x)); }
;   DI void operator()(const Acc8& acc, const pg8::Unit& u, int wr, int wc, int fr, int fq) const {
;     ...
; #pragma unroll
;           for (int m = 0; m < 4; ++m) {
;             const unsigned o2 = ((unsigned)EPI_ROWS(ai, m) * 256u + c8) * 2u;
;             const f32x4 k0 = kq0[m], k1 = kq1[m]; const float inv = invq[m];
;             const f32x4 x0 = acc[ai][bj][m][0], x1 = acc[ai][bj][m][1];
;             f32x4 kk0, kk1;
;             kk0[0] = k0[0] * kwa.x * inv; kk0[1] = k0[1] * kwa.y * inv; kk0[2] = k0[2] * kwa.z * inv; kk0[3] = k0[3] * kwa.w * inv;
;             kk1[0] = k1[0] * kwb.x * inv; kk1[1] = k1[1] * kwb.y * inv; kk1[2] = k1[2] * kwb.z * inv; kk1[3] = k1[3] * kwb.w * inv;
;             f32x4 av0, av1, kka0, kka1, kp0, kp1;
;             av0[0] = sigmoidf_(a0a.x + x0[0]); av0[1] = sigmoidf_(a0a.y + x0[1]); av0[2] = sigmoidf_(a0a.z + x0[2]); av0[3] = sigmoidf_(a0a.w + x0[3]);
;             av1[0] = sigmoidf_(a0b.x + x1[0]); av1[1] = sigmoidf_(a0b.y + x1[1]); av1[2] = sigmoidf_(a0b.z + x1[2]); av1[3] = sigmoidf_(a0b.w + x1[3]);
;             kka0 = kk0 * av0; kka1 = kk1 * av1;
;             kp0[0] = k0[0] * (1.f + (av0[0] - 1.f) * kaa.x); kp0[1] = k0[1] * (1.f + (av0[1] - 1.f) * kaa.y);
;             kp0[2] = k0[2] * (1.f + (av0[2] - 1.f) * kaa.z); kp0[3] = k0[3] * (1.f + (av0[3] - 1.f) * kaa.w);
;             kp1[0] = k1[0] * (1.f + (av1[0] - 1.f) * kab.x); kp1[1] = k1[1] * (1.f + (av1[1] - 1.f) * kab.y);
;             kp1[2] = k1[2] * (1.f + (av1[2] - 1.f) * kab.z); kp1[3] = k1[3] * (1.f + (av1[3] - 1.f) * kab.w);
;             *(uint4*)((char*)sKKA + o2) = pack8(kka0, kka1); *(uint4*)((char*)sKP + o2) = pack8(kp0, kp1);
	v_cvt_pk_bf16_f32 v33, v176, v177
	v_pk_fma_f32 v[170:171], v[170:171], v[132:133], 1.0 op_sel_hi:[1,1,0]
	global_store_dwordx4 v204, v[30:33], s[18:19]
	v_pk_mul_f32 v[170:171], v[170:171], v[172:173]
	s_nop 0
	v_cvt_pk_bf16_f32 v31, v34, v35
	v_pk_mul_f32 v[34:35], v[144:145], v[164:165]
	v_cvt_pk_bf16_f32 v33, v170, v171
	v_pk_mul_f32 v[170:171], v[200:201], v[34:35] op_sel_hi:[0,1]
	v_add_f32_e32 v34, v78, v138
	v_add_f32_e32 v35, v79, v139
	v_mul_f32_e32 v34, 0xbfb8aa3b, v34
	v_mul_f32_e32 v35, 0xbfb8aa3b, v35
	v_exp_f32_e32 v34, v34
	v_exp_f32_e32 v35, v35
	v_cvt_pk_bf16_f32 v32, v36, v37
	v_pk_mul_f32 v[36:37], v[142:143], v[162:163]
	v_cvt_pk_bf16_f32 v30, v174, v175
	v_pk_add_f32 v[34:35], v[34:35], 1.0 op_sel_hi:[1,0]
	v_pk_mul_f32 v[172:173], v[200:201], v[36:37] op_sel_hi:[0,1]
	v_add_f32_e32 v36, v80, v140
	v_add_f32_e32 v37, v81, v141
	v_mul_f32_e32 v36, 0xbfb8aa3b, v36
	v_rcp_f32_e32 v35, v35
	v_mul_f32_e32 v37, 0xbfb8aa3b, v37
	v_exp_f32_e32 v36, v36
	v_exp_f32_e32 v37, v37
	v_rcp_f32_e32 v34, v34
	s_nop 0
	v_pk_add_f32 v[178:179], v[34:35], -1.0 op_sel_hi:[1,0]
	v_pk_add_f32 v[36:37], v[36:37], 1.0 op_sel_hi:[1,0]
	v_pk_fma_f32 v[178:179], v[178:179], v[150:151], 1.0 op_sel_hi:[1,1,0]
	global_store_dwordx4 v204, v[30:33], s[16:17]
	v_add_f32_e32 v174, v74, v134
	v_mul_f32_e32 v174, 0xbfb8aa3b, v174
	v_pk_mul_f32 v[32:33], v[146:147], v[166:167]
	v_pk_mul_f32 v[166:167], v[178:179], v[166:167]
	v_exp_f32_e32 v176, v174
	v_add_f32_e32 v174, v75, v135
	v_mul_f32_e32 v174, 0xbfb8aa3b, v174
	v_rcp_f32_e32 v37, v37
	v_pk_mul_f32 v[30:31], v[148:149], v[168:169]
	v_exp_f32_e32 v177, v174
	v_pk_mul_f32 v[30:31], v[30:31], v[200:201] op_sel_hi:[1,0]
	v_pk_mul_f32 v[32:33], v[32:33], v[200:201] op_sel_hi:[1,0]
	v_rcp_f32_e32 v36, v36
	s_nop 0
	v_pk_mul_f32 v[178:179], v[36:37], v[30:31]
	v_pk_mul_f32 v[30:31], v[34:35], v[32:33]
	v_pk_add_f32 v[32:33], v[36:37], -1.0 op_sel_hi:[1,0]
	v_add_f32_e32 v174, v76, v136
	v_pk_fma_f32 v[32:33], v[32:33], v[152:153], 1.0 op_sel_hi:[1,1,0]
	v_add_f32_e32 v175, v77, v137
	v_pk_mul_f32 v[34:35], v[32:33], v[168:169]
	v_pk_add_f32 v[32:33], v[176:177], 1.0 op_sel_hi:[1,0]
	v_mul_f32_e32 v174, 0xbfb8aa3b, v174
	v_mul_f32_e32 v175, 0xbfb8aa3b, v175
	v_exp_f32_e32 v174, v174
	v_exp_f32_e32 v175, v175
	v_rcp_f32_e32 v33, v33
	v_cvt_pk_bf16_f32 v30, v30, v31
	v_cvt_pk_bf16_f32 v31, v178, v179
	v_rcp_f32_e32 v32, v32
	s_nop 0
	v_pk_add_f32 v[36:37], v[32:33], -1.0 op_sel_hi:[1,0]
	v_pk_mul_f32 v[32:33], v[32:33], v[172:173]
	v_pk_fma_f32 v[36:37], v[36:37], v[130:131], 1.0 op_sel_hi:[1,1,0]
	v_cvt_pk_bf16_f32 v32, v32, v33
	v_pk_mul_f32 v[36:37], v[36:37], v[162:163]
	v_pk_add_f32 v[162:163], v[174:175], 1.0 op_sel_hi:[1,0]
	s_nop 0
	s_nop 0
	v_rcp_f32_e32 v163, v163
	s_nop 0
	v_rcp_f32_e32 v162, v162
	s_nop 0
	v_pk_mul_f32 v[168:169], v[162:163], v[170:171]
	v_pk_add_f32 v[162:163], v[162:163], -1.0 op_sel_hi:[1,0]
	v_cvt_pk_bf16_f32 v33, v168, v169
	v_pk_fma_f32 v[162:163], v[162:163], v[132:133], 1.0 op_sel_hi:[1,1,0]
	global_store_dwordx4 v180, v[30:33], s[18:19]
	v_pk_mul_f32 v[162:163], v[162:163], v[164:165]
	s_nop 0
	v_cvt_pk_bf16_f32 v30, v166, v167
	v_cvt_pk_bf16_f32 v31, v34, v35
	v_cvt_pk_bf16_f32 v32, v36, v37
	v_cvt_pk_bf16_f32 v33, v162, v163
	global_store_dwordx4 v180, v[30:33], s[16:17]
	v_pk_mul_f32 v[34:35], v[144:145], v[156:157]
	v_pk_mul_f32 v[36:37], v[142:143], v[154:155]
	v_pk_mul_f32 v[30:31], v[148:149], v[160:161]
	v_pk_mul_f32 v[32:33], v[146:147], v[158:159]
	v_pk_mul_f32 v[30:31], v[30:31], v[0:1] op_sel_hi:[1,0]
	v_pk_mul_f32 v[32:33], v[32:33], v[0:1] op_sel_hi:[1,0]
	v_pk_mul_f32 v[142:143], v[0:1], v[34:35] op_sel_hi:[0,1]
	v_pk_mul_f32 v[144:145], v[0:1], v[36:37] op_sel_hi:[0,1]
	v_add_f32_e32 v0, v70, v138
	v_mul_f32_e32 v0, 0xbfb8aa3b, v0
	v_exp_f32_e32 v34, v0
	v_add_f32_e32 v0, v71, v139
	v_mul_f32_e32 v0, 0xbfb8aa3b, v0
	v_exp_f32_e32 v35, v0
	v_add_f32_e32 v0, v72, v140
	v_mul_f32_e32 v0, 0xbfb8aa3b, v0
	v_exp_f32_e32 v36, v0
	v_add_f32_e32 v0, v73, v141
	v_mul_f32_e32 v0, 0xbfb8aa3b, v0
	v_exp_f32_e32 v37, v0
	v_add_f32_e32 v0, v66, v134
	v_mul_f32_e32 v0, 0xbfb8aa3b, v0
	v_exp_f32_e32 v138, v0
	v_add_f32_e32 v0, v67, v135
	v_mul_f32_e32 v0, 0xbfb8aa3b, v0
	v_exp_f32_e32 v139, v0
	v_add_f32_e32 v0, v68, v136
	v_mul_f32_e32 v0, 0xbfb8aa3b, v0
	v_exp_f32_e32 v134, v0
	v_add_f32_e32 v0, v69, v137
	v_mul_f32_e32 v0, 0xbfb8aa3b, v0
	v_pk_add_f32 v[34:35], v[34:35], 1.0 op_sel_hi:[1,0]
	v_exp_f32_e32 v135, v0
	v_pk_add_f32 v[36:37], v[36:37], 1.0 op_sel_hi:[1,0]
	v_add_u32_e32 v162, v216, v240
	v_rcp_f32_e32 v35, v35
	s_nop 0
	v_rcp_f32_e32 v34, v34
	s_nop 0
	v_pk_add_f32 v[136:137], v[34:35], -1.0 op_sel_hi:[1,0]
	v_rcp_f32_e32 v37, v37
	v_pk_fma_f32 v[136:137], v[136:137], v[150:151], 1.0 op_sel_hi:[1,1,0]
	v_rcp_f32_e32 v36, v36
	s_nop 0
	v_pk_mul_f32 v[140:141], v[36:37], v[30:31]
	v_pk_mul_f32 v[30:31], v[34:35], v[32:33]
	v_pk_add_f32 v[32:33], v[36:37], -1.0 op_sel_hi:[1,0]
	v_pk_mul_f32 v[136:137], v[136:137], v[158:159]
	v_pk_fma_f32 v[32:33], v[32:33], v[152:153], 1.0 op_sel_hi:[1,1,0]
	v_cvt_pk_bf16_f32 v30, v30, v31
	v_pk_mul_f32 v[34:35], v[32:33], v[160:161]
	v_pk_add_f32 v[32:33], v[138:139], 1.0 op_sel_hi:[1,0]
	v_cvt_pk_bf16_f32 v31, v140, v141
	s_nop 0
	v_rcp_f32_e32 v33, v33
	s_nop 0
	v_rcp_f32_e32 v32, v32
	s_nop 0
	v_pk_add_f32 v[36:37], v[32:33], -1.0 op_sel_hi:[1,0]
	v_pk_mul_f32 v[32:33], v[32:33], v[144:145]
	v_pk_fma_f32 v[36:37], v[36:37], v[130:131], 1.0 op_sel_hi:[1,1,0]
	v_pk_add_f32 v[130:131], v[134:135], 1.0 op_sel_hi:[1,0]
	v_pk_mul_f32 v[36:37], v[36:37], v[154:155]
	v_cvt_pk_bf16_f32 v32, v32, v33
	v_rcp_f32_e32 v131, v131
; DI uint4 pack8(f32x4 a, f32x4 b) { uint4 r; r.x = pack2(a[0], a[1]); r.y = pack2(a[2], a[3]); r.z = pack2(b[0], b[1]); r.w = pack2(b[2], b[3]); return r; }
; DI float sigmoidf_(float x) { return 1.f / (1.f + __expf(-x)); }
;   DI void operator()(const Acc8& acc, const pg8::Unit& u, int wr, int wc, int fr, int fq) const {
;     ...
;         for (int ai = 0; ai < 2; ++ai) {
;           f32x4 kq0[4], kq1[4]; float invq[4];
; #pragma unroll
;           for (int m = 0; m < 4; ++m) {
;             const unsigned row = (unsigned)EPI_ROWS(ai, m);
;             kq0[m] = *(const f32x4*)((const char*)zk + (row * 256u + c8) * 4u); kq1[m] = *(const f32x4*)((const char*)zk + (row * 256u + c8) * 4u + 16);
;             invq[m] = invn[row * 4u + (c8 >> 6)];
;           }
; #pragma unroll
;           for (int m = 0; m < 4; ++m) {
;             const unsigned o2 = ((unsigned)EPI_ROWS(ai, m) * 256u + c8) * 2u;
;             const f32x4 k0 = kq0[m], k1 = kq1[m]; const float inv = invq[m];
;             const f32x4 x0 = acc[ai][bj][m][0], x1 = acc[ai][bj][m][1];
;             f32x4 kk0, kk1;
;             kk0[0] = k0[0] * kwa.x * inv; kk0[1] = k0[1] * kwa.y * inv; kk0[2] = k0[2] * kwa.z * inv; kk0[3] = k0[3] * kwa.w * inv;
;             kk1[0] = k1[0] * kwb.x * inv; kk1[1] = k1[1] * kwb.y * inv; kk1[2] = k1[2] * kwb.z * inv; kk1[3] = k1[3] * kwb.w * inv;
;             f32x4 av0, av1, kka0, kka1, kp0, kp1;
;             av0[0] = sigmoidf_(a0a.x + x0[0]); av0[1] = sigmoidf_(a0a.y + x0[1]); av0[2] = sigmoidf_(a0a.z + x0[2]); av0[3] = sigmoidf_(a0a.w + x0[3]);
;             av1[0] = sigmoidf_(a0b.x + x1[0]); av1[1] = sigmoidf_(a0b.y + x1[1]); av1[2] = sigmoidf_(a0b.z + x1[2]); av1[3] = sigmoidf_(a0b.w + x1[3]);
;             kka0 = kk0 * av0; kka1 = kk1 * av1;
;             kp0[0] = k0[0] * (1.f + (av0[0] - 1.f) * kaa.x); kp0[1] = k0[1] * (1.f + (av0[1] - 1.f) * kaa.y);
;             kp0[2] = k0[2] * (1.f + (av0[2] - 1.f) * kaa.z); kp0[3] = k0[3] * (1.f + (av0[3] - 1.f) * kaa.w);
;             kp1[0] = k1[0] * (1.f + (av1[0] - 1.f) * kab.x); kp1[1] = k1[1] * (1.f + (av1[1] - 1.f) * kab.y);
;             kp1[2] = k1[2] * (1.f + (av1[2] - 1.f) * kab.z); kp1[3] = k1[3] * (1.f + (av1[3] - 1.f) * kab.w);
;             *(uint4*)((char*)sKKA + o2) = pack8(kka0, kka1); *(uint4*)((char*)sKP + o2) = pack8(kp0, kp1);
	s_nop 0
	v_rcp_f32_e32 v130, v130
	s_nop 0
	v_pk_mul_f32 v[134:135], v[130:131], v[142:143]
	v_pk_add_f32 v[130:131], v[130:131], -1.0 op_sel_hi:[1,0]
	v_cvt_pk_bf16_f32 v33, v134, v135
	v_pk_fma_f32 v[130:131], v[130:131], v[132:133], 1.0 op_sel_hi:[1,1,0]
	global_store_dwordx4 v162, v[30:33], s[18:19]
	v_pk_mul_f32 v[130:131], v[130:131], v[156:157]
	s_nop 0
	v_cvt_pk_bf16_f32 v30, v136, v137
	v_cvt_pk_bf16_f32 v31, v34, v35
	v_cvt_pk_bf16_f32 v32, v36, v37
	v_cvt_pk_bf16_f32 v33, v130, v131
	global_store_dwordx4 v162, v[30:33], s[16:17]
	v_add_u32_e32 v0, 0x80, v192
	global_load_dwordx4 v[130:133], v[198:199], off offset:528
	global_load_dwordx4 v[134:137], v[198:199], off offset:512
	v_lshlrev_b32_e32 v251, 2, v0
	v_ashrrev_i32_e32 v199, 6, v0
	v_lshlrev_b32_e32 v240, 1, v0
	v_lshlrev_b32_e32 v0, 10, v190
	v_add_u32_e32 v0, v251, v0
	global_load_dwordx4 v[178:181], v0, s[22:23] offset:16
	global_load_dwordx4 v[182:185], v0, s[22:23]
	v_add_u32_e32 v0, v199, v203
	v_lshl_add_u64 v[30:31], v[0:1], 2, s[20:21]
	v_add_u32_e32 v0, v250, v251
	global_load_dword v30, v[30:31], off
	s_nop 0
	global_load_dwordx4 v[170:173], v0, s[22:23] offset:16
	global_load_dwordx4 v[174:177], v0, s[22:23]
	v_add_u32_e32 v0, v249, v199
	v_lshl_add_u64 v[32:33], v[0:1], 2, s[20:21]
	v_add_u32_e32 v0, v248, v251
	global_load_dword v200, v[32:33], off
	global_load_dwordx4 v[162:165], v0, s[22:23] offset:16
	global_load_dwordx4 v[166:169], v0, s[22:23]
	v_add_u32_e32 v0, v247, v199
	v_lshl_add_u64 v[32:33], v[0:1], 2, s[20:21]
	v_add_u32_e32 v0, v245, v251
	global_load_dword v198, v[32:33], off
	global_load_dwordx4 v[154:157], v0, s[22:23] offset:16
	global_load_dwordx4 v[158:161], v0, s[22:23]
	v_add_u32_e32 v0, v244, v199
	v_lshl_add_u64 v[32:33], v[0:1], 2, s[20:21]
	global_load_dword v0, v[32:33], off
	global_load_dwordx4 v[146:149], v[196:197], off offset:528
	global_load_dwordx4 v[150:153], v[196:197], off offset:512
	global_load_dwordx4 v[138:141], v[194:195], off offset:528
	global_load_dwordx4 v[142:145], v[194:195], off offset:512
	v_add_u32_e32 v243, v240, v243
	s_waitcnt vmcnt(0)
	v_pk_mul_f32 v[32:33], v[152:153], v[184:185]
	v_pk_mul_f32 v[34:35], v[150:151], v[182:183]
	v_pk_mul_f32 v[206:207], v[32:33], v[30:31] op_sel_hi:[1,0]
	v_pk_mul_f32 v[208:209], v[34:35], v[30:31] op_sel_hi:[1,0]
	v_pk_mul_f32 v[32:33], v[148:149], v[180:181]
	v_pk_mul_f32 v[34:35], v[146:147], v[178:179]
	v_pk_mul_f32 v[196:197], v[30:31], v[32:33] op_sel_hi:[0,1]
	v_pk_mul_f32 v[202:203], v[30:31], v[34:35] op_sel_hi:[0,1]
	v_add_f32_e32 v30, v62, v134
	v_mul_f32_e32 v30, 0xbfb8aa3b, v30
	v_exp_f32_e32 v214, v30
	v_add_f32_e32 v30, v63, v135
	v_mul_f32_e32 v30, 0xbfb8aa3b, v30
	v_exp_f32_e32 v215, v30
	v_add_f32_e32 v30, v64, v136
	v_mul_f32_e32 v30, 0xbfb8aa3b, v30
	v_exp_f32_e32 v212, v30
	v_add_f32_e32 v30, v65, v137
	v_mul_f32_e32 v30, 0xbfb8aa3b, v30
	v_exp_f32_e32 v213, v30
	v_add_f32_e32 v30, v58, v130
	v_mul_f32_e32 v30, 0xbfb8aa3b, v30
	v_exp_f32_e32 v210, v30
	v_add_f32_e32 v30, v59, v131
	v_mul_f32_e32 v30, 0xbfb8aa3b, v30
	v_exp_f32_e32 v211, v30
	v_add_f32_e32 v30, v60, v132
	v_mul_f32_e32 v30, 0xbfb8aa3b, v30
	v_exp_f32_e32 v204, v30
	v_add_f32_e32 v30, v61, v133
	v_mul_f32_e32 v30, 0xbfb8aa3b, v30
	v_exp_f32_e32 v205, v30
	v_pk_add_f32 v[30:31], v[214:215], 1.0 op_sel_hi:[1,0]
	s_nop 0
	s_nop 0
	v_rcp_f32_e32 v195, v31
	s_nop 0
	v_rcp_f32_e32 v194, v30
	s_nop 0
	v_pk_add_f32 v[30:31], v[194:195], -1.0 op_sel_hi:[1,0]
	s_nop 0
	v_pk_fma_f32 v[30:31], v[30:31], v[142:143], 1.0 op_sel_hi:[1,1,0]
	s_nop 0
	v_pk_mul_f32 v[182:183], v[30:31], v[182:183]
	v_pk_add_f32 v[30:31], v[212:213], 1.0 op_sel_hi:[1,0]
	s_nop 0
	s_nop 0
	v_rcp_f32_e32 v31, v31
	s_nop 0
	v_rcp_f32_e32 v30, v30
	s_nop 0
	v_pk_mul_f32 v[32:33], v[30:31], v[206:207]
	v_pk_add_f32 v[30:31], v[30:31], -1.0 op_sel_hi:[1,0]
	v_pk_mul_f32 v[34:35], v[194:195], v[208:209]
	v_pk_fma_f32 v[30:31], v[30:31], v[144:145], 1.0 op_sel_hi:[1,1,0]
	s_nop 0
	v_pk_mul_f32 v[36:37], v[30:31], v[184:185]
	v_pk_add_f32 v[30:31], v[210:211], 1.0 op_sel_hi:[1,0]
	s_nop 0
	s_nop 0
	v_rcp_f32_e32 v31, v31
	s_nop 0
	v_rcp_f32_e32 v30, v30
	s_nop 0
	v_pk_add_f32 v[184:185], v[30:31], -1.0 op_sel_hi:[1,0]
	s_nop 0
	v_pk_fma_f32 v[184:185], v[184:185], v[138:139], 1.0 op_sel_hi:[1,1,0]
	s_nop 0
	v_pk_mul_f32 v[178:179], v[184:185], v[178:179]
	v_pk_add_f32 v[184:185], v[204:205], 1.0 op_sel_hi:[1,0]
	s_nop 0
	s_nop 0
	v_rcp_f32_e32 v185, v185
	s_nop 0
	v_rcp_f32_e32 v184, v184
	v_pk_mul_f32 v[194:195], v[30:31], v[202:203]
	v_pk_add_f32 v[30:31], v[184:185], -1.0 op_sel_hi:[1,0]
	v_pk_mul_f32 v[186:187], v[184:185], v[196:197]
	v_pk_fma_f32 v[30:31], v[30:31], v[140:141], 1.0 op_sel_hi:[1,1,0]
	s_nop 0
	v_pk_mul_f32 v[180:181], v[30:31], v[180:181]
	v_cvt_pk_bf16_f32 v30, v34, v35
	v_cvt_pk_bf16_f32 v31, v32, v33
	v_cvt_pk_bf16_f32 v32, v194, v195
	v_cvt_pk_bf16_f32 v33, v186, v187
	v_pk_mul_f32 v[34:35], v[148:149], v[172:173]
	global_store_dwordx4 v243, v[30:33], s[18:19]
	v_add_u32_e32 v194, v242, v240
	s_nop 0
	v_cvt_pk_bf16_f32 v32, v178, v179
	v_pk_mul_f32 v[178:179], v[200:201], v[34:35] op_sel_hi:[0,1]
	v_add_f32_e32 v34, v54, v134
	v_add_f32_e32 v35, v55, v135
	v_mul_f32_e32 v34, 0xbfb8aa3b, v34
	v_mul_f32_e32 v35, 0xbfb8aa3b, v35
	v_exp_f32_e32 v34, v34
	v_exp_f32_e32 v35, v35
	v_cvt_pk_bf16_f32 v31, v36, v37
	v_pk_mul_f32 v[36:37], v[146:147], v[170:171]
	v_cvt_pk_bf16_f32 v33, v180, v181
	v_pk_add_f32 v[34:35], v[34:35], 1.0 op_sel_hi:[1,0]
	v_pk_mul_f32 v[180:181], v[200:201], v[36:37] op_sel_hi:[0,1]
	v_add_f32_e32 v36, v56, v136
	v_add_f32_e32 v37, v57, v137
	v_mul_f32_e32 v36, 0xbfb8aa3b, v36
; DI uint4 pack8(f32x4 a, f32x4 b) { uint4 r; r.x = pack2(a[0], a[1]); r.y = pack2(a[2], a[3]); r.z = pack2(b[0], b[1]); r.w = pack2(b[2], b[3]); return r; }
; DI float sigmoidf_(float x) { return 1.f / (1.f + __expf(-x)); }
;   DI void operator()(const Acc8& acc, const pg8::Unit& u, int wr, int wc, int fr, int fq) const {
;     ...
; #pragma unroll
;           for (int m = 0; m < 4; ++m) {
;             const unsigned o2 = ((unsigned)EPI_ROWS(ai, m) * 256u + c8) * 2u;
;             const f32x4 k0 = kq0[m], k1 = kq1[m]; const float inv = invq[m];
;             const f32x4 x0 = acc[ai][bj][m][0], x1 = acc[ai][bj][m][1];
;             f32x4 kk0, kk1;
;             kk0[0] = k0[0] * kwa.x * inv; kk0[1] = k0[1] * kwa.y * inv; kk0[2] = k0[2] * kwa.z * inv; kk0[3] = k0[3] * kwa.w * inv;
;             kk1[0] = k1[0] * kwb.x * inv; kk1[1] = k1[1] * kwb.y * inv; kk1[2] = k1[2] * kwb.z * inv; kk1[3] = k1[3] * kwb.w * inv;
;             f32x4 av0, av1, kka0, kka1, kp0, kp1;
;             av0[0] = sigmoidf_(a0a.x + x0[0]); av0[1] = sigmoidf_(a0a.y + x0[1]); av0[2] = sigmoidf_(a0a.z + x0[2]); av0[3] = sigmoidf_(a0a.w + x0[3]);
;             av1[0] = sigmoidf_(a0b.x + x1[0]); av1[1] = sigmoidf_(a0b.y + x1[1]); av1[2] = sigmoidf_(a0b.z + x1[2]); av1[3] = sigmoidf_(a0b.w + x1[3]);
;             kka0 = kk0 * av0; kka1 = kk1 * av1;
;             kp0[0] = k0[0] * (1.f + (av0[0] - 1.f) * kaa.x); kp0[1] = k0[1] * (1.f + (av0[1] - 1.f) * kaa.y);
;             kp0[2] = k0[2] * (1.f + (av0[2] - 1.f) * kaa.z); kp0[3] = k0[3] * (1.f + (av0[3] - 1.f) * kaa.w);
;             kp1[0] = k1[0] * (1.f + (av1[0] - 1.f) * kab.x); kp1[1] = k1[1] * (1.f + (av1[1] - 1.f) * kab.y);
;             kp1[2] = k1[2] * (1.f + (av1[2] - 1.f) * kab.z); kp1[3] = k1[3] * (1.f + (av1[3] - 1.f) * kab.w);
;             *(uint4*)((char*)sKKA + o2) = pack8(kka0, kka1); *(uint4*)((char*)sKP + o2) = pack8(kp0, kp1);
	v_rcp_f32_e32 v35, v35
	v_mul_f32_e32 v37, 0xbfb8aa3b, v37
	v_exp_f32_e32 v36, v36
	v_exp_f32_e32 v37, v37
	v_rcp_f32_e32 v34, v34
	s_nop 0
	v_pk_add_f32 v[186:187], v[34:35], -1.0 op_sel_hi:[1,0]
	v_cvt_pk_bf16_f32 v30, v182, v183
	v_pk_fma_f32 v[186:187], v[186:187], v[142:143], 1.0 op_sel_hi:[1,1,0]
	v_pk_add_f32 v[36:37], v[36:37], 1.0 op_sel_hi:[1,0]
	global_store_dwordx4 v243, v[30:33], s[16:17]
	v_add_f32_e32 v182, v50, v130
	v_mul_f32_e32 v182, 0xbfb8aa3b, v182
	v_pk_mul_f32 v[32:33], v[150:151], v[174:175]
	v_pk_mul_f32 v[174:175], v[186:187], v[174:175]
	v_exp_f32_e32 v184, v182
	v_add_f32_e32 v182, v51, v131
	v_mul_f32_e32 v182, 0xbfb8aa3b, v182
	v_rcp_f32_e32 v37, v37
	v_div_scale_f32 v186, s[4:5], v36, v36, 1.0
	v_rcp_f32_e32 v187, v186
	v_pk_mul_f32 v[30:31], v[152:153], v[176:177]
	v_exp_f32_e32 v185, v182
	v_pk_mul_f32 v[30:31], v[30:31], v[200:201] op_sel_hi:[1,0]
	v_fma_f32 v195, -v186, v187, 1.0
	v_fmac_f32_e32 v187, v195, v187
	v_div_scale_f32 v195, vcc, 1.0, v36, 1.0
	v_mul_f32_e32 v196, v195, v187
	v_fma_f32 v197, -v186, v196, v195
	v_fmac_f32_e32 v196, v197, v187
	v_fma_f32 v186, -v186, v196, v195
	v_div_fmas_f32 v186, v186, v187, v196
	v_pk_mul_f32 v[32:33], v[32:33], v[200:201] op_sel_hi:[1,0]
	v_div_fixup_f32 v36, v186, v36, 1.0
	v_pk_mul_f32 v[186:187], v[36:37], v[30:31]
	v_pk_mul_f32 v[30:31], v[34:35], v[32:33]
	v_pk_add_f32 v[32:33], v[36:37], -1.0 op_sel_hi:[1,0]
	v_add_f32_e32 v182, v52, v132
	v_pk_fma_f32 v[32:33], v[32:33], v[144:145], 1.0 op_sel_hi:[1,1,0]
	v_add_f32_e32 v183, v53, v133
	v_pk_mul_f32 v[34:35], v[32:33], v[176:177]
	v_pk_add_f32 v[32:33], v[184:185], 1.0 op_sel_hi:[1,0]
	v_mul_f32_e32 v182, 0xbfb8aa3b, v182
	v_mul_f32_e32 v183, 0xbfb8aa3b, v183
	v_exp_f32_e32 v182, v182
	v_exp_f32_e32 v183, v183
	v_rcp_f32_e32 v33, v33
	v_cvt_pk_bf16_f32 v30, v30, v31
	v_cvt_pk_bf16_f32 v31, v186, v187
	v_rcp_f32_e32 v32, v32
	s_nop 0
	v_pk_add_f32 v[36:37], v[32:33], -1.0 op_sel_hi:[1,0]
	v_pk_mul_f32 v[32:33], v[32:33], v[180:181]
	v_pk_fma_f32 v[36:37], v[36:37], v[138:139], 1.0 op_sel_hi:[1,1,0]
	v_cvt_pk_bf16_f32 v32, v32, v33
	v_pk_mul_f32 v[36:37], v[36:37], v[170:171]
	v_pk_add_f32 v[170:171], v[182:183], 1.0 op_sel_hi:[1,0]
	s_nop 0
	s_nop 0
	v_rcp_f32_e32 v171, v171
	s_nop 0
	v_rcp_f32_e32 v170, v170
	s_nop 0
	v_pk_mul_f32 v[176:177], v[170:171], v[178:179]
	v_pk_add_f32 v[170:171], v[170:171], -1.0 op_sel_hi:[1,0]
	v_cvt_pk_bf16_f32 v33, v176, v177
	v_pk_fma_f32 v[170:171], v[170:171], v[140:141], 1.0 op_sel_hi:[1,1,0]
	global_store_dwordx4 v194, v[30:33], s[18:19]
	v_pk_mul_f32 v[170:171], v[170:171], v[172:173]
	v_add_u32_e32 v182, v241, v240
	v_cvt_pk_bf16_f32 v30, v174, v175
	v_cvt_pk_bf16_f32 v31, v34, v35
	v_cvt_pk_bf16_f32 v32, v36, v37
	v_cvt_pk_bf16_f32 v33, v170, v171
	global_store_dwordx4 v194, v[30:33], s[16:17]
	s_nop 1
	v_pk_mul_f32 v[30:31], v[152:153], v[168:169]
	v_pk_mul_f32 v[32:33], v[150:151], v[166:167]
	v_pk_mul_f32 v[170:171], v[30:31], v[198:199] op_sel_hi:[1,0]
	v_pk_mul_f32 v[30:31], v[148:149], v[164:165]
	v_pk_mul_f32 v[172:173], v[32:33], v[198:199] op_sel_hi:[1,0]
	v_pk_mul_f32 v[174:175], v[198:199], v[30:31] op_sel_hi:[0,1]
	v_add_f32_e32 v30, v46, v134
	v_add_f32_e32 v31, v47, v135
	v_mul_f32_e32 v30, 0xbfb8aa3b, v30
	v_mul_f32_e32 v31, 0xbfb8aa3b, v31
	v_exp_f32_e32 v30, v30
	v_exp_f32_e32 v31, v31
	v_pk_mul_f32 v[32:33], v[146:147], v[162:163]
	v_pk_add_f32 v[30:31], v[30:31], 1.0 op_sel_hi:[1,0]
	v_pk_mul_f32 v[176:177], v[198:199], v[32:33] op_sel_hi:[0,1]
	s_nop 0
	v_rcp_f32_e32 v179, v31
	s_nop 0
	v_rcp_f32_e32 v178, v30
	v_add_f32_e32 v30, v48, v136
	v_add_f32_e32 v31, v49, v137
	v_mul_f32_e32 v30, 0xbfb8aa3b, v30
	v_mul_f32_e32 v31, 0xbfb8aa3b, v31
	v_exp_f32_e32 v30, v30
	v_exp_f32_e32 v31, v31
	s_nop 0
	v_pk_add_f32 v[30:31], v[30:31], 1.0 op_sel_hi:[1,0]
	s_nop 0
	s_nop 0
	v_rcp_f32_e32 v181, v31
	s_nop 0
	v_rcp_f32_e32 v180, v30
	v_add_f32_e32 v30, v42, v130
	v_add_f32_e32 v31, v43, v131
	v_mul_f32_e32 v30, 0xbfb8aa3b, v30
	v_mul_f32_e32 v31, 0xbfb8aa3b, v31
	v_exp_f32_e32 v30, v30
	v_exp_f32_e32 v31, v31
	s_nop 0
	v_pk_add_f32 v[30:31], v[30:31], 1.0 op_sel_hi:[1,0]
	s_nop 0
	s_nop 0
	v_rcp_f32_e32 v31, v31
	s_nop 0
	v_rcp_f32_e32 v30, v30
	v_add_f32_e32 v32, v44, v132
	v_add_f32_e32 v33, v45, v133
	v_mul_f32_e32 v32, 0xbfb8aa3b, v32
	v_mul_f32_e32 v33, 0xbfb8aa3b, v33
	v_exp_f32_e32 v32, v32
	v_exp_f32_e32 v33, v33
	s_nop 0
	v_pk_add_f32 v[32:33], v[32:33], 1.0 op_sel_hi:[1,0]
	s_nop 0
	s_nop 0
	v_rcp_f32_e32 v33, v33
	s_nop 0
	v_rcp_f32_e32 v32, v32
	v_pk_mul_f32 v[34:35], v[180:181], v[170:171]
	v_pk_mul_f32 v[36:37], v[178:179], v[172:173]
	v_pk_mul_f32 v[170:171], v[32:33], v[174:175]
	v_pk_mul_f32 v[172:173], v[30:31], v[176:177]
	v_pk_add_f32 v[174:175], v[178:179], -1.0 op_sel_hi:[1,0]
	v_pk_add_f32 v[30:31], v[30:31], -1.0 op_sel_hi:[1,0]
	v_pk_fma_f32 v[174:175], v[174:175], v[142:143], 1.0 op_sel_hi:[1,1,0]
	v_pk_fma_f32 v[30:31], v[30:31], v[138:139], 1.0 op_sel_hi:[1,1,0]
	v_pk_mul_f32 v[166:167], v[174:175], v[166:167]
	v_pk_add_f32 v[174:175], v[180:181], -1.0 op_sel_hi:[1,0]
	v_pk_mul_f32 v[162:163], v[30:31], v[162:163]
	v_pk_add_f32 v[30:31], v[32:33], -1.0 op_sel_hi:[1,0]
	v_pk_fma_f32 v[174:175], v[174:175], v[144:145], 1.0 op_sel_hi:[1,1,0]
	v_pk_fma_f32 v[30:31], v[30:31], v[140:141], 1.0 op_sel_hi:[1,1,0]
	v_pk_mul_f32 v[168:169], v[174:175], v[168:169]
	v_pk_mul_f32 v[164:165], v[30:31], v[164:165]
	v_cvt_pk_bf16_f32 v30, v36, v37
	v_cvt_pk_bf16_f32 v31, v34, v35
	v_cvt_pk_bf16_f32 v32, v172, v173
	v_cvt_pk_bf16_f32 v33, v170, v171
	global_store_dwordx4 v182, v[30:33], s[18:19]
	v_add_u32_e32 v174, v239, v240
	s_nop 0
; DI uint4 pack8(f32x4 a, f32x4 b) { uint4 r; r.x = pack2(a[0], a[1]); r.y = pack2(a[2], a[3]); r.z = pack2(b[0], b[1]); r.w = pack2(b[2], b[3]); return r; }
; DI float sigmoidf_(float x) { return 1.f / (1.f + __expf(-x)); }
;   DI void operator()(const Acc8& acc, const pg8::Unit& u, int wr, int wc, int fr, int fq) const {
;     ...
;         for (int ai = 0; ai < 2; ++ai) {
;           f32x4 kq0[4], kq1[4]; float invq[4];
; #pragma unroll
;           for (int m = 0; m < 4; ++m) {
;             const unsigned row = (unsigned)EPI_ROWS(ai, m);
;             kq0[m] = *(const f32x4*)((const char*)zk + (row * 256u + c8) * 4u); kq1[m] = *(const f32x4*)((const char*)zk + (row * 256u + c8) * 4u + 16);
;             invq[m] = invn[row * 4u + (c8 >> 6)];
;           }
; #pragma unroll
;           for (int m = 0; m < 4; ++m) {
;             const unsigned o2 = ((unsigned)EPI_ROWS(ai, m) * 256u + c8) * 2u;
;             const f32x4 k0 = kq0[m], k1 = kq1[m]; const float inv = invq[m];
;             const f32x4 x0 = acc[ai][bj][m][0], x1 = acc[ai][bj][m][1];
;             f32x4 kk0, kk1;
;             kk0[0] = k0[0] * kwa.x * inv; kk0[1] = k0[1] * kwa.y * inv; kk0[2] = k0[2] * kwa.z * inv; kk0[3] = k0[3] * kwa.w * inv;
;             kk1[0] = k1[0] * kwb.x * inv; kk1[1] = k1[1] * kwb.y * inv; kk1[2] = k1[2] * kwb.z * inv; kk1[3] = k1[3] * kwb.w * inv;
;             f32x4 av0, av1, kka0, kka1, kp0, kp1;
;             av0[0] = sigmoidf_(a0a.x + x0[0]); av0[1] = sigmoidf_(a0a.y + x0[1]); av0[2] = sigmoidf_(a0a.z + x0[2]); av0[3] = sigmoidf_(a0a.w + x0[3]);
;             av1[0] = sigmoidf_(a0b.x + x1[0]); av1[1] = sigmoidf_(a0b.y + x1[1]); av1[2] = sigmoidf_(a0b.z + x1[2]); av1[3] = sigmoidf_(a0b.w + x1[3]);
;             kka0 = kk0 * av0; kka1 = kk1 * av1;
;             kp0[0] = k0[0] * (1.f + (av0[0] - 1.f) * kaa.x); kp0[1] = k0[1] * (1.f + (av0[1] - 1.f) * kaa.y);
;             kp0[2] = k0[2] * (1.f + (av0[2] - 1.f) * kaa.z); kp0[3] = k0[3] * (1.f + (av0[3] - 1.f) * kaa.w);
;             kp1[0] = k1[0] * (1.f + (av1[0] - 1.f) * kab.x); kp1[1] = k1[1] * (1.f + (av1[1] - 1.f) * kab.y);
;             kp1[2] = k1[2] * (1.f + (av1[2] - 1.f) * kab.z); kp1[3] = k1[3] * (1.f + (av1[3] - 1.f) * kab.w);
;             *(uint4*)((char*)sKKA + o2) = pack8(kka0, kka1); *(uint4*)((char*)sKP + o2) = pack8(kp0, kp1);
	v_cvt_pk_bf16_f32 v30, v166, v167
	v_cvt_pk_bf16_f32 v31, v168, v169
	v_cvt_pk_bf16_f32 v32, v162, v163
	v_cvt_pk_bf16_f32 v33, v164, v165
	global_store_dwordx4 v182, v[30:33], s[16:17]
	s_nop 1
	v_pk_mul_f32 v[30:31], v[152:153], v[160:161]
	v_pk_mul_f32 v[32:33], v[150:151], v[158:159]
	v_pk_mul_f32 v[162:163], v[30:31], v[0:1] op_sel_hi:[1,0]
	v_pk_mul_f32 v[164:165], v[32:33], v[0:1] op_sel_hi:[1,0]
	v_pk_mul_f32 v[30:31], v[148:149], v[156:157]
	v_pk_mul_f32 v[32:33], v[146:147], v[154:155]
	v_pk_mul_f32 v[166:167], v[0:1], v[30:31] op_sel_hi:[0,1]
	v_pk_mul_f32 v[168:169], v[0:1], v[32:33] op_sel_hi:[0,1]
	v_add_f32_e32 v0, v38, v134
	v_mul_f32_e32 v0, 0xbfb8aa3b, v0
	v_exp_f32_e32 v30, v0
	v_add_f32_e32 v0, v39, v135
	v_mul_f32_e32 v0, 0xbfb8aa3b, v0
	v_exp_f32_e32 v31, v0
	s_nop 0
	v_pk_add_f32 v[30:31], v[30:31], 1.0 op_sel_hi:[1,0]
	s_nop 0
	s_nop 0
	v_rcp_f32_e32 v171, v31
	s_nop 0
	v_rcp_f32_e32 v170, v30
	v_add_f32_e32 v0, v40, v136
	v_mul_f32_e32 v0, 0xbfb8aa3b, v0
	v_exp_f32_e32 v30, v0
	v_add_f32_e32 v0, v41, v137
	v_mul_f32_e32 v0, 0xbfb8aa3b, v0
	v_exp_f32_e32 v31, v0
	s_nop 0
	v_pk_add_f32 v[30:31], v[30:31], 1.0 op_sel_hi:[1,0]
	s_nop 0
	s_nop 0
	v_rcp_f32_e32 v173, v31
	s_nop 0
	v_rcp_f32_e32 v172, v30
	v_add_f32_e32 v0, v232, v130
	v_mul_f32_e32 v0, 0xbfb8aa3b, v0
	v_exp_f32_e32 v30, v0
	v_add_f32_e32 v0, v233, v131
	v_mul_f32_e32 v0, 0xbfb8aa3b, v0
	v_exp_f32_e32 v31, v0
	s_nop 0
	v_pk_add_f32 v[30:31], v[30:31], 1.0 op_sel_hi:[1,0]
	s_nop 0
	s_nop 0
	v_rcp_f32_e32 v31, v31
	s_nop 0
	v_rcp_f32_e32 v30, v30
	v_add_f32_e32 v0, v234, v132
	v_mul_f32_e32 v0, 0xbfb8aa3b, v0
	v_exp_f32_e32 v32, v0
	v_add_f32_e32 v0, v235, v133
	v_mul_f32_e32 v0, 0xbfb8aa3b, v0
	v_exp_f32_e32 v33, v0
	s_nop 0
	v_pk_add_f32 v[32:33], v[32:33], 1.0 op_sel_hi:[1,0]
	s_nop 0
	s_nop 0
	v_rcp_f32_e32 v33, v33
	s_nop 0
	v_rcp_f32_e32 v32, v32
	v_pk_mul_f32 v[34:35], v[172:173], v[162:163]
	v_pk_mul_f32 v[36:37], v[170:171], v[164:165]
	v_pk_mul_f32 v[162:163], v[32:33], v[166:167]
	v_pk_mul_f32 v[164:165], v[30:31], v[168:169]
	v_pk_add_f32 v[166:167], v[170:171], -1.0 op_sel_hi:[1,0]
	v_pk_add_f32 v[30:31], v[30:31], -1.0 op_sel_hi:[1,0]
	v_pk_fma_f32 v[166:167], v[166:167], v[142:143], 1.0 op_sel_hi:[1,1,0]
	v_pk_fma_f32 v[30:31], v[30:31], v[138:139], 1.0 op_sel_hi:[1,1,0]
	v_pk_mul_f32 v[158:159], v[166:167], v[158:159]
	v_pk_add_f32 v[166:167], v[172:173], -1.0 op_sel_hi:[1,0]
	v_pk_mul_f32 v[154:155], v[30:31], v[154:155]
	v_pk_add_f32 v[30:31], v[32:33], -1.0 op_sel_hi:[1,0]
	v_pk_fma_f32 v[166:167], v[166:167], v[144:145], 1.0 op_sel_hi:[1,1,0]
	v_pk_fma_f32 v[30:31], v[30:31], v[140:141], 1.0 op_sel_hi:[1,1,0]
	v_pk_mul_f32 v[160:161], v[166:167], v[160:161]
	v_pk_mul_f32 v[156:157], v[30:31], v[156:157]
	v_cvt_pk_bf16_f32 v30, v36, v37
	v_cvt_pk_bf16_f32 v31, v34, v35
	v_cvt_pk_bf16_f32 v32, v164, v165
	v_cvt_pk_bf16_f32 v33, v162, v163
	global_store_dwordx4 v174, v[30:33], s[18:19]
	s_nop 1
	v_cvt_pk_bf16_f32 v30, v158, v159
	v_cvt_pk_bf16_f32 v31, v160, v161
	v_cvt_pk_bf16_f32 v32, v154, v155
	v_cvt_pk_bf16_f32 v33, v156, v157
	global_store_dwordx4 v174, v[30:33], s[16:17]
	v_add_u32_e32 v0, v191, v251
	global_load_dwordx4 v[178:181], v0, s[22:23] offset:16
	global_load_dwordx4 v[182:185], v0, s[22:23]
	v_add_u32_e32 v0, v246, v199
	v_lshl_add_u64 v[30:31], v[0:1], 2, s[20:21]
	global_load_dword v30, v[30:31], off
	v_add_u32_e32 v0, v219, v251
	global_load_dwordx4 v[170:173], v0, s[22:23] offset:16
	global_load_dwordx4 v[174:177], v0, s[22:23]
	v_add_u32_e32 v0, v227, v199
	v_lshl_add_u64 v[32:33], v[0:1], 2, s[20:21]
	v_add_u32_e32 v0, v201, v251
	global_load_dword v196, v[32:33], off
	global_load_dwordx4 v[162:165], v0, s[22:23] offset:16
	global_load_dwordx4 v[166:169], v0, s[22:23]
	v_add_u32_e32 v0, v236, v199
	v_lshl_add_u64 v[32:33], v[0:1], 2, s[20:21]
	v_add_u32_e32 v0, v237, v251
	global_load_dword v194, v[32:33], off
	global_load_dwordx4 v[154:157], v0, s[22:23] offset:16
	global_load_dwordx4 v[158:161], v0, s[22:23]
	v_add_u32_e32 v0, v238, v199
	v_lshl_add_u64 v[32:33], v[0:1], 2, s[20:21]
	global_load_dword v0, v[32:33], off
	v_add_u32_e32 v191, v218, v240
	s_waitcnt vmcnt(0)
	v_pk_mul_f32 v[32:33], v[152:153], v[184:185]
	v_pk_mul_f32 v[34:35], v[150:151], v[182:183]
	v_pk_mul_f32 v[198:199], v[32:33], v[30:31] op_sel_hi:[1,0]
	v_pk_mul_f32 v[200:201], v[34:35], v[30:31] op_sel_hi:[1,0]
	v_pk_mul_f32 v[32:33], v[148:149], v[180:181]
	v_pk_mul_f32 v[34:35], v[146:147], v[178:179]
	v_pk_mul_f32 v[202:203], v[30:31], v[32:33] op_sel_hi:[0,1]
	v_pk_mul_f32 v[204:205], v[30:31], v[34:35] op_sel_hi:[0,1]
	v_add_f32_e32 v30, v6, v134
	v_add_f32_e32 v31, v7, v135
	v_mul_f32_e32 v30, 0xbfb8aa3b, v30
	v_mul_f32_e32 v31, 0xbfb8aa3b, v31
	v_exp_f32_e32 v30, v30
	v_exp_f32_e32 v31, v31
	s_nop 0
	v_pk_add_f32 v[30:31], v[30:31], 1.0 op_sel_hi:[1,0]
	s_nop 0
	s_nop 0
	v_rcp_f32_e32 v207, v31
	s_nop 0
	v_rcp_f32_e32 v206, v30
	v_add_f32_e32 v30, v8, v136
	v_add_f32_e32 v31, v9, v137
	v_mul_f32_e32 v30, 0xbfb8aa3b, v30
	v_mul_f32_e32 v31, 0xbfb8aa3b, v31
	v_exp_f32_e32 v30, v30
	v_exp_f32_e32 v31, v31
	s_nop 0
	v_pk_add_f32 v[30:31], v[30:31], 1.0 op_sel_hi:[1,0]
	s_nop 0
	s_nop 0
	v_rcp_f32_e32 v209, v31
	s_nop 0
	v_rcp_f32_e32 v208, v30
	v_add_f32_e32 v30, v26, v130
	v_add_f32_e32 v31, v27, v131
	v_mul_f32_e32 v30, 0xbfb8aa3b, v30
	v_mul_f32_e32 v31, 0xbfb8aa3b, v31
	v_exp_f32_e32 v30, v30
	v_exp_f32_e32 v31, v31
	s_nop 0
	v_pk_add_f32 v[30:31], v[30:31], 1.0 op_sel_hi:[1,0]
	s_nop 0
	s_nop 0
	v_rcp_f32_e32 v31, v31
	s_nop 0
	v_rcp_f32_e32 v30, v30
	v_add_f32_e32 v32, v28, v132
	v_add_f32_e32 v33, v29, v133
	v_mul_f32_e32 v32, 0xbfb8aa3b, v32
; DI uint4 pack8(f32x4 a, f32x4 b) { uint4 r; r.x = pack2(a[0], a[1]); r.y = pack2(a[2], a[3]); r.z = pack2(b[0], b[1]); r.w = pack2(b[2], b[3]); return r; }
; DI float sigmoidf_(float x) { return 1.f / (1.f + __expf(-x)); }
;   DI void operator()(const Acc8& acc, const pg8::Unit& u, int wr, int wc, int fr, int fq) const {
;     ...
; #pragma unroll
;           for (int m = 0; m < 4; ++m) {
;             const unsigned o2 = ((unsigned)EPI_ROWS(ai, m) * 256u + c8) * 2u;
;             const f32x4 k0 = kq0[m], k1 = kq1[m]; const float inv = invq[m];
;             const f32x4 x0 = acc[ai][bj][m][0], x1 = acc[ai][bj][m][1];
;             f32x4 kk0, kk1;
;             kk0[0] = k0[0] * kwa.x * inv; kk0[1] = k0[1] * kwa.y * inv; kk0[2] = k0[2] * kwa.z * inv; kk0[3] = k0[3] * kwa.w * inv;
;             kk1[0] = k1[0] * kwb.x * inv; kk1[1] = k1[1] * kwb.y * inv; kk1[2] = k1[2] * kwb.z * inv; kk1[3] = k1[3] * kwb.w * inv;
;             f32x4 av0, av1, kka0, kka1, kp0, kp1;
;             av0[0] = sigmoidf_(a0a.x + x0[0]); av0[1] = sigmoidf_(a0a.y + x0[1]); av0[2] = sigmoidf_(a0a.z + x0[2]); av0[3] = sigmoidf_(a0a.w + x0[3]);
;             av1[0] = sigmoidf_(a0b.x + x1[0]); av1[1] = sigmoidf_(a0b.y + x1[1]); av1[2] = sigmoidf_(a0b.z + x1[2]); av1[3] = sigmoidf_(a0b.w + x1[3]);
;             kka0 = kk0 * av0; kka1 = kk1 * av1;
;             kp0[0] = k0[0] * (1.f + (av0[0] - 1.f) * kaa.x); kp0[1] = k0[1] * (1.f + (av0[1] - 1.f) * kaa.y);
;             kp0[2] = k0[2] * (1.f + (av0[2] - 1.f) * kaa.z); kp0[3] = k0[3] * (1.f + (av0[3] - 1.f) * kaa.w);
;             kp1[0] = k1[0] * (1.f + (av1[0] - 1.f) * kab.x); kp1[1] = k1[1] * (1.f + (av1[1] - 1.f) * kab.y);
;             kp1[2] = k1[2] * (1.f + (av1[2] - 1.f) * kab.z); kp1[3] = k1[3] * (1.f + (av1[3] - 1.f) * kab.w);
;             *(uint4*)((char*)sKKA + o2) = pack8(kka0, kka1); *(uint4*)((char*)sKP + o2) = pack8(kp0, kp1);
	v_mul_f32_e32 v33, 0xbfb8aa3b, v33
	v_exp_f32_e32 v32, v32
	v_exp_f32_e32 v33, v33
	s_nop 0
	v_pk_add_f32 v[32:33], v[32:33], 1.0 op_sel_hi:[1,0]
	s_nop 0
	s_nop 0
	v_rcp_f32_e32 v33, v33
	s_nop 0
	v_rcp_f32_e32 v32, v32
	v_pk_mul_f32 v[34:35], v[208:209], v[198:199]
	v_pk_mul_f32 v[36:37], v[206:207], v[200:201]
	v_pk_mul_f32 v[198:199], v[30:31], v[204:205]
	v_pk_add_f32 v[200:201], v[206:207], -1.0 op_sel_hi:[1,0]
	v_pk_add_f32 v[30:31], v[30:31], -1.0 op_sel_hi:[1,0]
	v_pk_fma_f32 v[200:201], v[200:201], v[142:143], 1.0 op_sel_hi:[1,1,0]
	v_pk_fma_f32 v[30:31], v[30:31], v[138:139], 1.0 op_sel_hi:[1,1,0]
	v_pk_mul_f32 v[182:183], v[200:201], v[182:183]
	v_pk_add_f32 v[200:201], v[208:209], -1.0 op_sel_hi:[1,0]
	v_pk_mul_f32 v[178:179], v[30:31], v[178:179]
	v_pk_add_f32 v[30:31], v[32:33], -1.0 op_sel_hi:[1,0]
	v_pk_mul_f32 v[186:187], v[32:33], v[202:203]
	v_pk_fma_f32 v[200:201], v[200:201], v[144:145], 1.0 op_sel_hi:[1,1,0]
	v_pk_fma_f32 v[30:31], v[30:31], v[140:141], 1.0 op_sel_hi:[1,1,0]
	v_pk_mul_f32 v[184:185], v[200:201], v[184:185]
	v_pk_mul_f32 v[180:181], v[30:31], v[180:181]
	v_cvt_pk_bf16_f32 v30, v36, v37
	v_cvt_pk_bf16_f32 v31, v34, v35
	v_cvt_pk_bf16_f32 v32, v198, v199
	v_cvt_pk_bf16_f32 v33, v186, v187
	global_store_dwordx4 v191, v[30:33], s[18:19]
	v_add_u32_e32 v186, v231, v240
	v_mov_b32_e32 v231, 0x1000
	v_cvt_pk_bf16_f32 v30, v182, v183
	v_cvt_pk_bf16_f32 v31, v184, v185
	v_cvt_pk_bf16_f32 v32, v178, v179
	v_cvt_pk_bf16_f32 v33, v180, v181
	global_store_dwordx4 v191, v[30:33], s[16:17]
	s_nop 1
	v_pk_mul_f32 v[30:31], v[152:153], v[176:177]
	v_pk_mul_f32 v[32:33], v[150:151], v[174:175]
	v_pk_mul_f32 v[178:179], v[30:31], v[196:197] op_sel_hi:[1,0]
	v_pk_mul_f32 v[30:31], v[148:149], v[172:173]
	v_pk_mul_f32 v[180:181], v[32:33], v[196:197] op_sel_hi:[1,0]
	v_pk_mul_f32 v[182:183], v[196:197], v[30:31] op_sel_hi:[0,1]
	v_add_f32_e32 v30, v22, v134
	v_add_f32_e32 v31, v23, v135
	v_mul_f32_e32 v30, 0xbfb8aa3b, v30
	v_mul_f32_e32 v31, 0xbfb8aa3b, v31
	v_exp_f32_e32 v30, v30
	v_exp_f32_e32 v31, v31
	v_pk_mul_f32 v[32:33], v[146:147], v[170:171]
	v_pk_add_f32 v[30:31], v[30:31], 1.0 op_sel_hi:[1,0]
	v_pk_mul_f32 v[184:185], v[196:197], v[32:33] op_sel_hi:[0,1]
	s_nop 0
	v_rcp_f32_e32 v197, v31
	s_nop 0
	v_rcp_f32_e32 v196, v30
	v_add_f32_e32 v30, v24, v136
	v_add_f32_e32 v31, v25, v137
	v_mul_f32_e32 v30, 0xbfb8aa3b, v30
	v_mul_f32_e32 v31, 0xbfb8aa3b, v31
	v_exp_f32_e32 v30, v30
	v_exp_f32_e32 v31, v31
	s_nop 0
	v_pk_add_f32 v[30:31], v[30:31], 1.0 op_sel_hi:[1,0]
	s_nop 0
	s_nop 0
	v_rcp_f32_e32 v199, v31
	s_nop 0
	v_rcp_f32_e32 v198, v30
	v_add_f32_e32 v30, v18, v130
	v_add_f32_e32 v31, v19, v131
	v_mul_f32_e32 v30, 0xbfb8aa3b, v30
	v_mul_f32_e32 v31, 0xbfb8aa3b, v31
	v_exp_f32_e32 v30, v30
	v_exp_f32_e32 v31, v31
	s_nop 0
	v_pk_add_f32 v[30:31], v[30:31], 1.0 op_sel_hi:[1,0]
	s_nop 0
	s_nop 0
	v_rcp_f32_e32 v31, v31
	s_nop 0
	v_rcp_f32_e32 v30, v30
	v_add_f32_e32 v32, v20, v132
	v_add_f32_e32 v33, v21, v133
	v_mul_f32_e32 v32, 0xbfb8aa3b, v32
	v_mul_f32_e32 v33, 0xbfb8aa3b, v33
	v_exp_f32_e32 v32, v32
	v_exp_f32_e32 v33, v33
	s_nop 0
	v_pk_add_f32 v[32:33], v[32:33], 1.0 op_sel_hi:[1,0]
	s_nop 0
	s_nop 0
	v_rcp_f32_e32 v33, v33
	s_nop 0
	v_rcp_f32_e32 v32, v32
	v_pk_mul_f32 v[34:35], v[198:199], v[178:179]
	v_pk_mul_f32 v[36:37], v[196:197], v[180:181]
	v_pk_mul_f32 v[178:179], v[32:33], v[182:183]
	v_pk_mul_f32 v[180:181], v[30:31], v[184:185]
	v_pk_add_f32 v[182:183], v[196:197], -1.0 op_sel_hi:[1,0]
	v_pk_add_f32 v[30:31], v[30:31], -1.0 op_sel_hi:[1,0]
	v_pk_fma_f32 v[182:183], v[182:183], v[142:143], 1.0 op_sel_hi:[1,1,0]
	v_pk_fma_f32 v[30:31], v[30:31], v[138:139], 1.0 op_sel_hi:[1,1,0]
	v_pk_mul_f32 v[174:175], v[182:183], v[174:175]
	v_pk_add_f32 v[182:183], v[198:199], -1.0 op_sel_hi:[1,0]
	v_pk_mul_f32 v[170:171], v[30:31], v[170:171]
	v_pk_add_f32 v[30:31], v[32:33], -1.0 op_sel_hi:[1,0]
	v_pk_fma_f32 v[182:183], v[182:183], v[144:145], 1.0 op_sel_hi:[1,1,0]
	v_pk_fma_f32 v[30:31], v[30:31], v[140:141], 1.0 op_sel_hi:[1,1,0]
	v_pk_mul_f32 v[176:177], v[182:183], v[176:177]
	v_pk_mul_f32 v[172:173], v[30:31], v[172:173]
	v_cvt_pk_bf16_f32 v30, v36, v37
	v_cvt_pk_bf16_f32 v31, v34, v35
	v_cvt_pk_bf16_f32 v32, v180, v181
	v_cvt_pk_bf16_f32 v33, v178, v179
	global_store_dwordx4 v186, v[30:33], s[18:19]
	v_add_u32_e32 v182, v217, v240
	s_nop 0
	v_cvt_pk_bf16_f32 v30, v174, v175
	v_cvt_pk_bf16_f32 v31, v176, v177
	v_cvt_pk_bf16_f32 v32, v170, v171
	v_cvt_pk_bf16_f32 v33, v172, v173
	global_store_dwordx4 v186, v[30:33], s[16:17]
	v_mov_b64_e32 v[184:185], v[232:233]
	v_mov_b64_e32 v[186:187], v[234:235]
	v_pk_mul_f32 v[30:31], v[152:153], v[168:169]
	v_pk_mul_f32 v[32:33], v[150:151], v[166:167]
	v_pk_mul_f32 v[170:171], v[30:31], v[194:195] op_sel_hi:[1,0]
	v_pk_mul_f32 v[30:31], v[148:149], v[164:165]
	v_pk_mul_f32 v[172:173], v[32:33], v[194:195] op_sel_hi:[1,0]
	v_pk_mul_f32 v[174:175], v[194:195], v[30:31] op_sel_hi:[0,1]
	v_add_f32_e32 v30, v14, v134
	v_add_f32_e32 v31, v15, v135
	v_mul_f32_e32 v30, 0xbfb8aa3b, v30
	v_mul_f32_e32 v31, 0xbfb8aa3b, v31
	v_exp_f32_e32 v30, v30
	v_exp_f32_e32 v31, v31
	v_pk_mul_f32 v[32:33], v[146:147], v[162:163]
	v_pk_add_f32 v[30:31], v[30:31], 1.0 op_sel_hi:[1,0]
	v_pk_mul_f32 v[176:177], v[194:195], v[32:33] op_sel_hi:[0,1]
; DI uint4 pack8(f32x4 a, f32x4 b) { uint4 r; r.x = pack2(a[0], a[1]); r.y = pack2(a[2], a[3]); r.z = pack2(b[0], b[1]); r.w = pack2(b[2], b[3]); return r; }
; DI float sigmoidf_(float x) { return 1.f / (1.f + __expf(-x)); }
;   DI void operator()(const Acc8& acc, const pg8::Unit& u, int wr, int wc, int fr, int fq) const {
;     ...
; #pragma unroll
;           for (int m = 0; m < 4; ++m) {
;             const unsigned o2 = ((unsigned)EPI_ROWS(ai, m) * 256u + c8) * 2u;
;             const f32x4 k0 = kq0[m], k1 = kq1[m]; const float inv = invq[m];
;             const f32x4 x0 = acc[ai][bj][m][0], x1 = acc[ai][bj][m][1];
;             f32x4 kk0, kk1;
;             kk0[0] = k0[0] * kwa.x * inv; kk0[1] = k0[1] * kwa.y * inv; kk0[2] = k0[2] * kwa.z * inv; kk0[3] = k0[3] * kwa.w * inv;
;             kk1[0] = k1[0] * kwb.x * inv; kk1[1] = k1[1] * kwb.y * inv; kk1[2] = k1[2] * kwb.z * inv; kk1[3] = k1[3] * kwb.w * inv;
;             f32x4 av0, av1, kka0, kka1, kp0, kp1;
;             av0[0] = sigmoidf_(a0a.x + x0[0]); av0[1] = sigmoidf_(a0a.y + x0[1]); av0[2] = sigmoidf_(a0a.z + x0[2]); av0[3] = sigmoidf_(a0a.w + x0[3]);
;             av1[0] = sigmoidf_(a0b.x + x1[0]); av1[1] = sigmoidf_(a0b.y + x1[1]); av1[2] = sigmoidf_(a0b.z + x1[2]); av1[3] = sigmoidf_(a0b.w + x1[3]);
;             kka0 = kk0 * av0; kka1 = kk1 * av1;
;             kp0[0] = k0[0] * (1.f + (av0[0] - 1.f) * kaa.x); kp0[1] = k0[1] * (1.f + (av0[1] - 1.f) * kaa.y);
;             kp0[2] = k0[2] * (1.f + (av0[2] - 1.f) * kaa.z); kp0[3] = k0[3] * (1.f + (av0[3] - 1.f) * kaa.w);
;             kp1[0] = k1[0] * (1.f + (av1[0] - 1.f) * kab.x); kp1[1] = k1[1] * (1.f + (av1[1] - 1.f) * kab.y);
;             kp1[2] = k1[2] * (1.f + (av1[2] - 1.f) * kab.z); kp1[3] = k1[3] * (1.f + (av1[3] - 1.f) * kab.w);
;             *(uint4*)((char*)sKKA + o2) = pack8(kka0, kka1); *(uint4*)((char*)sKP + o2) = pack8(kp0, kp1);
	s_nop 0
	v_rcp_f32_e32 v179, v31
	s_nop 0
	v_rcp_f32_e32 v178, v30
	v_add_f32_e32 v30, v16, v136
	v_add_f32_e32 v31, v17, v137
	v_mul_f32_e32 v30, 0xbfb8aa3b, v30
	v_mul_f32_e32 v31, 0xbfb8aa3b, v31
	v_exp_f32_e32 v30, v30
	v_exp_f32_e32 v31, v31
	s_nop 0
	v_pk_add_f32 v[30:31], v[30:31], 1.0 op_sel_hi:[1,0]
	s_nop 0
	s_nop 0
	v_rcp_f32_e32 v181, v31
	s_nop 0
	v_rcp_f32_e32 v180, v30
	v_add_f32_e32 v30, v10, v130
	v_add_f32_e32 v31, v11, v131
	v_mul_f32_e32 v30, 0xbfb8aa3b, v30
	v_mul_f32_e32 v31, 0xbfb8aa3b, v31
	v_exp_f32_e32 v30, v30
	v_exp_f32_e32 v31, v31
	s_nop 0
	v_pk_add_f32 v[30:31], v[30:31], 1.0 op_sel_hi:[1,0]
	s_nop 0
	s_nop 0
	v_rcp_f32_e32 v31, v31
	s_nop 0
	v_rcp_f32_e32 v30, v30
	v_add_f32_e32 v32, v12, v132
	v_add_f32_e32 v33, v13, v133
	v_mul_f32_e32 v32, 0xbfb8aa3b, v32
	v_mul_f32_e32 v33, 0xbfb8aa3b, v33
	v_exp_f32_e32 v32, v32
	v_exp_f32_e32 v33, v33
	s_nop 0
	v_pk_add_f32 v[32:33], v[32:33], 1.0 op_sel_hi:[1,0]
	s_nop 0
	s_nop 0
	v_rcp_f32_e32 v33, v33
	s_nop 0
	v_rcp_f32_e32 v32, v32
	v_pk_mul_f32 v[34:35], v[180:181], v[170:171]
	v_pk_mul_f32 v[36:37], v[178:179], v[172:173]
	v_pk_mul_f32 v[170:171], v[32:33], v[174:175]
	v_pk_mul_f32 v[172:173], v[30:31], v[176:177]
	v_pk_add_f32 v[174:175], v[178:179], -1.0 op_sel_hi:[1,0]
	v_pk_add_f32 v[30:31], v[30:31], -1.0 op_sel_hi:[1,0]
	v_pk_fma_f32 v[174:175], v[174:175], v[142:143], 1.0 op_sel_hi:[1,1,0]
	v_pk_fma_f32 v[30:31], v[30:31], v[138:139], 1.0 op_sel_hi:[1,1,0]
	v_pk_mul_f32 v[166:167], v[174:175], v[166:167]
	v_pk_add_f32 v[174:175], v[180:181], -1.0 op_sel_hi:[1,0]
	v_pk_mul_f32 v[162:163], v[30:31], v[162:163]
	v_pk_add_f32 v[30:31], v[32:33], -1.0 op_sel_hi:[1,0]
	v_pk_fma_f32 v[174:175], v[174:175], v[144:145], 1.0 op_sel_hi:[1,1,0]
	v_pk_fma_f32 v[30:31], v[30:31], v[140:141], 1.0 op_sel_hi:[1,1,0]
	v_pk_mul_f32 v[168:169], v[174:175], v[168:169]
	v_pk_mul_f32 v[164:165], v[30:31], v[164:165]
	v_cvt_pk_bf16_f32 v30, v36, v37
	v_cvt_pk_bf16_f32 v31, v34, v35
	v_cvt_pk_bf16_f32 v32, v172, v173
	v_cvt_pk_bf16_f32 v33, v170, v171
	global_store_dwordx4 v182, v[30:33], s[18:19]
	s_nop 1
	v_cvt_pk_bf16_f32 v30, v166, v167
	v_cvt_pk_bf16_f32 v31, v168, v169
	v_cvt_pk_bf16_f32 v32, v162, v163
	v_cvt_pk_bf16_f32 v33, v164, v165
	global_store_dwordx4 v182, v[30:33], s[16:17]
	v_add_u32_e32 v162, v216, v240
	s_nop 0
	v_pk_mul_f32 v[30:31], v[152:153], v[160:161]
	v_pk_mul_f32 v[32:33], v[150:151], v[158:159]
	v_pk_mul_f32 v[150:151], v[30:31], v[0:1] op_sel_hi:[1,0]
	v_pk_mul_f32 v[152:153], v[32:33], v[0:1] op_sel_hi:[1,0]
	v_pk_mul_f32 v[30:31], v[148:149], v[156:157]
	v_pk_mul_f32 v[32:33], v[146:147], v[154:155]
	v_pk_mul_f32 v[146:147], v[0:1], v[30:31] op_sel_hi:[0,1]
	v_pk_mul_f32 v[148:149], v[0:1], v[32:33] op_sel_hi:[0,1]
	v_add_f32_e32 v0, v222, v134
	v_mul_f32_e32 v0, 0xbfb8aa3b, v0
	v_exp_f32_e32 v30, v0
	v_add_f32_e32 v0, v223, v135
	v_mul_f32_e32 v0, 0xbfb8aa3b, v0
	v_exp_f32_e32 v31, v0
	s_nop 0
	v_pk_add_f32 v[30:31], v[30:31], 1.0 op_sel_hi:[1,0]
	s_nop 0
	s_nop 0
	v_rcp_f32_e32 v135, v31
	s_nop 0
	v_rcp_f32_e32 v134, v30
	v_add_f32_e32 v0, v224, v136
	v_mul_f32_e32 v0, 0xbfb8aa3b, v0
	v_exp_f32_e32 v30, v0
	v_add_f32_e32 v0, v225, v137
	v_mul_f32_e32 v0, 0xbfb8aa3b, v0
	v_exp_f32_e32 v31, v0
	s_nop 0
	v_pk_add_f32 v[30:31], v[30:31], 1.0 op_sel_hi:[1,0]
	s_nop 0
	s_nop 0
	v_rcp_f32_e32 v137, v31
	s_nop 0
	v_rcp_f32_e32 v136, v30
	v_add_f32_e32 v0, v2, v130
	v_mul_f32_e32 v0, 0xbfb8aa3b, v0
	v_exp_f32_e32 v30, v0
	v_add_f32_e32 v0, v3, v131
	v_mul_f32_e32 v0, 0xbfb8aa3b, v0
	v_exp_f32_e32 v31, v0
	s_nop 0
	v_pk_add_f32 v[30:31], v[30:31], 1.0 op_sel_hi:[1,0]
	s_nop 0
	s_nop 0
	v_rcp_f32_e32 v31, v31
	s_nop 0
	v_rcp_f32_e32 v30, v30
	v_add_f32_e32 v0, v4, v132
	v_mul_f32_e32 v0, 0xbfb8aa3b, v0
	v_exp_f32_e32 v32, v0
	v_add_f32_e32 v0, v5, v133
	v_mul_f32_e32 v0, 0xbfb8aa3b, v0
	v_exp_f32_e32 v33, v0
	v_pk_mul_f32 v[132:133], v[30:31], v[148:149]
	v_pk_add_f32 v[30:31], v[30:31], -1.0 op_sel_hi:[1,0]
	v_pk_add_f32 v[32:33], v[32:33], 1.0 op_sel_hi:[1,0]
	s_nop 0
	v_pk_fma_f32 v[30:31], v[30:31], v[138:139], 1.0 op_sel_hi:[1,1,0]
	v_rcp_f32_e32 v33, v33
	v_pk_mul_f32 v[138:139], v[30:31], v[154:155]
	v_rcp_f32_e32 v32, v32
	v_pk_mul_f32 v[34:35], v[136:137], v[150:151]
	v_pk_mul_f32 v[36:37], v[134:135], v[152:153]
	v_pk_add_f32 v[134:135], v[134:135], -1.0 op_sel_hi:[1,0]
	v_pk_add_f32 v[136:137], v[136:137], -1.0 op_sel_hi:[1,0]
	v_pk_add_f32 v[30:31], v[32:33], -1.0 op_sel_hi:[1,0]
	v_pk_mul_f32 v[130:131], v[32:33], v[146:147]
	v_pk_fma_f32 v[134:135], v[134:135], v[142:143], 1.0 op_sel_hi:[1,1,0]
	v_pk_fma_f32 v[136:137], v[136:137], v[144:145], 1.0 op_sel_hi:[1,1,0]
	v_pk_fma_f32 v[30:31], v[30:31], v[140:141], 1.0 op_sel_hi:[1,1,0]
	v_pk_mul_f32 v[134:135], v[134:135], v[158:159]
	v_pk_mul_f32 v[136:137], v[136:137], v[160:161]
	v_pk_mul_f32 v[140:141], v[30:31], v[156:157]
	v_cvt_pk_bf16_f32 v30, v36, v37
	v_cvt_pk_bf16_f32 v31, v34, v35
	v_cvt_pk_bf16_f32 v32, v132, v133
	v_cvt_pk_bf16_f32 v33, v130, v131
	global_store_dwordx4 v162, v[30:33], s[18:19]
	s_nop 1
	v_cvt_pk_bf16_f32 v30, v134, v135
	v_cvt_pk_bf16_f32 v31, v136, v137
	v_cvt_pk_bf16_f32 v32, v138, v139
	v_cvt_pk_bf16_f32 v33, v140, v141
	global_store_dwordx4 v162, v[30:33], s[16:17]
	s_mov_b64 s[16:17], 0

; #define PG8_STAGE(bufoff, gbase, voff) do { _Pragma("unroll") for (int _i = 0; _i < 2; ++_i) \
;     __builtin_amdgcn_global_load_lds((const unsigned*)((const char*)(gbase) + (voff)[_i]), (LAS unsigned*)(lds + (bufoff) + ldsw + _i * 8192), 16, 0, 0); } while (0)
; #define PG8_LDA(dst, b, h) do { _Pragma("unroll") for (int m = 0; m < 4; ++m) _Pragma("unroll") for (int k = 0; k < 2; ++k) dst[m][k] = *(const LAS bf16x8*)(lds + PG8_SA(b, h) + aoff + m * 2048 + k * 1024); } while (0)
; #define PG8_LDB(dst, b, h) do { _Pragma("unroll") for (int n = 0; n < 2; ++n) _Pragma("unroll") for (int k = 0; k < 2; ++k) dst[n][k] = *(const LAS bf16x8*)(lds + PG8_SB(b, h) + boff + n * 2048 + k * 1024); } while (0)
; #define PG8_MMA(ai, bj, At, Bt) do { __builtin_amdgcn_s_setprio(1); _Pragma("unroll") for (int m = 0; m < 4; ++m) _Pragma("unroll") for (int n = 0; n < 2; ++n) _Pragma("unroll") for (int k = 0; k < 2; ++k) \
;     acc[ai][bj][m][n] = __builtin_amdgcn_mfma_f32_16x16x32_bf16(Bt[n][k], At[m][k], acc[ai][bj][m][n], 0, 0, 0); __builtin_amdgcn_s_setprio(0); } while (0)
; #define PG8_WAIT_V(n) asm volatile("s_waitcnt vmcnt(" #n ")" ::: "memory")
; template <class Epi, class Sched>
; DI void gemm_phase(LAS unsigned char* lds, const Gemm g, const Sched& S, const Epi& E, int wid_k) {
;     ...
;     for (int t = 0; t < nt; t += 2) {
;       const bool last = (t == nt - 2);
;       const char* a1 = cA + (size_t)(t + 1) * kstep;
;       const char* a2 = last ? nA : cA + (size_t)(t + 2) * kstep; const char* b2 = last ? nB : cB + (size_t)(t + 2) * kstep;
;       const char* a3 = a2 + kstep; const char* b3 = b2 + kstep;
;       PG8_LDB(B0, 0, 0); PG8_SCHED; PG8_LDA(At, 0, 0); PG8_STAGE(PG8_SA(1, 1), a1 + hstepA, voffA);
;       PG8_WAIT_L(8); PG8_BAR; PG8_WAIT_L(0); PG8_MMA(0, 0, At, B0); PG8_BAR; PG8_SCHED;
;       PG8_LDB(B1, 0, 1); PG8_STAGE(PG8_SB(0, 0), b2, voffB);
;       PG8_BAR; PG8_WAIT_L(0); PG8_MMA(0, 1, At, B1); PG8_BAR;
;       PG8_LDA(At, 0, 1); PG8_STAGE(PG8_SA(0, 0), a2, voffA);
;       PG8_BAR; PG8_WAIT_L(0); PG8_MMA(1, 0, At, B0); PG8_BAR; PG8_SCHED;
;       PG8_STAGE(PG8_SB(0, 1), b2 + hstepB, voffB);
;       PG8_WAIT_V(6); PG8_BAR; PG8_MMA(1, 1, At, B1); PG8_BAR;
;       PG8_LDB(B0, 1, 0); PG8_SCHED; PG8_LDA(At, 1, 0); PG8_STAGE(PG8_SA(0, 1), a2 + hstepA, voffA);
;       PG8_WAIT_L(8); PG8_BAR; PG8_WAIT_L(0); PG8_MMA(0, 0, At, B0); PG8_BAR; PG8_SCHED;
.LBB0_1720:
	s_add_u32 s18, s16, 0xfffc0080
	s_addc_u32 s19, s17, -1
	s_add_i32 s64, 0, 0x10000
	v_add_u32_e32 v156, s64, v142
	ds_read_b128 v[144:147], v156
	ds_read_b128 v[148:151], v156 offset:1024
	ds_read_b128 v[152:155], v156 offset:2048
	ds_read_b128 v[156:159], v156 offset:3072
	s_cmp_eq_u32 s63, 12
	s_cselect_b32 s21, s11, s19
	s_cselect_b32 s20, s49, s18
	s_cselect_b32 s19, s9, s62
	s_cselect_b32 s18, s60, s61
	v_lshl_add_u64 v[194:195], s[16:17], 0, v[136:137]
	s_add_i32 m0, s7, 0xc000
	ds_read_b128 v[160:163], v143
	ds_read_b128 v[164:167], v143 offset:1024
	ds_read_b128 v[168:171], v143 offset:2048
	ds_read_b128 v[172:175], v143 offset:3072
	ds_read_b128 v[176:179], v143 offset:4096
	ds_read_b128 v[180:183], v143 offset:5120
	ds_read_b128 v[184:187], v143 offset:6144
	ds_read_b128 v[190:193], v143 offset:7168
	global_load_lds_dwordx4 v[194:195], off
	v_lshl_add_u64 v[194:195], s[16:17], 0, v[138:139]
	s_add_i32 m0, s7, 0xe000
	s_nop 0
	global_load_lds_dwordx4 v[194:195], off
	s_waitcnt lgkmcnt(8)
	s_barrier
	s_waitcnt lgkmcnt(0)
	s_setprio 1
	s_waitcnt lgkmcnt(0)
	v_mfma_f32_16x16x32_bf16 v[126:129], v[144:147], v[160:163], v[126:129]
	v_mfma_f32_16x16x32_bf16 v[122:125], v[152:155], v[160:163], v[122:125]
	v_mfma_f32_16x16x32_bf16 v[118:121], v[144:147], v[168:171], v[118:121]
	v_mfma_f32_16x16x32_bf16 v[114:117], v[152:155], v[168:171], v[114:117]
	v_mfma_f32_16x16x32_bf16 v[102:105], v[144:147], v[176:179], v[102:105]
	v_mfma_f32_16x16x32_bf16 v[98:101], v[152:155], v[176:179], v[98:101]
	v_mfma_f32_16x16x32_bf16 v[86:89], v[144:147], v[184:187], v[86:89]
	v_mfma_f32_16x16x32_bf16 v[82:85], v[152:155], v[184:187], v[82:85]
	v_mfma_f32_16x16x32_bf16 v[126:129], v[148:151], v[164:167], v[126:129]
	v_mfma_f32_16x16x32_bf16 v[122:125], v[156:159], v[164:167], v[122:125]
	v_mfma_f32_16x16x32_bf16 v[118:121], v[148:151], v[172:175], v[118:121]
	v_mfma_f32_16x16x32_bf16 v[114:117], v[156:159], v[172:175], v[114:117]
	v_mfma_f32_16x16x32_bf16 v[102:105], v[148:151], v[180:183], v[102:105]
	v_mfma_f32_16x16x32_bf16 v[98:101], v[156:159], v[180:183], v[98:101]
	v_mfma_f32_16x16x32_bf16 v[86:89], v[148:151], v[190:193], v[86:89]
	v_mfma_f32_16x16x32_bf16 v[82:85], v[156:159], v[190:193], v[82:85]
	s_setprio 0
	s_barrier
	s_add_i32 s70, 0, 0x14000
	s_add_i32 s64, s64, s31
	v_add_u32_e32 v206, s70, v142
	v_lshl_add_u64 v[210:211], s[18:19], 0, v[0:1]
	s_mov_b32 m0, s64
	ds_read_b128 v[194:197], v206
	ds_read_b128 v[198:201], v206 offset:1024
	ds_read_b128 v[202:205], v206 offset:2048
	ds_read_b128 v[206:209], v206 offset:3072
	global_load_lds_dwordx4 v[210:211], off
	v_lshl_add_u64 v[212:213], s[18:19], 0, v[134:135]
	s_add_i32 m0, s64, 0x2000
	s_nop 0
	global_load_lds_dwordx4 v[212:213], off
	s_barrier
	s_waitcnt lgkmcnt(0)
	s_setprio 1
	s_waitcnt lgkmcnt(0)
	v_mfma_f32_16x16x32_bf16 v[110:113], v[194:197], v[160:163], v[110:113]
	v_mfma_f32_16x16x32_bf16 v[106:109], v[202:205], v[160:163], v[106:109]
	v_mfma_f32_16x16x32_bf16 v[94:97], v[194:197], v[168:171], v[94:97]
	v_mfma_f32_16x16x32_bf16 v[90:93], v[202:205], v[168:171], v[90:93]
	v_mfma_f32_16x16x32_bf16 v[78:81], v[194:197], v[176:179], v[78:81]
	v_mfma_f32_16x16x32_bf16 v[74:77], v[202:205], v[176:179], v[74:77]
	v_mfma_f32_16x16x32_bf16 v[70:73], v[194:197], v[184:187], v[70:73]
	v_mfma_f32_16x16x32_bf16 v[66:69], v[202:205], v[184:187], v[66:69]
	v_mfma_f32_16x16x32_bf16 v[110:113], v[198:201], v[164:167], v[110:113]
	v_mfma_f32_16x16x32_bf16 v[106:109], v[206:209], v[164:167], v[106:109]
	v_mfma_f32_16x16x32_bf16 v[94:97], v[198:201], v[172:175], v[94:97]
	v_mfma_f32_16x16x32_bf16 v[90:93], v[206:209], v[172:175], v[90:93]
	v_mfma_f32_16x16x32_bf16 v[78:81], v[198:201], v[180:183], v[78:81]
	v_mfma_f32_16x16x32_bf16 v[74:77], v[206:209], v[180:183], v[74:77]
	v_mfma_f32_16x16x32_bf16 v[70:73], v[198:201], v[190:193], v[70:73]
	v_mfma_f32_16x16x32_bf16 v[66:69], v[206:209], v[190:193], v[66:69]
	s_setprio 0
	s_mov_b32 m0, s7
	v_lshl_add_u64 v[214:215], s[20:21], 0, v[130:131]
	s_barrier
	ds_read_b128 v[160:163], v143 offset:16384
	ds_read_b128 v[164:167], v143 offset:17408
	ds_read_b128 v[168:171], v143 offset:18432
	ds_read_b128 v[172:175], v143 offset:19456
	ds_read_b128 v[176:179], v143 offset:20480
	ds_read_b128 v[180:183], v143 offset:21504
	ds_read_b128 v[184:187], v143 offset:22528
	ds_read_b128 v[190:193], v143 offset:23552
	global_load_lds_dwordx4 v[214:215], off
	v_lshl_add_u64 v[216:217], s[20:21], 0, v[132:133]
	s_mov_b32 m0, s34
	s_nop 0
	global_load_lds_dwordx4 v[216:217], off
	s_barrier
	s_waitcnt lgkmcnt(0)
	s_setprio 1
	s_waitcnt lgkmcnt(0)
	v_mfma_f32_16x16x32_bf16 v[62:65], v[144:147], v[160:163], v[62:65]
	v_mfma_f32_16x16x32_bf16 v[58:61], v[152:155], v[160:163], v[58:61]
	v_mfma_f32_16x16x32_bf16 v[54:57], v[144:147], v[168:171], v[54:57]
	v_mfma_f32_16x16x32_bf16 v[50:53], v[152:155], v[168:171], v[50:53]
	v_mfma_f32_16x16x32_bf16 v[38:41], v[144:147], v[176:179], v[38:41]
	v_mfma_f32_16x16x32_bf16 v[34:37], v[152:155], v[176:179], v[34:37]
	v_mfma_f32_16x16x32_bf16 v[22:25], v[144:147], v[184:187], v[22:25]
	v_mfma_f32_16x16x32_bf16 v[18:21], v[152:155], v[184:187], v[18:21]
	v_mfma_f32_16x16x32_bf16 v[62:65], v[148:151], v[164:167], v[62:65]
	v_mfma_f32_16x16x32_bf16 v[58:61], v[156:159], v[164:167], v[58:61]
	v_mfma_f32_16x16x32_bf16 v[54:57], v[148:151], v[172:175], v[54:57]
	v_mfma_f32_16x16x32_bf16 v[50:53], v[156:159], v[172:175], v[50:53]
	v_mfma_f32_16x16x32_bf16 v[38:41], v[148:151], v[180:183], v[38:41]
	v_mfma_f32_16x16x32_bf16 v[34:37], v[156:159], v[180:183], v[34:37]
	v_mfma_f32_16x16x32_bf16 v[22:25], v[148:151], v[190:193], v[22:25]
	v_mfma_f32_16x16x32_bf16 v[18:21], v[156:159], v[190:193], v[18:21]
	s_setprio 0
	s_barrier
; #define PG8_STAGE(bufoff, gbase, voff) do { _Pragma("unroll") for (int _i = 0; _i < 2; ++_i) \
;     __builtin_amdgcn_global_load_lds((const unsigned*)((const char*)(gbase) + (voff)[_i]), (LAS unsigned*)(lds + (bufoff) + ldsw + _i * 8192), 16, 0, 0); } while (0)
; #define PG8_LDA(dst, b, h) do { _Pragma("unroll") for (int m = 0; m < 4; ++m) _Pragma("unroll") for (int k = 0; k < 2; ++k) dst[m][k] = *(const LAS bf16x8*)(lds + PG8_SA(b, h) + aoff + m * 2048 + k * 1024); } while (0)
; #define PG8_LDB(dst, b, h) do { _Pragma("unroll") for (int n = 0; n < 2; ++n) _Pragma("unroll") for (int k = 0; k < 2; ++k) dst[n][k] = *(const LAS bf16x8*)(lds + PG8_SB(b, h) + boff + n * 2048 + k * 1024); } while (0)
; #define PG8_MMA(ai, bj, At, Bt) do { __builtin_amdgcn_s_setprio(1); _Pragma("unroll") for (int m = 0; m < 4; ++m) _Pragma("unroll") for (int n = 0; n < 2; ++n) _Pragma("unroll") for (int k = 0; k < 2; ++k) \
;     acc[ai][bj][m][n] = __builtin_amdgcn_mfma_f32_16x16x32_bf16(Bt[n][k], At[m][k], acc[ai][bj][m][n], 0, 0, 0); __builtin_amdgcn_s_setprio(0); } while (0)
; #define PG8_WAIT_V(n) asm volatile("s_waitcnt vmcnt(" #n ")" ::: "memory")
; #define PG8_WAIT_L(n) asm volatile("s_waitcnt lgkmcnt(" #n ")" ::: "memory")
; #define PG8_BAR __builtin_amdgcn_s_barrier()
; #define PG8_SCHED __builtin_amdgcn_sched_barrier(0)
; template <class Epi, class Sched>
; DI void gemm_phase(LAS unsigned char* lds, const Gemm g, const Sched& S, const Epi& E, int wid_k) {
;     ...
;       PG8_STAGE(PG8_SB(0, 1), b2 + hstepB, voffB);
;       PG8_WAIT_V(6); PG8_BAR; PG8_MMA(1, 1, At, B1); PG8_BAR;
;       PG8_LDB(B0, 1, 0); PG8_SCHED; PG8_LDA(At, 1, 0); PG8_STAGE(PG8_SA(0, 1), a2 + hstepA, voffA);
;       PG8_WAIT_L(8); PG8_BAR; PG8_WAIT_L(0); PG8_MMA(0, 0, At, B0); PG8_BAR; PG8_SCHED;
;       PG8_LDB(B1, 1, 1); PG8_STAGE(PG8_SB(1, 0), b3, voffB);
;       PG8_BAR; PG8_WAIT_L(0); PG8_MMA(0, 1, At, B1); PG8_BAR;
;       PG8_LDA(At, 1, 1); PG8_STAGE(PG8_SA(1, 0), a3, voffA);
;       PG8_BAR; PG8_WAIT_L(0); PG8_MMA(1, 0, At, B0); PG8_BAR; PG8_SCHED;
	s_add_u32 s64, s18, 0x40000
	s_addc_u32 s65, s19, 0
	s_add_i32 s70, s70, s31
	v_lshl_add_u64 v[144:145], s[64:65], 0, v[0:1]
	s_mov_b32 m0, s70
	s_nop 0
	global_load_lds_dwordx4 v[144:145], off
	v_lshl_add_u64 v[144:145], s[64:65], 0, v[134:135]
	s_add_i32 m0, s70, 0x2000
	s_nop 0
	global_load_lds_dwordx4 v[144:145], off
	s_waitcnt vmcnt(6)
	s_barrier
	s_setprio 1
	v_mfma_f32_16x16x32_bf16 v[46:49], v[194:197], v[160:163], v[46:49]
	v_mfma_f32_16x16x32_bf16 v[42:45], v[202:205], v[160:163], v[42:45]
	v_mfma_f32_16x16x32_bf16 v[30:33], v[194:197], v[168:171], v[30:33]
	v_mfma_f32_16x16x32_bf16 v[26:29], v[202:205], v[168:171], v[26:29]
	v_mfma_f32_16x16x32_bf16 v[14:17], v[194:197], v[176:179], v[14:17]
	v_mfma_f32_16x16x32_bf16 v[10:13], v[202:205], v[176:179], v[10:13]
	v_mfma_f32_16x16x32_bf16 v[6:9], v[194:197], v[184:187], v[6:9]
	v_mfma_f32_16x16x32_bf16 v[2:5], v[202:205], v[184:187], v[2:5]
	v_mfma_f32_16x16x32_bf16 v[46:49], v[198:201], v[164:167], v[46:49]
	v_mfma_f32_16x16x32_bf16 v[42:45], v[206:209], v[164:167], v[42:45]
	v_mfma_f32_16x16x32_bf16 v[30:33], v[198:201], v[172:175], v[30:33]
	v_mfma_f32_16x16x32_bf16 v[26:29], v[206:209], v[172:175], v[26:29]
	v_mfma_f32_16x16x32_bf16 v[14:17], v[198:201], v[180:183], v[14:17]
	v_mfma_f32_16x16x32_bf16 v[10:13], v[206:209], v[180:183], v[10:13]
	v_mfma_f32_16x16x32_bf16 v[6:9], v[198:201], v[190:193], v[6:9]
	v_mfma_f32_16x16x32_bf16 v[2:5], v[206:209], v[190:193], v[2:5]
	s_setprio 0
	s_add_i32 s64, 0, 0x18000
	v_add_u32_e32 v156, s64, v142
	s_barrier
	ds_read_b128 v[144:147], v156
	ds_read_b128 v[148:151], v156 offset:1024
	ds_read_b128 v[152:155], v156 offset:2048
	ds_read_b128 v[156:159], v156 offset:3072
	s_add_u32 s20, s20, 0x40000
	s_addc_u32 s21, s21, 0
	s_mov_b32 m0, s35
	v_lshl_add_u64 v[194:195], s[20:21], 0, v[130:131]
	ds_read_b128 v[160:163], v143 offset:32768
	ds_read_b128 v[164:167], v143 offset:33792
	ds_read_b128 v[168:171], v143 offset:34816
	ds_read_b128 v[172:175], v143 offset:35840
	ds_read_b128 v[176:179], v143 offset:36864
	ds_read_b128 v[180:183], v143 offset:37888
	ds_read_b128 v[184:187], v143 offset:38912
	ds_read_b128 v[190:193], v143 offset:39936
	global_load_lds_dwordx4 v[194:195], off
	v_lshl_add_u64 v[194:195], s[20:21], 0, v[132:133]
	s_mov_b32 m0, s36
	s_nop 0
	global_load_lds_dwordx4 v[194:195], off
	s_waitcnt lgkmcnt(8)
	s_barrier
	s_waitcnt lgkmcnt(0)
	s_setprio 1
	s_waitcnt lgkmcnt(0)
	v_mfma_f32_16x16x32_bf16 v[126:129], v[144:147], v[160:163], v[126:129]
	v_mfma_f32_16x16x32_bf16 v[122:125], v[152:155], v[160:163], v[122:125]
	v_mfma_f32_16x16x32_bf16 v[118:121], v[144:147], v[168:171], v[118:121]
	v_mfma_f32_16x16x32_bf16 v[114:117], v[152:155], v[168:171], v[114:117]
	v_mfma_f32_16x16x32_bf16 v[102:105], v[144:147], v[176:179], v[102:105]
	v_mfma_f32_16x16x32_bf16 v[98:101], v[152:155], v[176:179], v[98:101]
	v_mfma_f32_16x16x32_bf16 v[86:89], v[144:147], v[184:187], v[86:89]
	v_mfma_f32_16x16x32_bf16 v[82:85], v[152:155], v[184:187], v[82:85]
	v_mfma_f32_16x16x32_bf16 v[126:129], v[148:151], v[164:167], v[126:129]
	v_mfma_f32_16x16x32_bf16 v[122:125], v[156:159], v[164:167], v[122:125]
	v_mfma_f32_16x16x32_bf16 v[118:121], v[148:151], v[172:175], v[118:121]
	v_mfma_f32_16x16x32_bf16 v[114:117], v[156:159], v[172:175], v[114:117]
	v_mfma_f32_16x16x32_bf16 v[102:105], v[148:151], v[180:183], v[102:105]
	v_mfma_f32_16x16x32_bf16 v[98:101], v[156:159], v[180:183], v[98:101]
	v_mfma_f32_16x16x32_bf16 v[86:89], v[148:151], v[190:193], v[86:89]
	v_mfma_f32_16x16x32_bf16 v[82:85], v[156:159], v[190:193], v[82:85]
	s_setprio 0
	s_barrier
	s_add_i32 s20, 0, 0x1c000
	s_add_i32 s21, s64, s31
	v_add_u32_e32 v206, s20, v142
	v_lshl_add_u64 v[210:211], v[210:211], 0, s[78:79]
	s_mov_b32 m0, s21
	ds_read_b128 v[194:197], v206
	ds_read_b128 v[198:201], v206 offset:1024
	ds_read_b128 v[202:205], v206 offset:2048
	ds_read_b128 v[206:209], v206 offset:3072
	global_load_lds_dwordx4 v[210:211], off
	v_lshl_add_u64 v[210:211], v[212:213], 0, s[78:79]
	s_add_i32 m0, s21, 0x2000
	s_nop 0
	global_load_lds_dwordx4 v[210:211], off
	s_barrier
	s_waitcnt lgkmcnt(0)
	s_setprio 1
	s_waitcnt lgkmcnt(0)
	v_mfma_f32_16x16x32_bf16 v[110:113], v[194:197], v[160:163], v[110:113]
	v_mfma_f32_16x16x32_bf16 v[106:109], v[202:205], v[160:163], v[106:109]
	v_mfma_f32_16x16x32_bf16 v[94:97], v[194:197], v[168:171], v[94:97]
	v_mfma_f32_16x16x32_bf16 v[90:93], v[202:205], v[168:171], v[90:93]
	v_mfma_f32_16x16x32_bf16 v[78:81], v[194:197], v[176:179], v[78:81]
	v_mfma_f32_16x16x32_bf16 v[74:77], v[202:205], v[176:179], v[74:77]
	v_mfma_f32_16x16x32_bf16 v[70:73], v[194:197], v[184:187], v[70:73]
	v_mfma_f32_16x16x32_bf16 v[66:69], v[202:205], v[184:187], v[66:69]
	v_mfma_f32_16x16x32_bf16 v[110:113], v[198:201], v[164:167], v[110:113]
	v_mfma_f32_16x16x32_bf16 v[106:109], v[206:209], v[164:167], v[106:109]
	v_mfma_f32_16x16x32_bf16 v[94:97], v[198:201], v[172:175], v[94:97]
	v_mfma_f32_16x16x32_bf16 v[90:93], v[206:209], v[172:175], v[90:93]
	v_mfma_f32_16x16x32_bf16 v[78:81], v[198:201], v[180:183], v[78:81]
	v_mfma_f32_16x16x32_bf16 v[74:77], v[206:209], v[180:183], v[74:77]
	v_mfma_f32_16x16x32_bf16 v[70:73], v[198:201], v[190:193], v[70:73]
	v_mfma_f32_16x16x32_bf16 v[66:69], v[206:209], v[190:193], v[66:69]
	s_setprio 0
	s_mov_b32 m0, s38
	v_lshl_add_u64 v[210:211], v[214:215], 0, s[78:79]
	s_barrier
	ds_read_b128 v[160:163], v143 offset:49152
	ds_read_b128 v[164:167], v143 offset:50176
	ds_read_b128 v[168:171], v143 offset:51200
	ds_read_b128 v[172:175], v143 offset:52224
	ds_read_b128 v[176:179], v143 offset:53248
	ds_read_b128 v[180:183], v143 offset:54272
	ds_read_b128 v[184:187], v143 offset:55296
	ds_read_b128 v[190:193], v143 offset:56320
	global_load_lds_dwordx4 v[210:211], off
	v_lshl_add_u64 v[210:211], v[216:217], 0, s[78:79]
	s_mov_b32 m0, s39
	s_nop 0
	global_load_lds_dwordx4 v[210:211], off
	s_barrier
; #define PG8_STAGE(bufoff, gbase, voff) do { _Pragma("unroll") for (int _i = 0; _i < 2; ++_i) \
;     __builtin_amdgcn_global_load_lds((const unsigned*)((const char*)(gbase) + (voff)[_i]), (LAS unsigned*)(lds + (bufoff) + ldsw + _i * 8192), 16, 0, 0); } while (0)
; #define PG8_LDA(dst, b, h) do { _Pragma("unroll") for (int m = 0; m < 4; ++m) _Pragma("unroll") for (int k = 0; k < 2; ++k) dst[m][k] = *(const LAS bf16x8*)(lds + PG8_SA(b, h) + aoff + m * 2048 + k * 1024); } while (0)
; #define PG8_MMA(ai, bj, At, Bt) do { __builtin_amdgcn_s_setprio(1); _Pragma("unroll") for (int m = 0; m < 4; ++m) _Pragma("unroll") for (int n = 0; n < 2; ++n) _Pragma("unroll") for (int k = 0; k < 2; ++k) \
;     acc[ai][bj][m][n] = __builtin_amdgcn_mfma_f32_16x16x32_bf16(Bt[n][k], At[m][k], acc[ai][bj][m][n], 0, 0, 0); __builtin_amdgcn_s_setprio(0); } while (0)
; #define PG8_WAIT_V(n) asm volatile("s_waitcnt vmcnt(" #n ")" ::: "memory")
; #define PG8_WAIT_L(n) asm volatile("s_waitcnt lgkmcnt(" #n ")" ::: "memory")
; #define PG8_BAR __builtin_amdgcn_s_barrier()
; #define PG8_SCHED __builtin_amdgcn_sched_barrier(0)
; template <class Epi, class Sched>
; DI void gemm_phase(LAS unsigned char* lds, const Gemm g, const Sched& S, const Epi& E, int wid_k) {
;     ...
;       PG8_BAR; PG8_WAIT_L(0); PG8_MMA(0, 1, At, B1); PG8_BAR;
;       PG8_LDA(At, 1, 1); PG8_STAGE(PG8_SA(1, 0), a3, voffA);
;       PG8_BAR; PG8_WAIT_L(0); PG8_MMA(1, 0, At, B0); PG8_BAR; PG8_SCHED;
;       PG8_STAGE(PG8_SB(1, 1), b3 + hstepB, voffB);
;       PG8_WAIT_V(6); PG8_BAR; PG8_MMA(1, 1, At, B1); PG8_BAR;
	s_waitcnt lgkmcnt(0)
	s_setprio 1
	s_waitcnt lgkmcnt(0)
	v_mfma_f32_16x16x32_bf16 v[62:65], v[144:147], v[160:163], v[62:65]
	v_mfma_f32_16x16x32_bf16 v[58:61], v[152:155], v[160:163], v[58:61]
	v_mfma_f32_16x16x32_bf16 v[54:57], v[144:147], v[168:171], v[54:57]
	v_mfma_f32_16x16x32_bf16 v[50:53], v[152:155], v[168:171], v[50:53]
	v_mfma_f32_16x16x32_bf16 v[38:41], v[144:147], v[176:179], v[38:41]
	v_mfma_f32_16x16x32_bf16 v[34:37], v[152:155], v[176:179], v[34:37]
	v_mfma_f32_16x16x32_bf16 v[22:25], v[144:147], v[184:187], v[22:25]
	v_mfma_f32_16x16x32_bf16 v[18:21], v[152:155], v[184:187], v[18:21]
	v_mfma_f32_16x16x32_bf16 v[62:65], v[148:151], v[164:167], v[62:65]
	v_mfma_f32_16x16x32_bf16 v[58:61], v[156:159], v[164:167], v[58:61]
	v_mfma_f32_16x16x32_bf16 v[54:57], v[148:151], v[172:175], v[54:57]
	v_mfma_f32_16x16x32_bf16 v[50:53], v[156:159], v[172:175], v[50:53]
	v_mfma_f32_16x16x32_bf16 v[38:41], v[148:151], v[180:183], v[38:41]
	v_mfma_f32_16x16x32_bf16 v[34:37], v[156:159], v[180:183], v[34:37]
	v_mfma_f32_16x16x32_bf16 v[22:25], v[148:151], v[190:193], v[22:25]
	v_mfma_f32_16x16x32_bf16 v[18:21], v[156:159], v[190:193], v[18:21]
	s_setprio 0
	s_barrier
	s_add_u32 s18, s18, 0x40080
	s_addc_u32 s19, s19, 0
	s_add_i32 s20, s20, s31
	v_lshl_add_u64 v[144:145], s[18:19], 0, v[0:1]
	s_mov_b32 m0, s20
	s_nop 0
	global_load_lds_dwordx4 v[144:145], off
	v_lshl_add_u64 v[144:145], s[18:19], 0, v[134:135]
	s_add_i32 m0, s20, 0x2000
	s_nop 0
	global_load_lds_dwordx4 v[144:145], off
	s_waitcnt vmcnt(6)
	s_barrier
	s_setprio 1
	v_mfma_f32_16x16x32_bf16 v[46:49], v[194:197], v[160:163], v[46:49]
	v_mfma_f32_16x16x32_bf16 v[42:45], v[202:205], v[160:163], v[42:45]
	v_mfma_f32_16x16x32_bf16 v[30:33], v[194:197], v[168:171], v[30:33]
	v_mfma_f32_16x16x32_bf16 v[26:29], v[202:205], v[168:171], v[26:29]
	v_mfma_f32_16x16x32_bf16 v[14:17], v[194:197], v[176:179], v[14:17]
	v_mfma_f32_16x16x32_bf16 v[10:13], v[202:205], v[176:179], v[10:13]
	v_mfma_f32_16x16x32_bf16 v[6:9], v[194:197], v[184:187], v[6:9]
	v_mfma_f32_16x16x32_bf16 v[2:5], v[202:205], v[184:187], v[2:5]
	v_mfma_f32_16x16x32_bf16 v[46:49], v[198:201], v[164:167], v[46:49]
	v_mfma_f32_16x16x32_bf16 v[42:45], v[206:209], v[164:167], v[42:45]
	v_mfma_f32_16x16x32_bf16 v[30:33], v[198:201], v[172:175], v[30:33]
	v_mfma_f32_16x16x32_bf16 v[26:29], v[206:209], v[172:175], v[26:29]
	v_mfma_f32_16x16x32_bf16 v[14:17], v[198:201], v[180:183], v[14:17]
	v_mfma_f32_16x16x32_bf16 v[10:13], v[206:209], v[180:183], v[10:13]
	v_mfma_f32_16x16x32_bf16 v[6:9], v[198:201], v[190:193], v[6:9]
	v_mfma_f32_16x16x32_bf16 v[2:5], v[206:209], v[190:193], v[2:5]
	s_setprio 0
	s_add_i32 s63, s63, 2
	s_add_u32 s16, s16, 0x100
	s_addc_u32 s17, s17, 0
	s_add_u32 s61, s61, 0x100
	s_addc_u32 s62, s62, 0
	s_cmp_gt_u32 s63, 13
	s_barrier
	s_cbranch_scc0 .LBB0_1720
; DI uint4 pack8(f32x4 a, f32x4 b) { uint4 r; r.x = pack2(a[0], a[1]); r.y = pack2(a[2], a[3]); r.z = pack2(b[0], b[1]); r.w = pack2(b[2], b[3]); return r; }
; template <class Epi, class Sched>
; DI void gemm_phase(LAS unsigned char* lds, const Gemm g, const Sched& S, const Epi& E, int wid_k) {
;     ...
;     { int fr_ = fr, fq_ = fq, wr_ = wr, wc_ = wc; asm volatile("" : "+v"(fr_), "+v"(fq_)); asm volatile("" : "+s"(wr_), "+s"(wc_)); E(acc, cur, wr_, wc_, fr_, fq_); }
;     if (!has_next) break;
;   DI void operator()(const Acc8& acc, const pg8::Unit& u, int wr, int wc, int fr, int fq) const {
; #pragma unroll
;     for (int ai = 0; ai < 2; ++ai)
; #pragma unroll
;       for (int m = 0; m < 4; ++m) {
;         u16* rowp = O + (size_t)EPI_ROWS(ai, m) * ldc;
; #pragma unroll
;         for (int bj = 0; bj < 2; ++bj) {
;           f32x4 v0 = acc[ai][bj][m][0], v1 = acc[ai][bj][m][1];
;           if (ACT == 1) {
; #pragma unroll
;             for (int e = 0; e < 4; ++e) { const float r0 = fmaxf(v0[e], 0.f), r1 = fmaxf(v1[e], 0.f); v0[e] = r0 * r0; v1[e] = r1 * r1; }
;           }
;           *(uint4*)(rowp + EPI_COL8(bj)) = pack8(v0, v1);
;         }
;       }
	v_mov_b32_e32 v144, v141
	v_mov_b32_e32 v145, v140
	s_mov_b32 s9, s30
	s_mov_b32 s11, s37
	s_lshl_b32 s6, s6, 8
	s_lshl_b32 s9, s9, 6
	s_add_i32 s9, s9, s6
	v_add_u32_e32 v144, s9, v144
	s_lshl_b32 s6, s48, 8
	s_lshl_b32 s9, s11, 5
	s_add_i32 s9, s9, s6
	v_cvt_pk_bf16_f32 v70, v70, v71
	v_cvt_pk_bf16_f32 v71, v72, v73
	v_cvt_pk_bf16_f32 v72, v66, v67
	v_add_u32_e32 v66, 0x80, v144
	v_lshl_add_u32 v146, v145, 3, s9
	v_ashrrev_i32_e32 v145, 31, v144
	v_ashrrev_i32_e32 v67, 31, v66
	v_lshlrev_b64 v[148:149], 11, v[144:145]
	v_ashrrev_i32_e32 v147, 31, v146
	v_cvt_pk_bf16_f32 v110, v110, v111
	v_cvt_pk_bf16_f32 v111, v112, v113
	v_cvt_pk_bf16_f32 v112, v106, v107
	v_add_u32_e32 v106, 16, v144
	v_lshlrev_b64 v[66:67], 11, v[66:67]
	v_cvt_pk_bf16_f32 v46, v46, v47
	v_cvt_pk_bf16_f32 v47, v48, v49
	v_cvt_pk_bf16_f32 v48, v42, v43
	v_add_u32_e32 v42, 0x90, v144
	v_lshl_add_u64 v[148:149], s[4:5], 0, v[148:149]
	v_cvt_pk_bf16_f32 v126, v126, v127
	v_cvt_pk_bf16_f32 v127, v128, v129
	v_cvt_pk_bf16_f32 v128, v122, v123
	v_lshlrev_b64 v[122:123], 1, v[146:147]
	v_ashrrev_i32_e32 v107, 31, v106
	v_lshl_add_u64 v[66:67], s[4:5], 0, v[66:67]
	v_ashrrev_i32_e32 v43, 31, v42
	v_cvt_pk_bf16_f32 v129, v124, v125
	v_lshl_add_u64 v[124:125], v[148:149], 0, v[122:123]
	v_cvt_pk_bf16_f32 v113, v108, v109
	v_lshlrev_b64 v[106:107], 11, v[106:107]
	v_cvt_pk_bf16_f32 v94, v94, v95
	v_cvt_pk_bf16_f32 v95, v96, v97
	v_cvt_pk_bf16_f32 v96, v90, v91
	v_add_u32_e32 v90, 32, v144
	v_cvt_pk_bf16_f32 v62, v62, v63
	v_cvt_pk_bf16_f32 v63, v64, v65
	v_cvt_pk_bf16_f32 v64, v58, v59
	v_lshl_add_u64 v[58:59], v[66:67], 0, v[122:123]
	v_cvt_pk_bf16_f32 v49, v44, v45
	v_lshlrev_b64 v[42:43], 11, v[42:43]
	v_cvt_pk_bf16_f32 v30, v30, v31
	v_cvt_pk_bf16_f32 v31, v32, v33
	v_cvt_pk_bf16_f32 v32, v26, v27
	v_add_u32_e32 v26, 0xa0, v144
	global_store_dwordx4 v[124:125], v[110:113], off offset:256 sc1
	v_ashrrev_i32_e32 v91, 31, v90
	global_store_dwordx4 v[58:59], v[46:49], off offset:256 sc1
	v_lshl_add_u64 v[110:111], s[4:5], 0, v[106:107]
	v_ashrrev_i32_e32 v27, 31, v26
	v_lshl_add_u64 v[46:47], s[4:5], 0, v[42:43]
	v_lshl_add_u64 v[110:111], v[110:111], 0, v[122:123]
	v_cvt_pk_bf16_f32 v97, v92, v93
	v_lshlrev_b64 v[90:91], 11, v[90:91]
	v_cvt_pk_bf16_f32 v78, v78, v79
	v_cvt_pk_bf16_f32 v79, v80, v81
	v_cvt_pk_bf16_f32 v80, v74, v75
	v_add_u32_e32 v74, 48, v144
	v_lshl_add_u64 v[46:47], v[46:47], 0, v[122:123]
	v_cvt_pk_bf16_f32 v33, v28, v29
	v_lshlrev_b64 v[26:27], 11, v[26:27]
	v_cvt_pk_bf16_f32 v14, v14, v15
	v_cvt_pk_bf16_f32 v15, v16, v17
	v_cvt_pk_bf16_f32 v16, v10, v11
	v_add_u32_e32 v10, 0xb0, v144
	global_store_dwordx4 v[110:111], v[94:97], off offset:256 sc1
	v_ashrrev_i32_e32 v75, 31, v74
	global_store_dwordx4 v[46:47], v[30:33], off offset:256 sc1
	v_lshl_add_u64 v[94:95], s[4:5], 0, v[90:91]
	v_ashrrev_i32_e32 v11, 31, v10
	v_lshl_add_u64 v[30:31], s[4:5], 0, v[26:27]
	v_lshl_add_u64 v[94:95], v[94:95], 0, v[122:123]
	v_cvt_pk_bf16_f32 v81, v76, v77
	v_lshlrev_b64 v[74:75], 11, v[74:75]
	v_lshl_add_u64 v[30:31], v[30:31], 0, v[122:123]
	v_cvt_pk_bf16_f32 v17, v12, v13
	v_lshlrev_b64 v[10:11], 11, v[10:11]
	global_store_dwordx4 v[94:95], v[78:81], off offset:256 sc1
	global_store_dwordx4 v[30:31], v[14:17], off offset:256 sc1
	v_cvt_pk_bf16_f32 v106, v118, v119
	v_lshl_add_u64 v[78:79], s[4:5], 0, v[74:75]
	v_lshl_add_u64 v[14:15], s[4:5], 0, v[10:11]
	v_cvt_pk_bf16_f32 v107, v120, v121
	v_cvt_pk_bf16_f32 v108, v114, v115
	v_cvt_pk_bf16_f32 v109, v116, v117
	v_cvt_pk_bf16_f32 v90, v102, v103
	v_cvt_pk_bf16_f32 v91, v104, v105
	v_cvt_pk_bf16_f32 v92, v98, v99
	v_cvt_pk_bf16_f32 v93, v100, v101
	v_cvt_pk_bf16_f32 v74, v86, v87
	v_cvt_pk_bf16_f32 v75, v88, v89
	v_cvt_pk_bf16_f32 v76, v82, v83
	v_cvt_pk_bf16_f32 v77, v84, v85
	v_lshl_add_u64 v[78:79], v[78:79], 0, v[122:123]
	v_cvt_pk_bf16_f32 v73, v68, v69
	v_cvt_pk_bf16_f32 v65, v60, v61
	v_cvt_pk_bf16_f32 v42, v54, v55
	v_cvt_pk_bf16_f32 v43, v56, v57
	v_cvt_pk_bf16_f32 v44, v50, v51
	v_cvt_pk_bf16_f32 v45, v52, v53
	v_cvt_pk_bf16_f32 v26, v38, v39
	v_cvt_pk_bf16_f32 v27, v40, v41
	v_cvt_pk_bf16_f32 v28, v34, v35
	v_cvt_pk_bf16_f32 v29, v36, v37
	v_cvt_pk_bf16_f32 v10, v22, v23
	v_cvt_pk_bf16_f32 v11, v24, v25
	v_cvt_pk_bf16_f32 v12, v18, v19
	v_cvt_pk_bf16_f32 v13, v20, v21
	v_lshl_add_u64 v[14:15], v[14:15], 0, v[122:123]
	v_cvt_pk_bf16_f32 v6, v6, v7
	v_cvt_pk_bf16_f32 v7, v8, v9
	v_cvt_pk_bf16_f32 v8, v2, v3
	v_cvt_pk_bf16_f32 v9, v4, v5
	s_and_b64 vcc, exec, s[2:3]
	s_mov_b32 s48, s8
	s_mov_b32 s6, s10
	s_mov_b64 s[18:19], s[14:15]
	s_mov_b64 s[16:17], s[12:13]
	global_store_dwordx4 v[124:125], v[126:129], off sc1
	global_store_dwordx4 v[110:111], v[106:109], off sc1
	global_store_dwordx4 v[94:95], v[90:93], off sc1
	global_store_dwordx4 v[78:79], v[74:77], off sc1
	global_store_dwordx4 v[78:79], v[70:73], off offset:256 sc1
	global_store_dwordx4 v[58:59], v[62:65], off sc1
	global_store_dwordx4 v[46:47], v[42:45], off sc1
	global_store_dwordx4 v[30:31], v[26:29], off sc1
	global_store_dwordx4 v[14:15], v[10:13], off sc1
	global_store_dwordx4 v[14:15], v[6:9], off offset:256 sc1
	s_cbranch_vccz .LBB0_1713
	s_waitcnt vmcnt(0)
	s_cmpk_gt_u32 s24, 0xff
	s_cbranch_scc1 .LBB0_1724
	s_barrier

; #define PG8_STAGE(bufoff, gbase, voff) do { _Pragma("unroll") for (int _i = 0; _i < 2; ++_i) \
;     __builtin_amdgcn_global_load_lds((const unsigned*)((const char*)(gbase) + (voff)[_i]), (LAS unsigned*)(lds + (bufoff) + ldsw + _i * 8192), 16, 0, 0); } while (0)
; #define PG8_LDA(dst, b, h) do { _Pragma("unroll") for (int m = 0; m < 4; ++m) _Pragma("unroll") for (int k = 0; k < 2; ++k) dst[m][k] = *(const LAS bf16x8*)(lds + PG8_SA(b, h) + aoff + m * 2048 + k * 1024); } while (0)
; #define PG8_LDB(dst, b, h) do { _Pragma("unroll") for (int n = 0; n < 2; ++n) _Pragma("unroll") for (int k = 0; k < 2; ++k) dst[n][k] = *(const LAS bf16x8*)(lds + PG8_SB(b, h) + boff + n * 2048 + k * 1024); } while (0)
; #define PG8_MMA(ai, bj, At, Bt) do { __builtin_amdgcn_s_setprio(1); _Pragma("unroll") for (int m = 0; m < 4; ++m) _Pragma("unroll") for (int n = 0; n < 2; ++n) _Pragma("unroll") for (int k = 0; k < 2; ++k) \
;     acc[ai][bj][m][n] = __builtin_amdgcn_mfma_f32_16x16x32_bf16(Bt[n][k], At[m][k], acc[ai][bj][m][n], 0, 0, 0); __builtin_amdgcn_s_setprio(0); } while (0)
; #define PG8_WAIT_V(n) asm volatile("s_waitcnt vmcnt(" #n ")" ::: "memory")
; template <class Epi, class Sched>
; DI void gemm_phase(LAS unsigned char* lds, const Gemm g, const Sched& S, const Epi& E, int wid_k) {
;     ...
;     for (int t = 0; t < nt; t += 2) {
;       const bool last = (t == nt - 2);
;       const char* a1 = cA + (size_t)(t + 1) * kstep;
;       const char* a2 = last ? nA : cA + (size_t)(t + 2) * kstep; const char* b2 = last ? nB : cB + (size_t)(t + 2) * kstep;
;       const char* a3 = a2 + kstep; const char* b3 = b2 + kstep;
;       PG8_LDB(B0, 0, 0); PG8_SCHED; PG8_LDA(At, 0, 0); PG8_STAGE(PG8_SA(1, 1), a1 + hstepA, voffA);
;       PG8_WAIT_L(8); PG8_BAR; PG8_WAIT_L(0); PG8_MMA(0, 0, At, B0); PG8_BAR; PG8_SCHED;
;       PG8_LDB(B1, 0, 1); PG8_STAGE(PG8_SB(0, 0), b2, voffB);
;       PG8_BAR; PG8_WAIT_L(0); PG8_MMA(0, 1, At, B1); PG8_BAR;
;       PG8_LDA(At, 0, 1); PG8_STAGE(PG8_SA(0, 0), a2, voffA);
;       PG8_BAR; PG8_WAIT_L(0); PG8_MMA(1, 0, At, B0); PG8_BAR; PG8_SCHED;
;       PG8_STAGE(PG8_SB(0, 1), b2 + hstepB, voffB);
;       PG8_WAIT_V(6); PG8_BAR; PG8_MMA(1, 1, At, B1); PG8_BAR;
;       PG8_LDB(B0, 1, 0); PG8_SCHED; PG8_LDA(At, 1, 0); PG8_STAGE(PG8_SA(0, 1), a2 + hstepA, voffA);
;       PG8_WAIT_L(8); PG8_BAR; PG8_WAIT_L(0); PG8_MMA(0, 0, At, B0); PG8_BAR; PG8_SCHED;
.LBB0_1847:
	s_add_u32 s18, s16, 0xfffc0080
	s_addc_u32 s19, s17, -1
	s_add_i32 s64, 0, 0x10000
	v_add_u32_e32 v140, s64, v144
	ds_read_b128 v[146:149], v140
	ds_read_b128 v[150:153], v140 offset:1024
	ds_read_b128 v[154:157], v140 offset:2048
	ds_read_b128 v[158:161], v140 offset:3072
	s_cmp_eq_u32 s63, 12
	s_cselect_b32 s21, s9, s19
	s_cselect_b32 s20, s49, s18
	s_cselect_b32 s19, s7, s62
	s_cselect_b32 s18, s60, s61
	v_lshl_add_u64 v[140:141], s[16:17], 0, v[136:137]
	s_add_i32 m0, s15, 0xc000
	ds_read_b128 v[162:165], v145
	ds_read_b128 v[166:169], v145 offset:1024
	ds_read_b128 v[170:173], v145 offset:2048
	ds_read_b128 v[174:177], v145 offset:3072
	ds_read_b128 v[178:181], v145 offset:4096
	ds_read_b128 v[182:185], v145 offset:5120
	ds_read_b128 v[190:193], v145 offset:6144
	ds_read_b128 v[194:197], v145 offset:7168
	global_load_lds_dwordx4 v[140:141], off
	v_lshl_add_u64 v[140:141], s[16:17], 0, v[138:139]
	s_add_i32 m0, s15, 0xe000
	s_nop 0
	global_load_lds_dwordx4 v[140:141], off
	s_waitcnt lgkmcnt(8)
	s_barrier
	s_waitcnt lgkmcnt(0)
	s_setprio 1
	s_waitcnt lgkmcnt(0)
	v_mfma_f32_16x16x32_bf16 v[126:129], v[146:149], v[162:165], v[126:129]
	v_mfma_f32_16x16x32_bf16 v[122:125], v[154:157], v[162:165], v[122:125]
	v_mfma_f32_16x16x32_bf16 v[110:113], v[146:149], v[170:173], v[110:113]
	v_mfma_f32_16x16x32_bf16 v[106:109], v[154:157], v[170:173], v[106:109]
	v_mfma_f32_16x16x32_bf16 v[94:97], v[146:149], v[178:181], v[94:97]
	v_mfma_f32_16x16x32_bf16 v[90:93], v[154:157], v[178:181], v[90:93]
	v_mfma_f32_16x16x32_bf16 v[78:81], v[146:149], v[190:193], v[78:81]
	v_mfma_f32_16x16x32_bf16 v[74:77], v[154:157], v[190:193], v[74:77]
	v_mfma_f32_16x16x32_bf16 v[126:129], v[150:153], v[166:169], v[126:129]
	v_mfma_f32_16x16x32_bf16 v[122:125], v[158:161], v[166:169], v[122:125]
	v_mfma_f32_16x16x32_bf16 v[110:113], v[150:153], v[174:177], v[110:113]
	v_mfma_f32_16x16x32_bf16 v[106:109], v[158:161], v[174:177], v[106:109]
	v_mfma_f32_16x16x32_bf16 v[94:97], v[150:153], v[182:185], v[94:97]
	v_mfma_f32_16x16x32_bf16 v[90:93], v[158:161], v[182:185], v[90:93]
	v_mfma_f32_16x16x32_bf16 v[78:81], v[150:153], v[194:197], v[78:81]
	v_mfma_f32_16x16x32_bf16 v[74:77], v[158:161], v[194:197], v[74:77]
	s_setprio 0
	s_barrier
	s_add_i32 s70, 0, 0x14000
	v_add_u32_e32 v140, s70, v144
	s_add_i32 s64, s64, s31
	ds_read_b128 v[198:201], v140
	ds_read_b128 v[202:205], v140 offset:1024
	ds_read_b128 v[206:209], v140 offset:2048
	ds_read_b128 v[210:213], v140 offset:3072
	v_lshl_add_u64 v[140:141], s[18:19], 0, v[0:1]
	s_mov_b32 m0, s64
	v_lshl_add_u64 v[186:187], s[18:19], 0, v[134:135]
	global_load_lds_dwordx4 v[140:141], off
	s_add_i32 m0, s64, 0x2000
	s_nop 0
	global_load_lds_dwordx4 v[186:187], off
	s_barrier
	s_waitcnt lgkmcnt(0)
	s_setprio 1
	s_waitcnt lgkmcnt(0)
	v_mfma_f32_16x16x32_bf16 v[118:121], v[198:201], v[162:165], v[118:121]
	v_mfma_f32_16x16x32_bf16 v[114:117], v[206:209], v[162:165], v[114:117]
	v_mfma_f32_16x16x32_bf16 v[102:105], v[198:201], v[170:173], v[102:105]
	v_mfma_f32_16x16x32_bf16 v[98:101], v[206:209], v[170:173], v[98:101]
	v_mfma_f32_16x16x32_bf16 v[86:89], v[198:201], v[178:181], v[86:89]
	v_mfma_f32_16x16x32_bf16 v[82:85], v[206:209], v[178:181], v[82:85]
	v_mfma_f32_16x16x32_bf16 v[70:73], v[198:201], v[190:193], v[70:73]
	v_mfma_f32_16x16x32_bf16 v[66:69], v[206:209], v[190:193], v[66:69]
	v_mfma_f32_16x16x32_bf16 v[118:121], v[202:205], v[166:169], v[118:121]
	v_mfma_f32_16x16x32_bf16 v[114:117], v[210:213], v[166:169], v[114:117]
	v_mfma_f32_16x16x32_bf16 v[102:105], v[202:205], v[174:177], v[102:105]
	v_mfma_f32_16x16x32_bf16 v[98:101], v[210:213], v[174:177], v[98:101]
	v_mfma_f32_16x16x32_bf16 v[86:89], v[202:205], v[182:185], v[86:89]
	v_mfma_f32_16x16x32_bf16 v[82:85], v[210:213], v[182:185], v[82:85]
	v_mfma_f32_16x16x32_bf16 v[70:73], v[202:205], v[194:197], v[70:73]
	v_mfma_f32_16x16x32_bf16 v[66:69], v[210:213], v[194:197], v[66:69]
	s_setprio 0
	s_mov_b32 m0, s15
	v_lshl_add_u64 v[214:215], s[20:21], 0, v[130:131]
	s_barrier
	ds_read_b128 v[162:165], v145 offset:16384
	ds_read_b128 v[166:169], v145 offset:17408
	ds_read_b128 v[170:173], v145 offset:18432
	ds_read_b128 v[174:177], v145 offset:19456
	ds_read_b128 v[178:181], v145 offset:20480
	ds_read_b128 v[182:185], v145 offset:21504
	ds_read_b128 v[190:193], v145 offset:22528
	ds_read_b128 v[194:197], v145 offset:23552
	global_load_lds_dwordx4 v[214:215], off
	v_lshl_add_u64 v[216:217], s[20:21], 0, v[132:133]
	s_mov_b32 m0, s34
	s_nop 0
	global_load_lds_dwordx4 v[216:217], off
	s_barrier
	s_waitcnt lgkmcnt(0)
	s_setprio 1
	s_waitcnt lgkmcnt(0)
	v_mfma_f32_16x16x32_bf16 v[62:65], v[146:149], v[162:165], v[62:65]
	v_mfma_f32_16x16x32_bf16 v[58:61], v[154:157], v[162:165], v[58:61]
	v_mfma_f32_16x16x32_bf16 v[46:49], v[146:149], v[170:173], v[46:49]
	v_mfma_f32_16x16x32_bf16 v[42:45], v[154:157], v[170:173], v[42:45]
	v_mfma_f32_16x16x32_bf16 v[30:33], v[146:149], v[178:181], v[30:33]
	v_mfma_f32_16x16x32_bf16 v[26:29], v[154:157], v[178:181], v[26:29]
	v_mfma_f32_16x16x32_bf16 v[14:17], v[146:149], v[190:193], v[14:17]
	v_mfma_f32_16x16x32_bf16 v[10:13], v[154:157], v[190:193], v[10:13]
	v_mfma_f32_16x16x32_bf16 v[62:65], v[150:153], v[166:169], v[62:65]
	v_mfma_f32_16x16x32_bf16 v[58:61], v[158:161], v[166:169], v[58:61]
	v_mfma_f32_16x16x32_bf16 v[46:49], v[150:153], v[174:177], v[46:49]
	v_mfma_f32_16x16x32_bf16 v[42:45], v[158:161], v[174:177], v[42:45]
	v_mfma_f32_16x16x32_bf16 v[30:33], v[150:153], v[182:185], v[30:33]
	v_mfma_f32_16x16x32_bf16 v[26:29], v[158:161], v[182:185], v[26:29]
	v_mfma_f32_16x16x32_bf16 v[14:17], v[150:153], v[194:197], v[14:17]
	v_mfma_f32_16x16x32_bf16 v[10:13], v[158:161], v[194:197], v[10:13]
	s_setprio 0
	s_barrier
; #define PG8_STAGE(bufoff, gbase, voff) do { _Pragma("unroll") for (int _i = 0; _i < 2; ++_i) \
;     __builtin_amdgcn_global_load_lds((const unsigned*)((const char*)(gbase) + (voff)[_i]), (LAS unsigned*)(lds + (bufoff) + ldsw + _i * 8192), 16, 0, 0); } while (0)
; #define PG8_LDA(dst, b, h) do { _Pragma("unroll") for (int m = 0; m < 4; ++m) _Pragma("unroll") for (int k = 0; k < 2; ++k) dst[m][k] = *(const LAS bf16x8*)(lds + PG8_SA(b, h) + aoff + m * 2048 + k * 1024); } while (0)
; #define PG8_LDB(dst, b, h) do { _Pragma("unroll") for (int n = 0; n < 2; ++n) _Pragma("unroll") for (int k = 0; k < 2; ++k) dst[n][k] = *(const LAS bf16x8*)(lds + PG8_SB(b, h) + boff + n * 2048 + k * 1024); } while (0)
; #define PG8_MMA(ai, bj, At, Bt) do { __builtin_amdgcn_s_setprio(1); _Pragma("unroll") for (int m = 0; m < 4; ++m) _Pragma("unroll") for (int n = 0; n < 2; ++n) _Pragma("unroll") for (int k = 0; k < 2; ++k) \
;     acc[ai][bj][m][n] = __builtin_amdgcn_mfma_f32_16x16x32_bf16(Bt[n][k], At[m][k], acc[ai][bj][m][n], 0, 0, 0); __builtin_amdgcn_s_setprio(0); } while (0)
; #define PG8_WAIT_V(n) asm volatile("s_waitcnt vmcnt(" #n ")" ::: "memory")
; #define PG8_WAIT_L(n) asm volatile("s_waitcnt lgkmcnt(" #n ")" ::: "memory")
; #define PG8_BAR __builtin_amdgcn_s_barrier()
; #define PG8_SCHED __builtin_amdgcn_sched_barrier(0)
; template <class Epi, class Sched>
; DI void gemm_phase(LAS unsigned char* lds, const Gemm g, const Sched& S, const Epi& E, int wid_k) {
;     ...
;       PG8_STAGE(PG8_SB(0, 1), b2 + hstepB, voffB);
;       PG8_WAIT_V(6); PG8_BAR; PG8_MMA(1, 1, At, B1); PG8_BAR;
;       PG8_LDB(B0, 1, 0); PG8_SCHED; PG8_LDA(At, 1, 0); PG8_STAGE(PG8_SA(0, 1), a2 + hstepA, voffA);
;       PG8_WAIT_L(8); PG8_BAR; PG8_WAIT_L(0); PG8_MMA(0, 0, At, B0); PG8_BAR; PG8_SCHED;
;       PG8_LDB(B1, 1, 1); PG8_STAGE(PG8_SB(1, 0), b3, voffB);
;       PG8_BAR; PG8_WAIT_L(0); PG8_MMA(0, 1, At, B1); PG8_BAR;
;       PG8_LDA(At, 1, 1); PG8_STAGE(PG8_SA(1, 0), a3, voffA);
;       PG8_BAR; PG8_WAIT_L(0); PG8_MMA(1, 0, At, B0); PG8_BAR; PG8_SCHED;
	s_add_u32 s64, s18, 0x40000
	s_addc_u32 s65, s19, 0
	s_add_i32 s70, s70, s31
	v_lshl_add_u64 v[146:147], s[64:65], 0, v[0:1]
	s_mov_b32 m0, s70
	s_nop 0
	global_load_lds_dwordx4 v[146:147], off
	v_lshl_add_u64 v[146:147], s[64:65], 0, v[134:135]
	s_add_i32 m0, s70, 0x2000
	s_nop 0
	global_load_lds_dwordx4 v[146:147], off
	s_waitcnt vmcnt(6)
	s_barrier
	s_setprio 1
	v_mfma_f32_16x16x32_bf16 v[54:57], v[198:201], v[162:165], v[54:57]
	v_mfma_f32_16x16x32_bf16 v[50:53], v[206:209], v[162:165], v[50:53]
	v_mfma_f32_16x16x32_bf16 v[38:41], v[198:201], v[170:173], v[38:41]
	v_mfma_f32_16x16x32_bf16 v[34:37], v[206:209], v[170:173], v[34:37]
	v_mfma_f32_16x16x32_bf16 v[22:25], v[198:201], v[178:181], v[22:25]
	v_mfma_f32_16x16x32_bf16 v[18:21], v[206:209], v[178:181], v[18:21]
	v_mfma_f32_16x16x32_bf16 v[6:9], v[198:201], v[190:193], v[6:9]
	v_mfma_f32_16x16x32_bf16 v[2:5], v[206:209], v[190:193], v[2:5]
	v_mfma_f32_16x16x32_bf16 v[54:57], v[202:205], v[166:169], v[54:57]
	v_mfma_f32_16x16x32_bf16 v[50:53], v[210:213], v[166:169], v[50:53]
	v_mfma_f32_16x16x32_bf16 v[38:41], v[202:205], v[174:177], v[38:41]
	v_mfma_f32_16x16x32_bf16 v[34:37], v[210:213], v[174:177], v[34:37]
	v_mfma_f32_16x16x32_bf16 v[22:25], v[202:205], v[182:185], v[22:25]
	v_mfma_f32_16x16x32_bf16 v[18:21], v[210:213], v[182:185], v[18:21]
	v_mfma_f32_16x16x32_bf16 v[6:9], v[202:205], v[194:197], v[6:9]
	v_mfma_f32_16x16x32_bf16 v[2:5], v[210:213], v[194:197], v[2:5]
	s_setprio 0
	s_add_i32 s64, 0, 0x18000
	v_add_u32_e32 v158, s64, v144
	s_barrier
	ds_read_b128 v[146:149], v158
	ds_read_b128 v[150:153], v158 offset:1024
	ds_read_b128 v[154:157], v158 offset:2048
	ds_read_b128 v[158:161], v158 offset:3072
	s_add_u32 s20, s20, 0x40000
	s_addc_u32 s21, s21, 0
	s_mov_b32 m0, s35
	v_lshl_add_u64 v[198:199], s[20:21], 0, v[130:131]
	ds_read_b128 v[162:165], v145 offset:32768
	ds_read_b128 v[166:169], v145 offset:33792
	ds_read_b128 v[170:173], v145 offset:34816
	ds_read_b128 v[174:177], v145 offset:35840
	ds_read_b128 v[178:181], v145 offset:36864
	ds_read_b128 v[182:185], v145 offset:37888
	ds_read_b128 v[190:193], v145 offset:38912
	ds_read_b128 v[194:197], v145 offset:39936
	global_load_lds_dwordx4 v[198:199], off
	v_lshl_add_u64 v[198:199], s[20:21], 0, v[132:133]
	s_mov_b32 m0, s36
	s_nop 0
	global_load_lds_dwordx4 v[198:199], off
	s_waitcnt lgkmcnt(8)
	s_barrier
	s_waitcnt lgkmcnt(0)
	s_setprio 1
	s_waitcnt lgkmcnt(0)
	v_mfma_f32_16x16x32_bf16 v[126:129], v[146:149], v[162:165], v[126:129]
	v_mfma_f32_16x16x32_bf16 v[122:125], v[154:157], v[162:165], v[122:125]
	v_mfma_f32_16x16x32_bf16 v[110:113], v[146:149], v[170:173], v[110:113]
	v_mfma_f32_16x16x32_bf16 v[106:109], v[154:157], v[170:173], v[106:109]
	v_mfma_f32_16x16x32_bf16 v[94:97], v[146:149], v[178:181], v[94:97]
	v_mfma_f32_16x16x32_bf16 v[90:93], v[154:157], v[178:181], v[90:93]
	v_mfma_f32_16x16x32_bf16 v[78:81], v[146:149], v[190:193], v[78:81]
	v_mfma_f32_16x16x32_bf16 v[74:77], v[154:157], v[190:193], v[74:77]
	v_mfma_f32_16x16x32_bf16 v[126:129], v[150:153], v[166:169], v[126:129]
	v_mfma_f32_16x16x32_bf16 v[122:125], v[158:161], v[166:169], v[122:125]
	v_mfma_f32_16x16x32_bf16 v[110:113], v[150:153], v[174:177], v[110:113]
	v_mfma_f32_16x16x32_bf16 v[106:109], v[158:161], v[174:177], v[106:109]
	v_mfma_f32_16x16x32_bf16 v[94:97], v[150:153], v[182:185], v[94:97]
	v_mfma_f32_16x16x32_bf16 v[90:93], v[158:161], v[182:185], v[90:93]
	v_mfma_f32_16x16x32_bf16 v[78:81], v[150:153], v[194:197], v[78:81]
	v_mfma_f32_16x16x32_bf16 v[74:77], v[158:161], v[194:197], v[74:77]
	s_setprio 0
	s_barrier
	s_add_i32 s20, 0, 0x1c000
	s_add_i32 s21, s64, s31
	v_add_u32_e32 v210, s20, v144
	v_lshl_add_u64 v[140:141], v[140:141], 0, s[78:79]
	s_mov_b32 m0, s21
	ds_read_b128 v[198:201], v210
	ds_read_b128 v[202:205], v210 offset:1024
	ds_read_b128 v[206:209], v210 offset:2048
	ds_read_b128 v[210:213], v210 offset:3072
	global_load_lds_dwordx4 v[140:141], off
	v_lshl_add_u64 v[140:141], v[186:187], 0, s[78:79]
	s_add_i32 m0, s21, 0x2000
	s_nop 0
	global_load_lds_dwordx4 v[140:141], off
	s_barrier
	s_waitcnt lgkmcnt(0)
	s_setprio 1
	s_waitcnt lgkmcnt(0)
	v_mfma_f32_16x16x32_bf16 v[118:121], v[198:201], v[162:165], v[118:121]
	v_mfma_f32_16x16x32_bf16 v[114:117], v[206:209], v[162:165], v[114:117]
	v_mfma_f32_16x16x32_bf16 v[102:105], v[198:201], v[170:173], v[102:105]
	v_mfma_f32_16x16x32_bf16 v[98:101], v[206:209], v[170:173], v[98:101]
	v_mfma_f32_16x16x32_bf16 v[86:89], v[198:201], v[178:181], v[86:89]
	v_mfma_f32_16x16x32_bf16 v[82:85], v[206:209], v[178:181], v[82:85]
	v_mfma_f32_16x16x32_bf16 v[70:73], v[198:201], v[190:193], v[70:73]
	v_mfma_f32_16x16x32_bf16 v[66:69], v[206:209], v[190:193], v[66:69]
	v_mfma_f32_16x16x32_bf16 v[118:121], v[202:205], v[166:169], v[118:121]
	v_mfma_f32_16x16x32_bf16 v[114:117], v[210:213], v[166:169], v[114:117]
	v_mfma_f32_16x16x32_bf16 v[102:105], v[202:205], v[174:177], v[102:105]
	v_mfma_f32_16x16x32_bf16 v[98:101], v[210:213], v[174:177], v[98:101]
	v_mfma_f32_16x16x32_bf16 v[86:89], v[202:205], v[182:185], v[86:89]
	v_mfma_f32_16x16x32_bf16 v[82:85], v[210:213], v[182:185], v[82:85]
	v_mfma_f32_16x16x32_bf16 v[70:73], v[202:205], v[194:197], v[70:73]
	v_mfma_f32_16x16x32_bf16 v[66:69], v[210:213], v[194:197], v[66:69]
	s_setprio 0
	s_mov_b32 m0, s38
	v_lshl_add_u64 v[140:141], v[214:215], 0, s[78:79]
	s_barrier
	ds_read_b128 v[162:165], v145 offset:49152
	ds_read_b128 v[166:169], v145 offset:50176
	ds_read_b128 v[170:173], v145 offset:51200
	ds_read_b128 v[174:177], v145 offset:52224
	ds_read_b128 v[178:181], v145 offset:53248
	ds_read_b128 v[182:185], v145 offset:54272
	ds_read_b128 v[190:193], v145 offset:55296
	ds_read_b128 v[194:197], v145 offset:56320
	global_load_lds_dwordx4 v[140:141], off
	v_lshl_add_u64 v[140:141], v[216:217], 0, s[78:79]
	s_mov_b32 m0, s39
	s_nop 0
	global_load_lds_dwordx4 v[140:141], off
	s_barrier
; DI uint4 pack8(f32x4 a, f32x4 b) { uint4 r; r.x = pack2(a[0], a[1]); r.y = pack2(a[2], a[3]); r.z = pack2(b[0], b[1]); r.w = pack2(b[2], b[3]); return r; }
; #define PG8_STAGE(bufoff, gbase, voff) do { _Pragma("unroll") for (int _i = 0; _i < 2; ++_i) \
;     __builtin_amdgcn_global_load_lds((const unsigned*)((const char*)(gbase) + (voff)[_i]), (LAS unsigned*)(lds + (bufoff) + ldsw + _i * 8192), 16, 0, 0); } while (0)
; #define PG8_LDA(dst, b, h) do { _Pragma("unroll") for (int m = 0; m < 4; ++m) _Pragma("unroll") for (int k = 0; k < 2; ++k) dst[m][k] = *(const LAS bf16x8*)(lds + PG8_SA(b, h) + aoff + m * 2048 + k * 1024); } while (0)
; #define PG8_MMA(ai, bj, At, Bt) do { __builtin_amdgcn_s_setprio(1); _Pragma("unroll") for (int m = 0; m < 4; ++m) _Pragma("unroll") for (int n = 0; n < 2; ++n) _Pragma("unroll") for (int k = 0; k < 2; ++k) \
;     acc[ai][bj][m][n] = __builtin_amdgcn_mfma_f32_16x16x32_bf16(Bt[n][k], At[m][k], acc[ai][bj][m][n], 0, 0, 0); __builtin_amdgcn_s_setprio(0); } while (0)
; #define PG8_WAIT_V(n) asm volatile("s_waitcnt vmcnt(" #n ")" ::: "memory")
; #define PG8_WAIT_L(n) asm volatile("s_waitcnt lgkmcnt(" #n ")" ::: "memory")
; #define PG8_BAR __builtin_amdgcn_s_barrier()
; #define PG8_SCHED __builtin_amdgcn_sched_barrier(0)
; template <class Epi, class Sched>
; DI void gemm_phase(LAS unsigned char* lds, const Gemm g, const Sched& S, const Epi& E, int wid_k) {
;     ...
;       PG8_BAR; PG8_WAIT_L(0); PG8_MMA(0, 1, At, B1); PG8_BAR;
;       PG8_LDA(At, 1, 1); PG8_STAGE(PG8_SA(1, 0), a3, voffA);
;       PG8_BAR; PG8_WAIT_L(0); PG8_MMA(1, 0, At, B0); PG8_BAR; PG8_SCHED;
;       PG8_STAGE(PG8_SB(1, 1), b3 + hstepB, voffB);
;       PG8_WAIT_V(6); PG8_BAR; PG8_MMA(1, 1, At, B1); PG8_BAR;
;   DI void operator()(const Acc8& acc, const pg8::Unit& u, int wr, int wc, int fr, int fq) const {
; #pragma unroll
;     for (int ai = 0; ai < 2; ++ai)
; #pragma unroll
;       for (int m = 0; m < 4; ++m) {
;         u16* rowp = O + (size_t)EPI_ROWS(ai, m) * ldc;
; #pragma unroll
;         for (int bj = 0; bj < 2; ++bj) {
;           f32x4 v0 = acc[ai][bj][m][0], v1 = acc[ai][bj][m][1];
;           if (ACT == 1) {
; #pragma unroll
;             for (int e = 0; e < 4; ++e) { const float r0 = fmaxf(v0[e], 0.f), r1 = fmaxf(v1[e], 0.f); v0[e] = r0 * r0; v1[e] = r1 * r1; }
;           }
;           *(uint4*)(rowp + EPI_COL8(bj)) = pack8(v0, v1);
;         }
;       }
	s_waitcnt lgkmcnt(0)
	s_setprio 1
	s_waitcnt lgkmcnt(0)
	v_mfma_f32_16x16x32_bf16 v[62:65], v[146:149], v[162:165], v[62:65]
	v_mfma_f32_16x16x32_bf16 v[58:61], v[154:157], v[162:165], v[58:61]
	v_mfma_f32_16x16x32_bf16 v[46:49], v[146:149], v[170:173], v[46:49]
	v_mfma_f32_16x16x32_bf16 v[42:45], v[154:157], v[170:173], v[42:45]
	v_mfma_f32_16x16x32_bf16 v[30:33], v[146:149], v[178:181], v[30:33]
	v_mfma_f32_16x16x32_bf16 v[26:29], v[154:157], v[178:181], v[26:29]
	v_mfma_f32_16x16x32_bf16 v[14:17], v[146:149], v[190:193], v[14:17]
	v_mfma_f32_16x16x32_bf16 v[10:13], v[154:157], v[190:193], v[10:13]
	v_mfma_f32_16x16x32_bf16 v[62:65], v[150:153], v[166:169], v[62:65]
	v_mfma_f32_16x16x32_bf16 v[58:61], v[158:161], v[166:169], v[58:61]
	v_mfma_f32_16x16x32_bf16 v[46:49], v[150:153], v[174:177], v[46:49]
	v_mfma_f32_16x16x32_bf16 v[42:45], v[158:161], v[174:177], v[42:45]
	v_mfma_f32_16x16x32_bf16 v[30:33], v[150:153], v[182:185], v[30:33]
	v_mfma_f32_16x16x32_bf16 v[26:29], v[158:161], v[182:185], v[26:29]
	v_mfma_f32_16x16x32_bf16 v[14:17], v[150:153], v[194:197], v[14:17]
	v_mfma_f32_16x16x32_bf16 v[10:13], v[158:161], v[194:197], v[10:13]
	s_setprio 0
	s_barrier
	s_add_u32 s18, s18, 0x40080
	s_addc_u32 s19, s19, 0
	s_add_i32 s20, s20, s31
	v_lshl_add_u64 v[140:141], s[18:19], 0, v[0:1]
	s_mov_b32 m0, s20
	s_nop 0
	global_load_lds_dwordx4 v[140:141], off
	v_lshl_add_u64 v[140:141], s[18:19], 0, v[134:135]
	s_add_i32 m0, s20, 0x2000
	s_nop 0
	global_load_lds_dwordx4 v[140:141], off
	s_waitcnt vmcnt(6)
	s_barrier
	s_setprio 1
	v_mfma_f32_16x16x32_bf16 v[54:57], v[198:201], v[162:165], v[54:57]
	v_mfma_f32_16x16x32_bf16 v[50:53], v[206:209], v[162:165], v[50:53]
	v_mfma_f32_16x16x32_bf16 v[38:41], v[198:201], v[170:173], v[38:41]
	v_mfma_f32_16x16x32_bf16 v[34:37], v[206:209], v[170:173], v[34:37]
	v_mfma_f32_16x16x32_bf16 v[22:25], v[198:201], v[178:181], v[22:25]
	v_mfma_f32_16x16x32_bf16 v[18:21], v[206:209], v[178:181], v[18:21]
	v_mfma_f32_16x16x32_bf16 v[6:9], v[198:201], v[190:193], v[6:9]
	v_mfma_f32_16x16x32_bf16 v[2:5], v[206:209], v[190:193], v[2:5]
	v_mfma_f32_16x16x32_bf16 v[54:57], v[202:205], v[166:169], v[54:57]
	v_mfma_f32_16x16x32_bf16 v[50:53], v[210:213], v[166:169], v[50:53]
	v_mfma_f32_16x16x32_bf16 v[38:41], v[202:205], v[174:177], v[38:41]
	v_mfma_f32_16x16x32_bf16 v[34:37], v[210:213], v[174:177], v[34:37]
	v_mfma_f32_16x16x32_bf16 v[22:25], v[202:205], v[182:185], v[22:25]
	v_mfma_f32_16x16x32_bf16 v[18:21], v[210:213], v[182:185], v[18:21]
	v_mfma_f32_16x16x32_bf16 v[6:9], v[202:205], v[194:197], v[6:9]
	v_mfma_f32_16x16x32_bf16 v[2:5], v[210:213], v[194:197], v[2:5]
	s_setprio 0
	s_add_i32 s63, s63, 2
	s_add_u32 s16, s16, 0x100
	s_addc_u32 s17, s17, 0
	s_add_u32 s61, s61, 0x100
	s_addc_u32 s62, s62, 0
	s_cmp_gt_u32 s63, 13
	s_barrier
	s_cbranch_scc0 .LBB0_1847
	v_mov_b32_e32 v141, v143
	v_mov_b32_e32 v140, v142
	s_mov_b32 s7, s37
	s_mov_b32 s9, s30
	s_lshl_b32 s14, s14, 8
	s_lshl_b32 s9, s9, 6
	s_add_i32 s9, s9, s14
	v_add_u32_e32 v140, s9, v140
	s_lshl_b32 s9, s48, 8
	s_lshl_b32 s7, s7, 5
	s_add_i32 s7, s7, s9
	v_max_f32_e32 v126, v126, v126
	v_max_f32_e32 v122, v122, v122
	v_max_f32_e32 v127, v127, v127
	v_max_f32_e32 v123, v123, v123
	v_lshl_add_u32 v146, v141, 3, s7
	v_ashrrev_i32_e32 v141, 31, v140
	v_max_f32_e32 v126, 0, v126
	v_max_f32_e32 v122, 0, v122
	v_max_f32_e32 v127, 0, v127
	v_max_f32_e32 v123, 0, v123
	v_max_f32_e32 v128, v128, v128
	v_max_f32_e32 v124, v124, v124
	v_max_f32_e32 v129, v129, v129
	v_max_f32_e32 v125, v125, v125
	v_lshlrev_b64 v[148:149], 13, v[140:141]
	v_pk_mul_f32 v[126:127], v[126:127], v[126:127]
	v_pk_mul_f32 v[122:123], v[122:123], v[122:123]
	v_max_f32_e32 v128, 0, v128
	v_max_f32_e32 v124, 0, v124
	v_max_f32_e32 v129, 0, v129
	v_max_f32_e32 v125, 0, v125
	v_ashrrev_i32_e32 v147, 31, v146
	v_lshl_add_u64 v[148:149], s[4:5], 0, v[148:149]
	v_pk_mul_f32 v[128:129], v[128:129], v[128:129]
	v_pk_mul_f32 v[150:151], v[124:125], v[124:125]
	v_cvt_pk_bf16_f32 v124, v126, v127
	v_cvt_pk_bf16_f32 v126, v122, v123
	v_lshlrev_b64 v[122:123], 1, v[146:147]
	v_max_f32_e32 v114, v114, v114
	v_max_f32_e32 v115, v115, v115
	v_cvt_pk_bf16_f32 v125, v128, v129
	v_cvt_pk_bf16_f32 v127, v150, v151
	v_lshl_add_u64 v[128:129], v[148:149], 0, v[122:123]
	v_max_f32_e32 v114, 0, v114
	v_max_f32_e32 v115, 0, v115
	global_store_dwordx4 v[128:129], v[124:127], off sc1
	v_max_f32_e32 v118, v118, v118
	v_max_f32_e32 v119, v119, v119
	v_pk_mul_f32 v[124:125], v[114:115], v[114:115]
	v_max_f32_e32 v115, v116, v116
	v_max_f32_e32 v114, v120, v120
	v_max_f32_e32 v116, 0, v115
	v_max_f32_e32 v115, v121, v121
	v_max_f32_e32 v117, v117, v117
	v_max_f32_e32 v118, 0, v118
	v_max_f32_e32 v119, 0, v119
	v_max_f32_e32 v114, 0, v114
	v_max_f32_e32 v115, 0, v115
	v_max_f32_e32 v117, 0, v117
	v_pk_mul_f32 v[118:119], v[118:119], v[118:119]
	v_pk_mul_f32 v[120:121], v[114:115], v[114:115]
	v_pk_mul_f32 v[126:127], v[116:117], v[116:117]
	v_max_f32_e32 v106, v106, v106
	v_max_f32_e32 v107, v107, v107
	v_cvt_pk_bf16_f32 v114, v118, v119
	v_cvt_pk_bf16_f32 v115, v120, v121
	v_cvt_pk_bf16_f32 v116, v124, v125
	v_cvt_pk_bf16_f32 v117, v126, v127
	v_max_f32_e32 v106, 0, v106
	v_max_f32_e32 v107, 0, v107
	global_store_dwordx4 v[128:129], v[114:117], off offset:256 sc1
	v_max_f32_e32 v110, v110, v110
	v_max_f32_e32 v111, v111, v111
	v_add_u32_e32 v114, 16, v140
	v_pk_mul_f32 v[116:117], v[106:107], v[106:107]
	v_max_f32_e32 v107, v108, v108
	v_ashrrev_i32_e32 v115, 31, v114
	v_max_f32_e32 v106, v112, v112
	v_max_f32_e32 v108, 0, v107
	v_max_f32_e32 v107, v113, v113
	v_max_f32_e32 v109, v109, v109
	v_lshlrev_b64 v[114:115], 13, v[114:115]
; DI uint4 pack8(f32x4 a, f32x4 b) { uint4 r; r.x = pack2(a[0], a[1]); r.y = pack2(a[2], a[3]); r.z = pack2(b[0], b[1]); r.w = pack2(b[2], b[3]); return r; }
;   DI void operator()(const Acc8& acc, const pg8::Unit& u, int wr, int wc, int fr, int fq) const {
; #pragma unroll
;     for (int ai = 0; ai < 2; ++ai)
; #pragma unroll
;       for (int m = 0; m < 4; ++m) {
;         u16* rowp = O + (size_t)EPI_ROWS(ai, m) * ldc;
; #pragma unroll
;         for (int bj = 0; bj < 2; ++bj) {
;           f32x4 v0 = acc[ai][bj][m][0], v1 = acc[ai][bj][m][1];
;           if (ACT == 1) {
; #pragma unroll
;             for (int e = 0; e < 4; ++e) { const float r0 = fmaxf(v0[e], 0.f), r1 = fmaxf(v1[e], 0.f); v0[e] = r0 * r0; v1[e] = r1 * r1; }
;           }
;           *(uint4*)(rowp + EPI_COL8(bj)) = pack8(v0, v1);
;         }
;       }
	v_max_f32_e32 v110, 0, v110
	v_max_f32_e32 v111, 0, v111
	v_max_f32_e32 v106, 0, v106
	v_max_f32_e32 v107, 0, v107
	v_max_f32_e32 v109, 0, v109
	v_lshl_add_u64 v[114:115], s[4:5], 0, v[114:115]
	v_pk_mul_f32 v[110:111], v[110:111], v[110:111]
	v_pk_mul_f32 v[112:113], v[106:107], v[106:107]
	v_pk_mul_f32 v[118:119], v[108:109], v[108:109]
	v_max_f32_e32 v98, v98, v98
	v_max_f32_e32 v99, v99, v99
	v_cvt_pk_bf16_f32 v106, v110, v111
	v_cvt_pk_bf16_f32 v107, v112, v113
	v_cvt_pk_bf16_f32 v108, v116, v117
	v_cvt_pk_bf16_f32 v109, v118, v119
	v_lshl_add_u64 v[110:111], v[114:115], 0, v[122:123]
	v_max_f32_e32 v98, 0, v98
	v_max_f32_e32 v99, 0, v99
	global_store_dwordx4 v[110:111], v[106:109], off sc1
	v_max_f32_e32 v102, v102, v102
	v_max_f32_e32 v103, v103, v103
	v_pk_mul_f32 v[106:107], v[98:99], v[98:99]
	v_max_f32_e32 v99, v100, v100
	v_max_f32_e32 v98, v104, v104
	v_max_f32_e32 v100, 0, v99
	v_max_f32_e32 v99, v105, v105
	v_max_f32_e32 v101, v101, v101
	v_max_f32_e32 v102, 0, v102
	v_max_f32_e32 v103, 0, v103
	v_max_f32_e32 v98, 0, v98
	v_max_f32_e32 v99, 0, v99
	v_max_f32_e32 v101, 0, v101
	v_pk_mul_f32 v[102:103], v[102:103], v[102:103]
	v_pk_mul_f32 v[104:105], v[98:99], v[98:99]
	v_pk_mul_f32 v[108:109], v[100:101], v[100:101]
	v_max_f32_e32 v90, v90, v90
	v_max_f32_e32 v91, v91, v91
	v_cvt_pk_bf16_f32 v98, v102, v103
	v_cvt_pk_bf16_f32 v99, v104, v105
	v_cvt_pk_bf16_f32 v100, v106, v107
	v_cvt_pk_bf16_f32 v101, v108, v109
	v_max_f32_e32 v90, 0, v90
	v_max_f32_e32 v91, 0, v91
	global_store_dwordx4 v[110:111], v[98:101], off offset:256 sc1
	v_max_f32_e32 v94, v94, v94
	v_max_f32_e32 v95, v95, v95
	v_add_u32_e32 v98, 32, v140
	v_pk_mul_f32 v[100:101], v[90:91], v[90:91]
	v_max_f32_e32 v91, v92, v92
	v_ashrrev_i32_e32 v99, 31, v98
	v_max_f32_e32 v90, v96, v96
	v_max_f32_e32 v92, 0, v91
	v_max_f32_e32 v91, v97, v97
	v_max_f32_e32 v93, v93, v93
	v_lshlrev_b64 v[98:99], 13, v[98:99]
	v_max_f32_e32 v94, 0, v94
	v_max_f32_e32 v95, 0, v95
	v_max_f32_e32 v90, 0, v90
	v_max_f32_e32 v91, 0, v91
	v_max_f32_e32 v93, 0, v93
	v_lshl_add_u64 v[98:99], s[4:5], 0, v[98:99]
	v_pk_mul_f32 v[94:95], v[94:95], v[94:95]
	v_pk_mul_f32 v[96:97], v[90:91], v[90:91]
	v_pk_mul_f32 v[102:103], v[92:93], v[92:93]
	v_max_f32_e32 v82, v82, v82
	v_max_f32_e32 v83, v83, v83
	v_cvt_pk_bf16_f32 v90, v94, v95
	v_cvt_pk_bf16_f32 v91, v96, v97
	v_cvt_pk_bf16_f32 v92, v100, v101
	v_cvt_pk_bf16_f32 v93, v102, v103
	v_lshl_add_u64 v[94:95], v[98:99], 0, v[122:123]
	v_max_f32_e32 v82, 0, v82
	v_max_f32_e32 v83, 0, v83
	global_store_dwordx4 v[94:95], v[90:93], off sc1
	v_max_f32_e32 v86, v86, v86
	v_max_f32_e32 v87, v87, v87
	v_pk_mul_f32 v[90:91], v[82:83], v[82:83]
	v_max_f32_e32 v83, v84, v84
	v_max_f32_e32 v82, v88, v88
	v_max_f32_e32 v84, 0, v83
	v_max_f32_e32 v83, v89, v89
	v_max_f32_e32 v85, v85, v85
	v_max_f32_e32 v86, 0, v86
	v_max_f32_e32 v87, 0, v87
	v_max_f32_e32 v82, 0, v82
	v_max_f32_e32 v83, 0, v83
	v_max_f32_e32 v85, 0, v85
	v_pk_mul_f32 v[86:87], v[86:87], v[86:87]
	v_pk_mul_f32 v[88:89], v[82:83], v[82:83]
	v_pk_mul_f32 v[92:93], v[84:85], v[84:85]
	v_max_f32_e32 v74, v74, v74
	v_max_f32_e32 v75, v75, v75
	v_cvt_pk_bf16_f32 v82, v86, v87
	v_cvt_pk_bf16_f32 v83, v88, v89
	v_cvt_pk_bf16_f32 v84, v90, v91
	v_cvt_pk_bf16_f32 v85, v92, v93
	v_max_f32_e32 v74, 0, v74
	v_max_f32_e32 v75, 0, v75
	global_store_dwordx4 v[94:95], v[82:85], off offset:256 sc1
	v_max_f32_e32 v78, v78, v78
	v_max_f32_e32 v79, v79, v79
	v_add_u32_e32 v82, 48, v140
	v_pk_mul_f32 v[84:85], v[74:75], v[74:75]
	v_max_f32_e32 v75, v76, v76
	v_ashrrev_i32_e32 v83, 31, v82
	v_max_f32_e32 v74, v80, v80
	v_max_f32_e32 v76, 0, v75
	v_max_f32_e32 v75, v81, v81
	v_max_f32_e32 v77, v77, v77
	v_lshlrev_b64 v[82:83], 13, v[82:83]
	v_max_f32_e32 v78, 0, v78
	v_max_f32_e32 v79, 0, v79
	v_max_f32_e32 v74, 0, v74
	v_max_f32_e32 v75, 0, v75
	v_max_f32_e32 v77, 0, v77
	v_lshl_add_u64 v[82:83], s[4:5], 0, v[82:83]
	v_pk_mul_f32 v[78:79], v[78:79], v[78:79]
	v_pk_mul_f32 v[80:81], v[74:75], v[74:75]
	v_pk_mul_f32 v[86:87], v[76:77], v[76:77]
	v_max_f32_e32 v66, v66, v66
	v_max_f32_e32 v67, v67, v67
	v_cvt_pk_bf16_f32 v74, v78, v79
	v_cvt_pk_bf16_f32 v75, v80, v81
	v_cvt_pk_bf16_f32 v76, v84, v85
	v_cvt_pk_bf16_f32 v77, v86, v87
	v_lshl_add_u64 v[78:79], v[82:83], 0, v[122:123]
	v_max_f32_e32 v66, 0, v66
	v_max_f32_e32 v67, 0, v67
	global_store_dwordx4 v[78:79], v[74:77], off sc1
	v_max_f32_e32 v70, v70, v70
	v_max_f32_e32 v71, v71, v71
	v_pk_mul_f32 v[74:75], v[66:67], v[66:67]
	v_max_f32_e32 v67, v68, v68
	v_max_f32_e32 v66, v72, v72
	v_max_f32_e32 v68, 0, v67
	v_max_f32_e32 v67, v73, v73
	v_max_f32_e32 v69, v69, v69
	v_max_f32_e32 v70, 0, v70
	v_max_f32_e32 v71, 0, v71
	v_max_f32_e32 v66, 0, v66
	v_max_f32_e32 v67, 0, v67
	v_max_f32_e32 v69, 0, v69
	v_pk_mul_f32 v[70:71], v[70:71], v[70:71]
	v_pk_mul_f32 v[72:73], v[66:67], v[66:67]
	v_pk_mul_f32 v[76:77], v[68:69], v[68:69]
	v_max_f32_e32 v58, v58, v58
	v_max_f32_e32 v59, v59, v59
	v_cvt_pk_bf16_f32 v66, v70, v71
	v_cvt_pk_bf16_f32 v67, v72, v73
	v_cvt_pk_bf16_f32 v68, v74, v75
	v_cvt_pk_bf16_f32 v69, v76, v77
	v_max_f32_e32 v58, 0, v58
	v_max_f32_e32 v59, 0, v59
	global_store_dwordx4 v[78:79], v[66:69], off offset:256 sc1
	v_max_f32_e32 v62, v62, v62
	v_max_f32_e32 v63, v63, v63
	v_add_u32_e32 v66, 0x80, v140
	v_pk_mul_f32 v[68:69], v[58:59], v[58:59]
	v_max_f32_e32 v59, v60, v60
	v_ashrrev_i32_e32 v67, 31, v66
	v_max_f32_e32 v58, v64, v64
	v_max_f32_e32 v60, 0, v59
	v_max_f32_e32 v59, v65, v65
	v_max_f32_e32 v61, v61, v61
	v_lshlrev_b64 v[66:67], 13, v[66:67]
	v_max_f32_e32 v62, 0, v62
	v_max_f32_e32 v63, 0, v63
	v_max_f32_e32 v58, 0, v58
	v_max_f32_e32 v59, 0, v59
; DI uint4 pack8(f32x4 a, f32x4 b) { uint4 r; r.x = pack2(a[0], a[1]); r.y = pack2(a[2], a[3]); r.z = pack2(b[0], b[1]); r.w = pack2(b[2], b[3]); return r; }
; template <class Epi, class Sched>
; DI void gemm_phase(LAS unsigned char* lds, const Gemm g, const Sched& S, const Epi& E, int wid_k) {
;     ...
;     { int fr_ = fr, fq_ = fq, wr_ = wr, wc_ = wc; asm volatile("" : "+v"(fr_), "+v"(fq_)); asm volatile("" : "+s"(wr_), "+s"(wc_)); E(acc, cur, wr_, wc_, fr_, fq_); }
;     if (!has_next) break;
;   DI void operator()(const Acc8& acc, const pg8::Unit& u, int wr, int wc, int fr, int fq) const {
; #pragma unroll
;     for (int ai = 0; ai < 2; ++ai)
; #pragma unroll
;       for (int m = 0; m < 4; ++m) {
;         u16* rowp = O + (size_t)EPI_ROWS(ai, m) * ldc;
; #pragma unroll
;         for (int bj = 0; bj < 2; ++bj) {
;           f32x4 v0 = acc[ai][bj][m][0], v1 = acc[ai][bj][m][1];
;           if (ACT == 1) {
; #pragma unroll
;             for (int e = 0; e < 4; ++e) { const float r0 = fmaxf(v0[e], 0.f), r1 = fmaxf(v1[e], 0.f); v0[e] = r0 * r0; v1[e] = r1 * r1; }
;           }
;           *(uint4*)(rowp + EPI_COL8(bj)) = pack8(v0, v1);
;         }
;       }
	v_max_f32_e32 v61, 0, v61
	v_lshl_add_u64 v[66:67], s[4:5], 0, v[66:67]
	v_pk_mul_f32 v[62:63], v[62:63], v[62:63]
	v_pk_mul_f32 v[64:65], v[58:59], v[58:59]
	v_pk_mul_f32 v[70:71], v[60:61], v[60:61]
	v_max_f32_e32 v50, v50, v50
	v_max_f32_e32 v51, v51, v51
	v_cvt_pk_bf16_f32 v58, v62, v63
	v_cvt_pk_bf16_f32 v59, v64, v65
	v_cvt_pk_bf16_f32 v60, v68, v69
	v_cvt_pk_bf16_f32 v61, v70, v71
	v_lshl_add_u64 v[62:63], v[66:67], 0, v[122:123]
	v_max_f32_e32 v50, 0, v50
	v_max_f32_e32 v51, 0, v51
	global_store_dwordx4 v[62:63], v[58:61], off sc1
	v_max_f32_e32 v54, v54, v54
	v_max_f32_e32 v55, v55, v55
	v_pk_mul_f32 v[58:59], v[50:51], v[50:51]
	v_max_f32_e32 v51, v52, v52
	v_max_f32_e32 v50, v56, v56
	v_max_f32_e32 v52, 0, v51
	v_max_f32_e32 v51, v57, v57
	v_max_f32_e32 v53, v53, v53
	v_max_f32_e32 v54, 0, v54
	v_max_f32_e32 v55, 0, v55
	v_max_f32_e32 v50, 0, v50
	v_max_f32_e32 v51, 0, v51
	v_max_f32_e32 v53, 0, v53
	v_pk_mul_f32 v[54:55], v[54:55], v[54:55]
	v_pk_mul_f32 v[56:57], v[50:51], v[50:51]
	v_pk_mul_f32 v[60:61], v[52:53], v[52:53]
	v_max_f32_e32 v42, v42, v42
	v_max_f32_e32 v43, v43, v43
	v_cvt_pk_bf16_f32 v50, v54, v55
	v_cvt_pk_bf16_f32 v51, v56, v57
	v_cvt_pk_bf16_f32 v52, v58, v59
	v_cvt_pk_bf16_f32 v53, v60, v61
	v_max_f32_e32 v42, 0, v42
	v_max_f32_e32 v43, 0, v43
	global_store_dwordx4 v[62:63], v[50:53], off offset:256 sc1
	v_max_f32_e32 v46, v46, v46
	v_max_f32_e32 v47, v47, v47
	v_add_u32_e32 v50, 0x90, v140
	v_pk_mul_f32 v[52:53], v[42:43], v[42:43]
	v_max_f32_e32 v43, v44, v44
	v_ashrrev_i32_e32 v51, 31, v50
	v_max_f32_e32 v42, v48, v48
	v_max_f32_e32 v44, 0, v43
	v_max_f32_e32 v43, v49, v49
	v_max_f32_e32 v45, v45, v45
	v_lshlrev_b64 v[50:51], 13, v[50:51]
	v_max_f32_e32 v46, 0, v46
	v_max_f32_e32 v47, 0, v47
	v_max_f32_e32 v42, 0, v42
	v_max_f32_e32 v43, 0, v43
	v_max_f32_e32 v45, 0, v45
	v_lshl_add_u64 v[50:51], s[4:5], 0, v[50:51]
	v_pk_mul_f32 v[46:47], v[46:47], v[46:47]
	v_pk_mul_f32 v[48:49], v[42:43], v[42:43]
	v_pk_mul_f32 v[54:55], v[44:45], v[44:45]
	v_max_f32_e32 v34, v34, v34
	v_max_f32_e32 v35, v35, v35
	v_cvt_pk_bf16_f32 v42, v46, v47
	v_cvt_pk_bf16_f32 v43, v48, v49
	v_cvt_pk_bf16_f32 v44, v52, v53
	v_cvt_pk_bf16_f32 v45, v54, v55
	v_lshl_add_u64 v[46:47], v[50:51], 0, v[122:123]
	v_max_f32_e32 v34, 0, v34
	v_max_f32_e32 v35, 0, v35
	global_store_dwordx4 v[46:47], v[42:45], off sc1
	v_max_f32_e32 v38, v38, v38
	v_max_f32_e32 v39, v39, v39
	v_pk_mul_f32 v[42:43], v[34:35], v[34:35]
	v_max_f32_e32 v35, v36, v36
	v_max_f32_e32 v34, v40, v40
	v_max_f32_e32 v36, 0, v35
	v_max_f32_e32 v35, v41, v41
	v_max_f32_e32 v37, v37, v37
	v_max_f32_e32 v38, 0, v38
	v_max_f32_e32 v39, 0, v39
	v_max_f32_e32 v34, 0, v34
	v_max_f32_e32 v35, 0, v35
	v_max_f32_e32 v37, 0, v37
	v_pk_mul_f32 v[38:39], v[38:39], v[38:39]
	v_pk_mul_f32 v[40:41], v[34:35], v[34:35]
	v_pk_mul_f32 v[44:45], v[36:37], v[36:37]
	v_max_f32_e32 v26, v26, v26
	v_max_f32_e32 v27, v27, v27
	v_cvt_pk_bf16_f32 v34, v38, v39
	v_cvt_pk_bf16_f32 v35, v40, v41
	v_cvt_pk_bf16_f32 v36, v42, v43
	v_cvt_pk_bf16_f32 v37, v44, v45
	v_max_f32_e32 v26, 0, v26
	v_max_f32_e32 v27, 0, v27
	global_store_dwordx4 v[46:47], v[34:37], off offset:256 sc1
	v_max_f32_e32 v30, v30, v30
	v_max_f32_e32 v31, v31, v31
	v_add_u32_e32 v34, 0xa0, v140
	v_pk_mul_f32 v[36:37], v[26:27], v[26:27]
	v_max_f32_e32 v27, v28, v28
	v_ashrrev_i32_e32 v35, 31, v34
	v_max_f32_e32 v26, v32, v32
	v_max_f32_e32 v28, 0, v27
	v_max_f32_e32 v27, v33, v33
	v_max_f32_e32 v29, v29, v29
	v_lshlrev_b64 v[34:35], 13, v[34:35]
	v_max_f32_e32 v30, 0, v30
	v_max_f32_e32 v31, 0, v31
	v_max_f32_e32 v26, 0, v26
	v_max_f32_e32 v27, 0, v27
	v_max_f32_e32 v29, 0, v29
	v_lshl_add_u64 v[34:35], s[4:5], 0, v[34:35]
	v_pk_mul_f32 v[30:31], v[30:31], v[30:31]
	v_pk_mul_f32 v[32:33], v[26:27], v[26:27]
	v_pk_mul_f32 v[38:39], v[28:29], v[28:29]
	v_max_f32_e32 v18, v18, v18
	v_max_f32_e32 v19, v19, v19
	v_cvt_pk_bf16_f32 v26, v30, v31
	v_cvt_pk_bf16_f32 v27, v32, v33
	v_cvt_pk_bf16_f32 v28, v36, v37
	v_cvt_pk_bf16_f32 v29, v38, v39
	v_lshl_add_u64 v[30:31], v[34:35], 0, v[122:123]
	v_max_f32_e32 v18, 0, v18
	v_max_f32_e32 v19, 0, v19
	global_store_dwordx4 v[30:31], v[26:29], off sc1
	v_max_f32_e32 v22, v22, v22
	v_max_f32_e32 v23, v23, v23
	v_pk_mul_f32 v[26:27], v[18:19], v[18:19]
	v_max_f32_e32 v19, v20, v20
	v_max_f32_e32 v18, v24, v24
	v_max_f32_e32 v20, 0, v19
	v_max_f32_e32 v19, v25, v25
	v_max_f32_e32 v21, v21, v21
	v_max_f32_e32 v22, 0, v22
	v_max_f32_e32 v23, 0, v23
	v_max_f32_e32 v18, 0, v18
	v_max_f32_e32 v19, 0, v19
	v_max_f32_e32 v21, 0, v21
	v_pk_mul_f32 v[22:23], v[22:23], v[22:23]
	v_pk_mul_f32 v[24:25], v[18:19], v[18:19]
	v_pk_mul_f32 v[28:29], v[20:21], v[20:21]
	v_max_f32_e32 v10, v10, v10
	v_max_f32_e32 v11, v11, v11
	v_cvt_pk_bf16_f32 v18, v22, v23
	v_cvt_pk_bf16_f32 v19, v24, v25
	v_cvt_pk_bf16_f32 v20, v26, v27
	v_cvt_pk_bf16_f32 v21, v28, v29
	v_max_f32_e32 v10, 0, v10
	v_max_f32_e32 v11, 0, v11
	global_store_dwordx4 v[30:31], v[18:21], off offset:256 sc1
	v_max_f32_e32 v14, v14, v14
	v_max_f32_e32 v15, v15, v15
	v_add_u32_e32 v18, 0xb0, v140
	v_pk_mul_f32 v[20:21], v[10:11], v[10:11]
	v_max_f32_e32 v11, v12, v12
	v_ashrrev_i32_e32 v19, 31, v18
	v_max_f32_e32 v10, v16, v16
	v_max_f32_e32 v12, 0, v11
	v_max_f32_e32 v11, v17, v17
	v_max_f32_e32 v13, v13, v13
	v_lshlrev_b64 v[18:19], 13, v[18:19]
	v_max_f32_e32 v14, 0, v14
	v_max_f32_e32 v15, 0, v15
	v_max_f32_e32 v10, 0, v10
	v_max_f32_e32 v11, 0, v11
	v_max_f32_e32 v13, 0, v13
	v_lshl_add_u64 v[18:19], s[4:5], 0, v[18:19]
	v_pk_mul_f32 v[14:15], v[14:15], v[14:15]
	v_pk_mul_f32 v[16:17], v[10:11], v[10:11]
	v_pk_mul_f32 v[22:23], v[12:13], v[12:13]
	v_max_f32_e32 v2, v2, v2
	v_max_f32_e32 v3, v3, v3
	v_cvt_pk_bf16_f32 v10, v14, v15
	v_cvt_pk_bf16_f32 v11, v16, v17
	v_cvt_pk_bf16_f32 v12, v20, v21
	v_cvt_pk_bf16_f32 v13, v22, v23
	v_lshl_add_u64 v[14:15], v[18:19], 0, v[122:123]
	v_max_f32_e32 v2, 0, v2
	v_max_f32_e32 v3, 0, v3
	global_store_dwordx4 v[14:15], v[10:13], off sc1
	v_max_f32_e32 v6, v6, v6
	v_max_f32_e32 v7, v7, v7
	v_pk_mul_f32 v[10:11], v[2:3], v[2:3]
	v_max_f32_e32 v3, v4, v4
	v_max_f32_e32 v2, v8, v8
	v_max_f32_e32 v4, 0, v3
	v_max_f32_e32 v3, v9, v9
	v_max_f32_e32 v5, v5, v5
	v_max_f32_e32 v6, 0, v6
	v_max_f32_e32 v7, 0, v7
	v_max_f32_e32 v2, 0, v2
	v_max_f32_e32 v3, 0, v3
	v_max_f32_e32 v5, 0, v5
	v_pk_mul_f32 v[6:7], v[6:7], v[6:7]
	v_pk_mul_f32 v[8:9], v[2:3], v[2:3]
	v_pk_mul_f32 v[12:13], v[4:5], v[4:5]
	v_cvt_pk_bf16_f32 v2, v6, v7
	v_cvt_pk_bf16_f32 v3, v8, v9
	v_cvt_pk_bf16_f32 v4, v10, v11
	v_cvt_pk_bf16_f32 v5, v12, v13
	s_and_b64 vcc, exec, s[2:3]
	s_mov_b32 s48, s6
	s_mov_b32 s14, s8
	s_mov_b64 s[18:19], s[12:13]
	s_mov_b64 s[16:17], s[10:11]
	global_store_dwordx4 v[14:15], v[2:5], off offset:256 sc1
	s_cbranch_vccz .LBB0_1840
	s_waitcnt vmcnt(0)
	s_cmpk_gt_u32 s24, 0xff
	s_cbranch_scc1 .LBB0_1851
	s_barrier

; #define PG8_STAGE(bufoff, gbase, voff) do { _Pragma("unroll") for (int _i = 0; _i < 2; ++_i) \
;     __builtin_amdgcn_global_load_lds((const unsigned*)((const char*)(gbase) + (voff)[_i]), (LAS unsigned*)(lds + (bufoff) + ldsw + _i * 8192), 16, 0, 0); } while (0)
; #define PG8_LDA(dst, b, h) do { _Pragma("unroll") for (int m = 0; m < 4; ++m) _Pragma("unroll") for (int k = 0; k < 2; ++k) dst[m][k] = *(const LAS bf16x8*)(lds + PG8_SA(b, h) + aoff + m * 2048 + k * 1024); } while (0)
; #define PG8_LDB(dst, b, h) do { _Pragma("unroll") for (int n = 0; n < 2; ++n) _Pragma("unroll") for (int k = 0; k < 2; ++k) dst[n][k] = *(const LAS bf16x8*)(lds + PG8_SB(b, h) + boff + n * 2048 + k * 1024); } while (0)
; #define PG8_MMA(ai, bj, At, Bt) do { __builtin_amdgcn_s_setprio(1); _Pragma("unroll") for (int m = 0; m < 4; ++m) _Pragma("unroll") for (int n = 0; n < 2; ++n) _Pragma("unroll") for (int k = 0; k < 2; ++k) \
;     acc[ai][bj][m][n] = __builtin_amdgcn_mfma_f32_16x16x32_bf16(Bt[n][k], At[m][k], acc[ai][bj][m][n], 0, 0, 0); __builtin_amdgcn_s_setprio(0); } while (0)
; #define PG8_WAIT_V(n) asm volatile("s_waitcnt vmcnt(" #n ")" ::: "memory")
; template <class Epi, class Sched>
; DI void gemm_phase(LAS unsigned char* lds, const Gemm g, const Sched& S, const Epi& E, int wid_k) {
;     ...
;     for (int t = 0; t < nt; t += 2) {
;       const bool last = (t == nt - 2);
;       const char* a1 = cA + (size_t)(t + 1) * kstep;
;       const char* a2 = last ? nA : cA + (size_t)(t + 2) * kstep; const char* b2 = last ? nB : cB + (size_t)(t + 2) * kstep;
;       const char* a3 = a2 + kstep; const char* b3 = b2 + kstep;
;       PG8_LDB(B0, 0, 0); PG8_SCHED; PG8_LDA(At, 0, 0); PG8_STAGE(PG8_SA(1, 1), a1 + hstepA, voffA);
;       PG8_WAIT_L(8); PG8_BAR; PG8_WAIT_L(0); PG8_MMA(0, 0, At, B0); PG8_BAR; PG8_SCHED;
;       PG8_LDB(B1, 0, 1); PG8_STAGE(PG8_SB(0, 0), b2, voffB);
;       PG8_BAR; PG8_WAIT_L(0); PG8_MMA(0, 1, At, B1); PG8_BAR;
;       PG8_LDA(At, 0, 1); PG8_STAGE(PG8_SA(0, 0), a2, voffA);
;       PG8_BAR; PG8_WAIT_L(0); PG8_MMA(1, 0, At, B0); PG8_BAR; PG8_SCHED;
;       PG8_STAGE(PG8_SB(0, 1), b2 + hstepB, voffB);
;       PG8_WAIT_V(6); PG8_BAR; PG8_MMA(1, 1, At, B1); PG8_BAR;
;       PG8_LDB(B0, 1, 0); PG8_SCHED; PG8_LDA(At, 1, 0); PG8_STAGE(PG8_SA(0, 1), a2 + hstepA, voffA);
;       PG8_WAIT_L(8); PG8_BAR; PG8_WAIT_L(0); PG8_MMA(0, 0, At, B0); PG8_BAR; PG8_SCHED;
.LBB0_1919:
	s_add_u32 s18, s16, 0xfff00080
	s_addc_u32 s19, s17, -1
	s_add_i32 s64, 0, 0x10000
	v_add_u32_e32 v156, s64, v142
	ds_read_b128 v[144:147], v156
	ds_read_b128 v[148:151], v156 offset:1024
	ds_read_b128 v[152:155], v156 offset:2048
	ds_read_b128 v[156:159], v156 offset:3072
	s_cmp_eq_u32 s63, 60
	s_cselect_b32 s21, s11, s19
	s_cselect_b32 s20, s49, s18
	s_cselect_b32 s19, s9, s62
	s_cselect_b32 s18, s60, s61
	v_lshl_add_u64 v[194:195], s[16:17], 0, v[136:137]
	s_add_i32 m0, s7, 0xc000
	ds_read_b128 v[160:163], v143
	ds_read_b128 v[164:167], v143 offset:1024
	ds_read_b128 v[168:171], v143 offset:2048
	ds_read_b128 v[172:175], v143 offset:3072
	ds_read_b128 v[176:179], v143 offset:4096
	ds_read_b128 v[180:183], v143 offset:5120
	ds_read_b128 v[184:187], v143 offset:6144
	ds_read_b128 v[190:193], v143 offset:7168
	global_load_lds_dwordx4 v[194:195], off
	v_lshl_add_u64 v[194:195], s[16:17], 0, v[138:139]
	s_add_i32 m0, s7, 0xe000
	s_nop 0
	global_load_lds_dwordx4 v[194:195], off
	s_waitcnt lgkmcnt(8)
	s_barrier
	s_waitcnt lgkmcnt(0)
	s_setprio 1
	s_waitcnt lgkmcnt(0)
	v_mfma_f32_16x16x32_bf16 v[126:129], v[144:147], v[160:163], v[126:129]
	v_mfma_f32_16x16x32_bf16 v[122:125], v[152:155], v[160:163], v[122:125]
	v_mfma_f32_16x16x32_bf16 v[118:121], v[144:147], v[168:171], v[118:121]
	v_mfma_f32_16x16x32_bf16 v[114:117], v[152:155], v[168:171], v[114:117]
	v_mfma_f32_16x16x32_bf16 v[102:105], v[144:147], v[176:179], v[102:105]
	v_mfma_f32_16x16x32_bf16 v[98:101], v[152:155], v[176:179], v[98:101]
	v_mfma_f32_16x16x32_bf16 v[86:89], v[144:147], v[184:187], v[86:89]
	v_mfma_f32_16x16x32_bf16 v[82:85], v[152:155], v[184:187], v[82:85]
	v_mfma_f32_16x16x32_bf16 v[126:129], v[148:151], v[164:167], v[126:129]
	v_mfma_f32_16x16x32_bf16 v[122:125], v[156:159], v[164:167], v[122:125]
	v_mfma_f32_16x16x32_bf16 v[118:121], v[148:151], v[172:175], v[118:121]
	v_mfma_f32_16x16x32_bf16 v[114:117], v[156:159], v[172:175], v[114:117]
	v_mfma_f32_16x16x32_bf16 v[102:105], v[148:151], v[180:183], v[102:105]
	v_mfma_f32_16x16x32_bf16 v[98:101], v[156:159], v[180:183], v[98:101]
	v_mfma_f32_16x16x32_bf16 v[86:89], v[148:151], v[190:193], v[86:89]
	v_mfma_f32_16x16x32_bf16 v[82:85], v[156:159], v[190:193], v[82:85]
	s_setprio 0
	s_barrier
	s_add_i32 s70, 0, 0x14000
	s_add_i32 s64, s64, s31
	v_add_u32_e32 v206, s70, v142
	v_lshl_add_u64 v[210:211], s[18:19], 0, v[0:1]
	s_mov_b32 m0, s64
	ds_read_b128 v[194:197], v206
	ds_read_b128 v[198:201], v206 offset:1024
	ds_read_b128 v[202:205], v206 offset:2048
	ds_read_b128 v[206:209], v206 offset:3072
	global_load_lds_dwordx4 v[210:211], off
	v_lshl_add_u64 v[212:213], s[18:19], 0, v[134:135]
	s_add_i32 m0, s64, 0x2000
	s_nop 0
	global_load_lds_dwordx4 v[212:213], off
	s_barrier
	s_waitcnt lgkmcnt(0)
	s_setprio 1
	s_waitcnt lgkmcnt(0)
	v_mfma_f32_16x16x32_bf16 v[110:113], v[194:197], v[160:163], v[110:113]
	v_mfma_f32_16x16x32_bf16 v[106:109], v[202:205], v[160:163], v[106:109]
	v_mfma_f32_16x16x32_bf16 v[94:97], v[194:197], v[168:171], v[94:97]
	v_mfma_f32_16x16x32_bf16 v[90:93], v[202:205], v[168:171], v[90:93]
	v_mfma_f32_16x16x32_bf16 v[78:81], v[194:197], v[176:179], v[78:81]
	v_mfma_f32_16x16x32_bf16 v[74:77], v[202:205], v[176:179], v[74:77]
	v_mfma_f32_16x16x32_bf16 v[70:73], v[194:197], v[184:187], v[70:73]
	v_mfma_f32_16x16x32_bf16 v[66:69], v[202:205], v[184:187], v[66:69]
	v_mfma_f32_16x16x32_bf16 v[110:113], v[198:201], v[164:167], v[110:113]
	v_mfma_f32_16x16x32_bf16 v[106:109], v[206:209], v[164:167], v[106:109]
	v_mfma_f32_16x16x32_bf16 v[94:97], v[198:201], v[172:175], v[94:97]
	v_mfma_f32_16x16x32_bf16 v[90:93], v[206:209], v[172:175], v[90:93]
	v_mfma_f32_16x16x32_bf16 v[78:81], v[198:201], v[180:183], v[78:81]
	v_mfma_f32_16x16x32_bf16 v[74:77], v[206:209], v[180:183], v[74:77]
	v_mfma_f32_16x16x32_bf16 v[70:73], v[198:201], v[190:193], v[70:73]
	v_mfma_f32_16x16x32_bf16 v[66:69], v[206:209], v[190:193], v[66:69]
	s_setprio 0
	s_mov_b32 m0, s7
	v_lshl_add_u64 v[214:215], s[20:21], 0, v[130:131]
	s_barrier
	ds_read_b128 v[160:163], v143 offset:16384
	ds_read_b128 v[164:167], v143 offset:17408
	ds_read_b128 v[168:171], v143 offset:18432
	ds_read_b128 v[172:175], v143 offset:19456
	ds_read_b128 v[176:179], v143 offset:20480
	ds_read_b128 v[180:183], v143 offset:21504
	ds_read_b128 v[184:187], v143 offset:22528
	ds_read_b128 v[190:193], v143 offset:23552
	global_load_lds_dwordx4 v[214:215], off
	v_lshl_add_u64 v[216:217], s[20:21], 0, v[132:133]
	s_mov_b32 m0, s34
	s_nop 0
	global_load_lds_dwordx4 v[216:217], off
	s_barrier
	s_waitcnt lgkmcnt(0)
	s_setprio 1
	s_waitcnt lgkmcnt(0)
	v_mfma_f32_16x16x32_bf16 v[62:65], v[144:147], v[160:163], v[62:65]
	v_mfma_f32_16x16x32_bf16 v[58:61], v[152:155], v[160:163], v[58:61]
	v_mfma_f32_16x16x32_bf16 v[54:57], v[144:147], v[168:171], v[54:57]
	v_mfma_f32_16x16x32_bf16 v[50:53], v[152:155], v[168:171], v[50:53]
	v_mfma_f32_16x16x32_bf16 v[38:41], v[144:147], v[176:179], v[38:41]
	v_mfma_f32_16x16x32_bf16 v[34:37], v[152:155], v[176:179], v[34:37]
	v_mfma_f32_16x16x32_bf16 v[22:25], v[144:147], v[184:187], v[22:25]
	v_mfma_f32_16x16x32_bf16 v[18:21], v[152:155], v[184:187], v[18:21]
	v_mfma_f32_16x16x32_bf16 v[62:65], v[148:151], v[164:167], v[62:65]
	v_mfma_f32_16x16x32_bf16 v[58:61], v[156:159], v[164:167], v[58:61]
	v_mfma_f32_16x16x32_bf16 v[54:57], v[148:151], v[172:175], v[54:57]
	v_mfma_f32_16x16x32_bf16 v[50:53], v[156:159], v[172:175], v[50:53]
	v_mfma_f32_16x16x32_bf16 v[38:41], v[148:151], v[180:183], v[38:41]
	v_mfma_f32_16x16x32_bf16 v[34:37], v[156:159], v[180:183], v[34:37]
	v_mfma_f32_16x16x32_bf16 v[22:25], v[148:151], v[190:193], v[22:25]
	v_mfma_f32_16x16x32_bf16 v[18:21], v[156:159], v[190:193], v[18:21]
	s_setprio 0
	s_barrier
; #define PG8_STAGE(bufoff, gbase, voff) do { _Pragma("unroll") for (int _i = 0; _i < 2; ++_i) \
;     __builtin_amdgcn_global_load_lds((const unsigned*)((const char*)(gbase) + (voff)[_i]), (LAS unsigned*)(lds + (bufoff) + ldsw + _i * 8192), 16, 0, 0); } while (0)
; #define PG8_LDA(dst, b, h) do { _Pragma("unroll") for (int m = 0; m < 4; ++m) _Pragma("unroll") for (int k = 0; k < 2; ++k) dst[m][k] = *(const LAS bf16x8*)(lds + PG8_SA(b, h) + aoff + m * 2048 + k * 1024); } while (0)
; #define PG8_LDB(dst, b, h) do { _Pragma("unroll") for (int n = 0; n < 2; ++n) _Pragma("unroll") for (int k = 0; k < 2; ++k) dst[n][k] = *(const LAS bf16x8*)(lds + PG8_SB(b, h) + boff + n * 2048 + k * 1024); } while (0)
; #define PG8_MMA(ai, bj, At, Bt) do { __builtin_amdgcn_s_setprio(1); _Pragma("unroll") for (int m = 0; m < 4; ++m) _Pragma("unroll") for (int n = 0; n < 2; ++n) _Pragma("unroll") for (int k = 0; k < 2; ++k) \
;     acc[ai][bj][m][n] = __builtin_amdgcn_mfma_f32_16x16x32_bf16(Bt[n][k], At[m][k], acc[ai][bj][m][n], 0, 0, 0); __builtin_amdgcn_s_setprio(0); } while (0)
; #define PG8_WAIT_V(n) asm volatile("s_waitcnt vmcnt(" #n ")" ::: "memory")
; #define PG8_WAIT_L(n) asm volatile("s_waitcnt lgkmcnt(" #n ")" ::: "memory")
; #define PG8_BAR __builtin_amdgcn_s_barrier()
; #define PG8_SCHED __builtin_amdgcn_sched_barrier(0)
; template <class Epi, class Sched>
; DI void gemm_phase(LAS unsigned char* lds, const Gemm g, const Sched& S, const Epi& E, int wid_k) {
;     ...
;       PG8_STAGE(PG8_SB(0, 1), b2 + hstepB, voffB);
;       PG8_WAIT_V(6); PG8_BAR; PG8_MMA(1, 1, At, B1); PG8_BAR;
;       PG8_LDB(B0, 1, 0); PG8_SCHED; PG8_LDA(At, 1, 0); PG8_STAGE(PG8_SA(0, 1), a2 + hstepA, voffA);
;       PG8_WAIT_L(8); PG8_BAR; PG8_WAIT_L(0); PG8_MMA(0, 0, At, B0); PG8_BAR; PG8_SCHED;
;       PG8_LDB(B1, 1, 1); PG8_STAGE(PG8_SB(1, 0), b3, voffB);
;       PG8_BAR; PG8_WAIT_L(0); PG8_MMA(0, 1, At, B1); PG8_BAR;
;       PG8_LDA(At, 1, 1); PG8_STAGE(PG8_SA(1, 0), a3, voffA);
	s_add_u32 s64, s18, 0x100000
	s_addc_u32 s65, s19, 0
	s_add_i32 s70, s70, s31
	v_lshl_add_u64 v[144:145], s[64:65], 0, v[0:1]
	s_mov_b32 m0, s70
	s_nop 0
	global_load_lds_dwordx4 v[144:145], off
	v_lshl_add_u64 v[144:145], s[64:65], 0, v[134:135]
	s_add_i32 m0, s70, 0x2000
	s_nop 0
	global_load_lds_dwordx4 v[144:145], off
	s_waitcnt vmcnt(6)
	s_barrier
	s_setprio 1
	v_mfma_f32_16x16x32_bf16 v[46:49], v[194:197], v[160:163], v[46:49]
	v_mfma_f32_16x16x32_bf16 v[42:45], v[202:205], v[160:163], v[42:45]
	v_mfma_f32_16x16x32_bf16 v[30:33], v[194:197], v[168:171], v[30:33]
	v_mfma_f32_16x16x32_bf16 v[26:29], v[202:205], v[168:171], v[26:29]
	v_mfma_f32_16x16x32_bf16 v[14:17], v[194:197], v[176:179], v[14:17]
	v_mfma_f32_16x16x32_bf16 v[10:13], v[202:205], v[176:179], v[10:13]
	v_mfma_f32_16x16x32_bf16 v[6:9], v[194:197], v[184:187], v[6:9]
	v_mfma_f32_16x16x32_bf16 v[2:5], v[202:205], v[184:187], v[2:5]
	v_mfma_f32_16x16x32_bf16 v[46:49], v[198:201], v[164:167], v[46:49]
	v_mfma_f32_16x16x32_bf16 v[42:45], v[206:209], v[164:167], v[42:45]
	v_mfma_f32_16x16x32_bf16 v[30:33], v[198:201], v[172:175], v[30:33]
	v_mfma_f32_16x16x32_bf16 v[26:29], v[206:209], v[172:175], v[26:29]
	v_mfma_f32_16x16x32_bf16 v[14:17], v[198:201], v[180:183], v[14:17]
	v_mfma_f32_16x16x32_bf16 v[10:13], v[206:209], v[180:183], v[10:13]
	v_mfma_f32_16x16x32_bf16 v[6:9], v[198:201], v[190:193], v[6:9]
	v_mfma_f32_16x16x32_bf16 v[2:5], v[206:209], v[190:193], v[2:5]
	s_setprio 0
	s_add_i32 s64, 0, 0x18000
	v_add_u32_e32 v156, s64, v142
	s_barrier
	ds_read_b128 v[144:147], v156
	ds_read_b128 v[148:151], v156 offset:1024
	ds_read_b128 v[152:155], v156 offset:2048
	ds_read_b128 v[156:159], v156 offset:3072
	s_add_u32 s20, s20, 0x100000
	s_addc_u32 s21, s21, 0
	s_mov_b32 m0, s35
	v_lshl_add_u64 v[194:195], s[20:21], 0, v[130:131]
	ds_read_b128 v[160:163], v143 offset:32768
	ds_read_b128 v[164:167], v143 offset:33792
	ds_read_b128 v[168:171], v143 offset:34816
	ds_read_b128 v[172:175], v143 offset:35840
	ds_read_b128 v[176:179], v143 offset:36864
	ds_read_b128 v[180:183], v143 offset:37888
	ds_read_b128 v[184:187], v143 offset:38912
	ds_read_b128 v[190:193], v143 offset:39936
	global_load_lds_dwordx4 v[194:195], off
	v_lshl_add_u64 v[194:195], s[20:21], 0, v[132:133]
	s_mov_b32 m0, s36
	s_nop 0
	global_load_lds_dwordx4 v[194:195], off
	s_waitcnt lgkmcnt(8)
	s_barrier
	s_waitcnt lgkmcnt(0)
	s_setprio 1
	s_waitcnt lgkmcnt(0)
	v_mfma_f32_16x16x32_bf16 v[126:129], v[144:147], v[160:163], v[126:129]
	v_mfma_f32_16x16x32_bf16 v[122:125], v[152:155], v[160:163], v[122:125]
	v_mfma_f32_16x16x32_bf16 v[118:121], v[144:147], v[168:171], v[118:121]
	v_mfma_f32_16x16x32_bf16 v[114:117], v[152:155], v[168:171], v[114:117]
	v_mfma_f32_16x16x32_bf16 v[102:105], v[144:147], v[176:179], v[102:105]
	v_mfma_f32_16x16x32_bf16 v[98:101], v[152:155], v[176:179], v[98:101]
	v_mfma_f32_16x16x32_bf16 v[86:89], v[144:147], v[184:187], v[86:89]
	v_mfma_f32_16x16x32_bf16 v[82:85], v[152:155], v[184:187], v[82:85]
	v_mfma_f32_16x16x32_bf16 v[126:129], v[148:151], v[164:167], v[126:129]
	v_mfma_f32_16x16x32_bf16 v[122:125], v[156:159], v[164:167], v[122:125]
	v_mfma_f32_16x16x32_bf16 v[118:121], v[148:151], v[172:175], v[118:121]
	v_mfma_f32_16x16x32_bf16 v[114:117], v[156:159], v[172:175], v[114:117]
	v_mfma_f32_16x16x32_bf16 v[102:105], v[148:151], v[180:183], v[102:105]
	v_mfma_f32_16x16x32_bf16 v[98:101], v[156:159], v[180:183], v[98:101]
	v_mfma_f32_16x16x32_bf16 v[86:89], v[148:151], v[190:193], v[86:89]
	v_mfma_f32_16x16x32_bf16 v[82:85], v[156:159], v[190:193], v[82:85]
	s_setprio 0
	s_barrier
	s_add_i32 s20, 0, 0x1c000
	s_add_i32 s21, s64, s31
	v_add_u32_e32 v206, s20, v142
	v_lshl_add_u64 v[210:211], v[210:211], 0, s[78:79]
	s_mov_b32 m0, s21
	ds_read_b128 v[194:197], v206
	ds_read_b128 v[198:201], v206 offset:1024
	ds_read_b128 v[202:205], v206 offset:2048
	ds_read_b128 v[206:209], v206 offset:3072
	global_load_lds_dwordx4 v[210:211], off
	v_lshl_add_u64 v[210:211], v[212:213], 0, s[78:79]
	s_add_i32 m0, s21, 0x2000
	s_nop 0
	global_load_lds_dwordx4 v[210:211], off
	s_barrier
	s_waitcnt lgkmcnt(0)
	s_setprio 1
	s_waitcnt lgkmcnt(0)
	v_mfma_f32_16x16x32_bf16 v[110:113], v[194:197], v[160:163], v[110:113]
	v_mfma_f32_16x16x32_bf16 v[106:109], v[202:205], v[160:163], v[106:109]
	v_mfma_f32_16x16x32_bf16 v[94:97], v[194:197], v[168:171], v[94:97]
	v_mfma_f32_16x16x32_bf16 v[90:93], v[202:205], v[168:171], v[90:93]
	v_mfma_f32_16x16x32_bf16 v[78:81], v[194:197], v[176:179], v[78:81]
	v_mfma_f32_16x16x32_bf16 v[74:77], v[202:205], v[176:179], v[74:77]
	v_mfma_f32_16x16x32_bf16 v[70:73], v[194:197], v[184:187], v[70:73]
	v_mfma_f32_16x16x32_bf16 v[66:69], v[202:205], v[184:187], v[66:69]
	v_mfma_f32_16x16x32_bf16 v[110:113], v[198:201], v[164:167], v[110:113]
	v_mfma_f32_16x16x32_bf16 v[106:109], v[206:209], v[164:167], v[106:109]
	v_mfma_f32_16x16x32_bf16 v[94:97], v[198:201], v[172:175], v[94:97]
	v_mfma_f32_16x16x32_bf16 v[90:93], v[206:209], v[172:175], v[90:93]
	v_mfma_f32_16x16x32_bf16 v[78:81], v[198:201], v[180:183], v[78:81]
	v_mfma_f32_16x16x32_bf16 v[74:77], v[206:209], v[180:183], v[74:77]
	v_mfma_f32_16x16x32_bf16 v[70:73], v[198:201], v[190:193], v[70:73]
	v_mfma_f32_16x16x32_bf16 v[66:69], v[206:209], v[190:193], v[66:69]
	s_setprio 0
	s_mov_b32 m0, s38
	v_lshl_add_u64 v[210:211], v[214:215], 0, s[78:79]
	s_barrier
	ds_read_b128 v[160:163], v143 offset:49152
	ds_read_b128 v[164:167], v143 offset:50176
	ds_read_b128 v[168:171], v143 offset:51200
	ds_read_b128 v[172:175], v143 offset:52224
	ds_read_b128 v[176:179], v143 offset:53248
	ds_read_b128 v[180:183], v143 offset:54272
	ds_read_b128 v[184:187], v143 offset:55296
	ds_read_b128 v[190:193], v143 offset:56320
	global_load_lds_dwordx4 v[210:211], off
	v_lshl_add_u64 v[210:211], v[216:217], 0, s[78:79]
	s_mov_b32 m0, s39
	s_nop 0
	global_load_lds_dwordx4 v[210:211], off
	s_barrier
; #define PG8_STAGE(bufoff, gbase, voff) do { _Pragma("unroll") for (int _i = 0; _i < 2; ++_i) \
;     __builtin_amdgcn_global_load_lds((const unsigned*)((const char*)(gbase) + (voff)[_i]), (LAS unsigned*)(lds + (bufoff) + ldsw + _i * 8192), 16, 0, 0); } while (0)
; #define PG8_MMA(ai, bj, At, Bt) do { __builtin_amdgcn_s_setprio(1); _Pragma("unroll") for (int m = 0; m < 4; ++m) _Pragma("unroll") for (int n = 0; n < 2; ++n) _Pragma("unroll") for (int k = 0; k < 2; ++k) \
;     acc[ai][bj][m][n] = __builtin_amdgcn_mfma_f32_16x16x32_bf16(Bt[n][k], At[m][k], acc[ai][bj][m][n], 0, 0, 0); __builtin_amdgcn_s_setprio(0); } while (0)
; #define PG8_WAIT_V(n) asm volatile("s_waitcnt vmcnt(" #n ")" ::: "memory")
; #define PG8_WAIT_L(n) asm volatile("s_waitcnt lgkmcnt(" #n ")" ::: "memory")
; #define PG8_BAR __builtin_amdgcn_s_barrier()
; #define PG8_SCHED __builtin_amdgcn_sched_barrier(0)
; template <class Epi, class Sched>
; DI void gemm_phase(LAS unsigned char* lds, const Gemm g, const Sched& S, const Epi& E, int wid_k) {
;     ...
;       PG8_BAR; PG8_WAIT_L(0); PG8_MMA(1, 0, At, B0); PG8_BAR; PG8_SCHED;
;       PG8_STAGE(PG8_SB(1, 1), b3 + hstepB, voffB);
;       PG8_WAIT_V(6); PG8_BAR; PG8_MMA(1, 1, At, B1); PG8_BAR;
;     }
	s_waitcnt lgkmcnt(0)
	s_setprio 1
	s_waitcnt lgkmcnt(0)
	v_mfma_f32_16x16x32_bf16 v[62:65], v[144:147], v[160:163], v[62:65]
	v_mfma_f32_16x16x32_bf16 v[58:61], v[152:155], v[160:163], v[58:61]
	v_mfma_f32_16x16x32_bf16 v[54:57], v[144:147], v[168:171], v[54:57]
	v_mfma_f32_16x16x32_bf16 v[50:53], v[152:155], v[168:171], v[50:53]
	v_mfma_f32_16x16x32_bf16 v[38:41], v[144:147], v[176:179], v[38:41]
	v_mfma_f32_16x16x32_bf16 v[34:37], v[152:155], v[176:179], v[34:37]
	v_mfma_f32_16x16x32_bf16 v[22:25], v[144:147], v[184:187], v[22:25]
	v_mfma_f32_16x16x32_bf16 v[18:21], v[152:155], v[184:187], v[18:21]
	v_mfma_f32_16x16x32_bf16 v[62:65], v[148:151], v[164:167], v[62:65]
	v_mfma_f32_16x16x32_bf16 v[58:61], v[156:159], v[164:167], v[58:61]
	v_mfma_f32_16x16x32_bf16 v[54:57], v[148:151], v[172:175], v[54:57]
	v_mfma_f32_16x16x32_bf16 v[50:53], v[156:159], v[172:175], v[50:53]
	v_mfma_f32_16x16x32_bf16 v[38:41], v[148:151], v[180:183], v[38:41]
	v_mfma_f32_16x16x32_bf16 v[34:37], v[156:159], v[180:183], v[34:37]
	v_mfma_f32_16x16x32_bf16 v[22:25], v[148:151], v[190:193], v[22:25]
	v_mfma_f32_16x16x32_bf16 v[18:21], v[156:159], v[190:193], v[18:21]
	s_setprio 0
	s_barrier
	s_add_u32 s18, s18, 0x100080
	s_addc_u32 s19, s19, 0
	s_add_i32 s20, s20, s31
	v_lshl_add_u64 v[144:145], s[18:19], 0, v[0:1]
	s_mov_b32 m0, s20
	s_nop 0
	global_load_lds_dwordx4 v[144:145], off
	v_lshl_add_u64 v[144:145], s[18:19], 0, v[134:135]
	s_add_i32 m0, s20, 0x2000
	s_nop 0
	global_load_lds_dwordx4 v[144:145], off
	s_waitcnt vmcnt(6)
	s_barrier
	s_setprio 1
	v_mfma_f32_16x16x32_bf16 v[46:49], v[194:197], v[160:163], v[46:49]
	v_mfma_f32_16x16x32_bf16 v[42:45], v[202:205], v[160:163], v[42:45]
	v_mfma_f32_16x16x32_bf16 v[30:33], v[194:197], v[168:171], v[30:33]
	v_mfma_f32_16x16x32_bf16 v[26:29], v[202:205], v[168:171], v[26:29]
	v_mfma_f32_16x16x32_bf16 v[14:17], v[194:197], v[176:179], v[14:17]
	v_mfma_f32_16x16x32_bf16 v[10:13], v[202:205], v[176:179], v[10:13]
	v_mfma_f32_16x16x32_bf16 v[6:9], v[194:197], v[184:187], v[6:9]
	v_mfma_f32_16x16x32_bf16 v[2:5], v[202:205], v[184:187], v[2:5]
	v_mfma_f32_16x16x32_bf16 v[46:49], v[198:201], v[164:167], v[46:49]
	v_mfma_f32_16x16x32_bf16 v[42:45], v[206:209], v[164:167], v[42:45]
	v_mfma_f32_16x16x32_bf16 v[30:33], v[198:201], v[172:175], v[30:33]
	v_mfma_f32_16x16x32_bf16 v[26:29], v[206:209], v[172:175], v[26:29]
	v_mfma_f32_16x16x32_bf16 v[14:17], v[198:201], v[180:183], v[14:17]
	v_mfma_f32_16x16x32_bf16 v[10:13], v[206:209], v[180:183], v[10:13]
	v_mfma_f32_16x16x32_bf16 v[6:9], v[198:201], v[190:193], v[6:9]
	v_mfma_f32_16x16x32_bf16 v[2:5], v[206:209], v[190:193], v[2:5]
	s_setprio 0
	s_add_i32 s63, s63, 2
	s_add_u32 s16, s16, 0x100
	s_addc_u32 s17, s17, 0
	s_add_u32 s61, s61, 0x100
	s_addc_u32 s62, s62, 0
	s_cmp_gt_u32 s63, 61
	s_barrier
	s_cbranch_scc0 .LBB0_1919
; DI uint4 pack8(f32x4 a, f32x4 b) { uint4 r; r.x = pack2(a[0], a[1]); r.y = pack2(a[2], a[3]); r.z = pack2(b[0], b[1]); r.w = pack2(b[2], b[3]); return r; }
; #define PG8_WAIT_V(n) asm volatile("s_waitcnt vmcnt(" #n ")" ::: "memory")
; #define PG8_BAR __builtin_amdgcn_s_barrier()
; template <class Epi, class Sched>
; DI void gemm_phase(LAS unsigned char* lds, const Gemm g, const Sched& S, const Epi& E, int wid_k) {
;     ...
;     { int fr_ = fr, fq_ = fq, wr_ = wr, wc_ = wc; asm volatile("" : "+v"(fr_), "+v"(fq_)); asm volatile("" : "+s"(wr_), "+s"(wc_)); E(acc, cur, wr_, wc_, fr_, fq_); }
;     if (!has_next) break;
; #pragma unroll
;     for (int a = 0; a < 2; ++a)
; #pragma unroll
;       for (int b = 0; b < 2; ++b)
; #pragma unroll
;         for (int m = 0; m < 4; ++m)
; #pragma unroll
;           for (int n = 0; n < 2; ++n) acc[a][b][m][n] = (f32x4){0.f, 0.f, 0.f, 0.f};
;     cur = nxt; cA = nA; cB = nB; ++ui;
;   }
;   PG8_WAIT_V(0);
;   if (wr == 0) PG8_BAR;
;   PG8_BAR;
;   DI void operator()(const Acc8& acc, const pg8::Unit& u, int wr, int wc, int fr, int fq) const {
; #pragma unroll
;     for (int ai = 0; ai < 2; ++ai)
; #pragma unroll
;       for (int m = 0; m < 4; ++m) {
;         u16* rowp = O + (size_t)EPI_ROWS(ai, m) * ldc;
; #pragma unroll
;         for (int bj = 0; bj < 2; ++bj) {
;           f32x4 v0 = acc[ai][bj][m][0], v1 = acc[ai][bj][m][1];
;           if (ACT == 1) {
; #pragma unroll
;             for (int e = 0; e < 4; ++e) { const float r0 = fmaxf(v0[e], 0.f), r1 = fmaxf(v1[e], 0.f); v0[e] = r0 * r0; v1[e] = r1 * r1; }
;           }
;           *(uint4*)(rowp + EPI_COL8(bj)) = pack8(v0, v1);
;         }
;       }
	v_mov_b32_e32 v144, v141
	v_mov_b32_e32 v145, v140
	s_mov_b32 s9, s30
	s_mov_b32 s11, s37
	s_lshl_b32 s6, s6, 8
	s_lshl_b32 s9, s9, 6
	s_add_i32 s9, s9, s6
	v_add_u32_e32 v144, s9, v144
	s_lshl_b32 s6, s48, 8
	s_lshl_b32 s9, s11, 5
	s_add_i32 s9, s9, s6
	v_cvt_pk_bf16_f32 v70, v70, v71
	v_cvt_pk_bf16_f32 v71, v72, v73
	v_cvt_pk_bf16_f32 v72, v66, v67
	v_add_u32_e32 v66, 0x80, v144
	v_lshl_add_u32 v146, v145, 3, s9
	v_ashrrev_i32_e32 v145, 31, v144
	v_ashrrev_i32_e32 v67, 31, v66
	v_lshlrev_b64 v[148:149], 11, v[144:145]
	v_ashrrev_i32_e32 v147, 31, v146
	v_cvt_pk_bf16_f32 v110, v110, v111
	v_cvt_pk_bf16_f32 v111, v112, v113
	v_cvt_pk_bf16_f32 v112, v106, v107
	v_add_u32_e32 v106, 16, v144
	v_lshlrev_b64 v[66:67], 11, v[66:67]
	v_cvt_pk_bf16_f32 v46, v46, v47
	v_cvt_pk_bf16_f32 v47, v48, v49
	v_cvt_pk_bf16_f32 v48, v42, v43
	v_add_u32_e32 v42, 0x90, v144
	v_lshl_add_u64 v[148:149], s[4:5], 0, v[148:149]
	v_cvt_pk_bf16_f32 v126, v126, v127
	v_cvt_pk_bf16_f32 v127, v128, v129
	v_cvt_pk_bf16_f32 v128, v122, v123
	v_lshlrev_b64 v[122:123], 1, v[146:147]
	v_ashrrev_i32_e32 v107, 31, v106
	v_lshl_add_u64 v[66:67], s[4:5], 0, v[66:67]
	v_ashrrev_i32_e32 v43, 31, v42
	v_cvt_pk_bf16_f32 v129, v124, v125
	v_lshl_add_u64 v[124:125], v[148:149], 0, v[122:123]
	v_cvt_pk_bf16_f32 v113, v108, v109
	v_lshlrev_b64 v[106:107], 11, v[106:107]
	v_cvt_pk_bf16_f32 v94, v94, v95
	v_cvt_pk_bf16_f32 v95, v96, v97
	v_cvt_pk_bf16_f32 v96, v90, v91
	v_add_u32_e32 v90, 32, v144
	v_cvt_pk_bf16_f32 v62, v62, v63
	v_cvt_pk_bf16_f32 v63, v64, v65
	v_cvt_pk_bf16_f32 v64, v58, v59
	v_lshl_add_u64 v[58:59], v[66:67], 0, v[122:123]
	v_cvt_pk_bf16_f32 v49, v44, v45
	v_lshlrev_b64 v[42:43], 11, v[42:43]
	v_cvt_pk_bf16_f32 v30, v30, v31
	v_cvt_pk_bf16_f32 v31, v32, v33
	v_cvt_pk_bf16_f32 v32, v26, v27
	v_add_u32_e32 v26, 0xa0, v144
	global_store_dwordx4 v[124:125], v[110:113], off offset:256 sc1
	v_ashrrev_i32_e32 v91, 31, v90
	global_store_dwordx4 v[58:59], v[46:49], off offset:256 sc1
	v_lshl_add_u64 v[110:111], s[4:5], 0, v[106:107]
	v_ashrrev_i32_e32 v27, 31, v26
	v_lshl_add_u64 v[46:47], s[4:5], 0, v[42:43]
	v_lshl_add_u64 v[110:111], v[110:111], 0, v[122:123]
	v_cvt_pk_bf16_f32 v97, v92, v93
	v_lshlrev_b64 v[90:91], 11, v[90:91]
	v_cvt_pk_bf16_f32 v78, v78, v79
	v_cvt_pk_bf16_f32 v79, v80, v81
	v_cvt_pk_bf16_f32 v80, v74, v75
	v_add_u32_e32 v74, 48, v144
	v_lshl_add_u64 v[46:47], v[46:47], 0, v[122:123]
	v_cvt_pk_bf16_f32 v33, v28, v29
	v_lshlrev_b64 v[26:27], 11, v[26:27]
	v_cvt_pk_bf16_f32 v14, v14, v15
	v_cvt_pk_bf16_f32 v15, v16, v17
	v_cvt_pk_bf16_f32 v16, v10, v11
	v_add_u32_e32 v10, 0xb0, v144
	global_store_dwordx4 v[110:111], v[94:97], off offset:256 sc1
	v_ashrrev_i32_e32 v75, 31, v74
	global_store_dwordx4 v[46:47], v[30:33], off offset:256 sc1
	v_lshl_add_u64 v[94:95], s[4:5], 0, v[90:91]
	v_ashrrev_i32_e32 v11, 31, v10
	v_lshl_add_u64 v[30:31], s[4:5], 0, v[26:27]
	v_lshl_add_u64 v[94:95], v[94:95], 0, v[122:123]
	v_cvt_pk_bf16_f32 v81, v76, v77
	v_lshlrev_b64 v[74:75], 11, v[74:75]
	v_lshl_add_u64 v[30:31], v[30:31], 0, v[122:123]
	v_cvt_pk_bf16_f32 v17, v12, v13
	v_lshlrev_b64 v[10:11], 11, v[10:11]
	global_store_dwordx4 v[94:95], v[78:81], off offset:256 sc1
	global_store_dwordx4 v[30:31], v[14:17], off offset:256 sc1
	v_cvt_pk_bf16_f32 v106, v118, v119
	v_lshl_add_u64 v[78:79], s[4:5], 0, v[74:75]
	v_lshl_add_u64 v[14:15], s[4:5], 0, v[10:11]
	v_cvt_pk_bf16_f32 v107, v120, v121
	v_cvt_pk_bf16_f32 v108, v114, v115
	v_cvt_pk_bf16_f32 v109, v116, v117
	v_cvt_pk_bf16_f32 v90, v102, v103
	v_cvt_pk_bf16_f32 v91, v104, v105
	v_cvt_pk_bf16_f32 v92, v98, v99
	v_cvt_pk_bf16_f32 v93, v100, v101
	v_cvt_pk_bf16_f32 v74, v86, v87
	v_cvt_pk_bf16_f32 v75, v88, v89
	v_cvt_pk_bf16_f32 v76, v82, v83
	v_cvt_pk_bf16_f32 v77, v84, v85
	v_lshl_add_u64 v[78:79], v[78:79], 0, v[122:123]
	v_cvt_pk_bf16_f32 v73, v68, v69
	v_cvt_pk_bf16_f32 v65, v60, v61
	v_cvt_pk_bf16_f32 v42, v54, v55
	v_cvt_pk_bf16_f32 v43, v56, v57
	v_cvt_pk_bf16_f32 v44, v50, v51
	v_cvt_pk_bf16_f32 v45, v52, v53
	v_cvt_pk_bf16_f32 v26, v38, v39
	v_cvt_pk_bf16_f32 v27, v40, v41
	v_cvt_pk_bf16_f32 v28, v34, v35
	v_cvt_pk_bf16_f32 v29, v36, v37
	v_cvt_pk_bf16_f32 v10, v22, v23
	v_cvt_pk_bf16_f32 v11, v24, v25
	v_cvt_pk_bf16_f32 v12, v18, v19
	v_cvt_pk_bf16_f32 v13, v20, v21
	v_lshl_add_u64 v[14:15], v[14:15], 0, v[122:123]
	v_cvt_pk_bf16_f32 v6, v6, v7
	v_cvt_pk_bf16_f32 v7, v8, v9
	v_cvt_pk_bf16_f32 v8, v2, v3
	v_cvt_pk_bf16_f32 v9, v4, v5
	s_and_b64 vcc, exec, s[2:3]
	s_mov_b32 s48, s8
	s_mov_b32 s6, s10
	s_mov_b64 s[18:19], s[14:15]
	s_mov_b64 s[16:17], s[12:13]
	global_store_dwordx4 v[124:125], v[126:129], off sc1
	global_store_dwordx4 v[110:111], v[106:109], off sc1
	global_store_dwordx4 v[94:95], v[90:93], off sc1
	global_store_dwordx4 v[78:79], v[74:77], off sc1
	global_store_dwordx4 v[78:79], v[70:73], off offset:256 sc1
	global_store_dwordx4 v[58:59], v[62:65], off sc1
	global_store_dwordx4 v[46:47], v[42:45], off sc1
	global_store_dwordx4 v[30:31], v[26:29], off sc1
	global_store_dwordx4 v[14:15], v[10:13], off sc1
	global_store_dwordx4 v[14:15], v[6:9], off offset:256 sc1
	s_cbranch_vccz .LBB0_1912
	s_waitcnt vmcnt(0)
	s_cmpk_gt_u32 s24, 0xff
	s_cbranch_scc1 .LBB0_1923
	s_barrier
